# S5 pass 2 output stage: the eight u-image reads of an iteration issued together ahead of the C-projection reads (fresh regs), lgkmcnt recomputed
# baseline (speedup 1.0000x reference)
.LBB0_242:
	s_or_b64 exec, exec, s[24:25]
	v_add_f32_e32 v219, v172, v172
	v_mul_f32_e32 v218, v173, v173
	v_mul_f32_e32 v219, v219, v173
	v_fma_f32 v218, v172, v172, -v218
	v_mul_f32_e32 v227, v219, v219
	v_fma_f32 v227, v218, v218, -v227
	v_add_f32_e32 v218, v218, v218
	v_mul_f32_e32 v218, v219, v218
	v_mul_f32_e32 v219, v218, v218
	v_fma_f32 v219, v227, v227, -v219
	v_add_f32_e32 v227, v227, v227
	v_mul_f32_e32 v218, v218, v227
	v_mul_f32_e32 v227, v218, v218
	v_fma_f32 v227, v219, v219, -v227
	v_add_f32_e32 v219, v219, v219
	v_mul_f32_e32 v218, v218, v219
	v_mul_f32_e32 v219, v218, v218
	v_fma_f32 v219, v227, v227, -v219
	v_add_f32_e32 v227, v227, v227
	v_mul_f32_e32 v218, v218, v227
	v_mul_f32_e32 v227, v218, v218
	v_fma_f32 v227, v219, v219, -v227
	v_add_f32_e32 v219, v219, v219
	v_mul_f32_e32 v219, v218, v219
	v_mul_f32_e32 v218, v219, v219
	v_fma_f32 v218, v227, v227, -v218
	v_add_f32_e32 v227, v227, v227
	v_mul_f32_e32 v219, v219, v227
	v_mul_f32_e32 v227, 0, v219
	v_fma_f32 v231, 0, v218, v227
	v_fma_f32 v227, v218, 0, -v227
	s_waitcnt vmcnt(60)
	v_add_f32_e32 v214, v214, v227
	v_mul_f32_e32 v227, v226, v220
	v_fmac_f32_e32 v227, v232, v221
	s_waitcnt vmcnt(59)
	v_add_f32_e32 v217, v217, v227
	v_mul_f32_e32 v227, v226, v221
	v_add_f32_e32 v215, v215, v231
	v_fma_f32 v227, v232, v220, -v227
	v_cndmask_b32_e64 v215, v215, 0, s[0:1]
	v_cndmask_b32_e64 v214, v214, 0, s[0:1]
	v_add_f32_e32 v216, v216, v227
	v_cmp_lt_u32_e64 s[0:1], 1, v233
	s_waitcnt lgkmcnt(0)
	s_barrier
	v_cndmask_b32_e64 v216, v220, v216, s[0:1]
	v_mul_f32_e32 v220, v219, v214
	v_fmac_f32_e32 v220, v218, v215
	s_waitcnt vmcnt(58)
	v_add_f32_e32 v213, v213, v220
	v_mul_f32_e32 v220, v219, v215
	v_fma_f32 v220, v218, v214, -v220
	v_add_f32_e32 v212, v212, v220
	v_cndmask_b32_e64 v217, v221, v217, s[0:1]
	v_cndmask_b32_e64 v212, v214, v212, s[0:1]
	v_mul_f32_e32 v214, v226, v216
	v_fmac_f32_e32 v214, v232, v217
	s_waitcnt vmcnt(57)
	v_add_f32_e32 v211, v211, v214
	v_mul_f32_e32 v214, v226, v217
	v_fma_f32 v214, v232, v216, -v214
	v_cndmask_b32_e64 v213, v215, v213, s[0:1]
	v_add_f32_e32 v210, v210, v214
	v_mul_f32_e32 v214, v219, v212
	v_fmac_f32_e32 v214, v218, v213
	s_waitcnt vmcnt(56)
	v_add_f32_e32 v207, v207, v214
	v_mul_f32_e32 v214, v219, v213
	v_cmp_lt_u32_e64 s[0:1], 2, v233
	v_fma_f32 v214, v218, v212, -v214
	v_add_f32_e32 v206, v206, v214
	v_cndmask_b32_e64 v210, v216, v210, s[0:1]
	v_cndmask_b32_e64 v211, v217, v211, s[0:1]
	v_cndmask_b32_e64 v206, v212, v206, s[0:1]
	v_mul_f32_e32 v212, v226, v210
	v_fmac_f32_e32 v212, v232, v211
	s_waitcnt vmcnt(55)
	v_add_f32_e32 v209, v209, v212
	v_mul_f32_e32 v212, v226, v211
	v_fma_f32 v212, v232, v210, -v212
	v_cndmask_b32_e64 v207, v213, v207, s[0:1]
	v_add_f32_e32 v208, v208, v212
	v_cmp_lt_u32_e64 s[0:1], 3, v233
	s_nop 1
	v_cndmask_b32_e64 v208, v210, v208, s[0:1]
	v_mul_f32_e32 v210, v219, v206
	v_fmac_f32_e32 v210, v218, v207
	s_waitcnt vmcnt(54)
	v_add_f32_e32 v205, v205, v210
	v_mul_f32_e32 v210, v219, v207
	v_fma_f32 v210, v218, v206, -v210
	v_add_f32_e32 v204, v204, v210
	v_cndmask_b32_e64 v209, v211, v209, s[0:1]
	v_cndmask_b32_e64 v204, v206, v204, s[0:1]
	v_mul_f32_e32 v206, v226, v208
	v_fmac_f32_e32 v206, v232, v209
	s_waitcnt vmcnt(53)
	v_add_f32_e32 v203, v203, v206
	v_mul_f32_e32 v206, v226, v209
	v_fma_f32 v206, v232, v208, -v206
	v_cndmask_b32_e64 v205, v207, v205, s[0:1]
	v_add_f32_e32 v202, v202, v206
	v_mul_f32_e32 v206, v219, v204
	v_fmac_f32_e32 v206, v218, v205
	s_waitcnt vmcnt(52)
	v_add_f32_e32 v199, v199, v206
	v_mul_f32_e32 v206, v219, v205
	v_cmp_lt_u32_e64 s[0:1], 4, v233
	v_fma_f32 v206, v218, v204, -v206
	v_add_f32_e32 v198, v198, v206
	v_cndmask_b32_e64 v202, v208, v202, s[0:1]
	v_cndmask_b32_e64 v203, v209, v203, s[0:1]
	v_cndmask_b32_e64 v198, v204, v198, s[0:1]
	v_mul_f32_e32 v204, v226, v202
	v_fmac_f32_e32 v204, v232, v203
	s_waitcnt vmcnt(51)
	v_add_f32_e32 v201, v201, v204
	v_mul_f32_e32 v204, v226, v203
	v_fma_f32 v204, v232, v202, -v204
	v_cndmask_b32_e64 v199, v205, v199, s[0:1]
	v_add_f32_e32 v200, v200, v204
	v_cmp_lt_u32_e64 s[0:1], 5, v233
	s_nop 1
	v_cndmask_b32_e64 v200, v202, v200, s[0:1]
	v_mul_f32_e32 v202, v219, v198
	v_fmac_f32_e32 v202, v218, v199
	s_waitcnt vmcnt(50)
	v_add_f32_e32 v197, v197, v202
	v_mul_f32_e32 v202, v219, v199
	v_fma_f32 v202, v218, v198, -v202
	v_add_f32_e32 v196, v196, v202
	v_cndmask_b32_e64 v201, v203, v201, s[0:1]
	v_cndmask_b32_e64 v196, v198, v196, s[0:1]
	v_mul_f32_e32 v198, v226, v200
	v_fmac_f32_e32 v198, v232, v201
	s_waitcnt vmcnt(49)
	v_add_f32_e32 v195, v195, v198
	v_mul_f32_e32 v198, v226, v201
	v_fma_f32 v198, v232, v200, -v198
	v_cndmask_b32_e64 v197, v199, v197, s[0:1]
	v_add_f32_e32 v194, v194, v198
	v_mul_f32_e32 v198, v219, v196
	v_fmac_f32_e32 v198, v218, v197
	s_waitcnt vmcnt(48)
	v_add_f32_e32 v191, v191, v198
	v_mul_f32_e32 v198, v219, v197
	v_cmp_lt_u32_e64 s[0:1], 6, v233
	v_fma_f32 v198, v218, v196, -v198
	v_add_f32_e32 v190, v190, v198
	v_cndmask_b32_e64 v194, v200, v194, s[0:1]
	v_cndmask_b32_e64 v195, v201, v195, s[0:1]
	v_cndmask_b32_e64 v190, v196, v190, s[0:1]
	v_mul_f32_e32 v196, v226, v194
	v_fmac_f32_e32 v196, v232, v195
	s_waitcnt vmcnt(47)
	v_add_f32_e32 v193, v193, v196
	v_mul_f32_e32 v196, v226, v195
	v_fma_f32 v196, v232, v194, -v196
	v_cndmask_b32_e64 v191, v197, v191, s[0:1]
	v_add_f32_e32 v192, v192, v196
	v_cmp_lt_u32_e64 s[0:1], 7, v233
	s_nop 1
	v_cndmask_b32_e64 v192, v194, v192, s[0:1]
	v_mul_f32_e32 v194, v219, v190
	v_fmac_f32_e32 v194, v218, v191
	s_waitcnt vmcnt(46)
	v_add_f32_e32 v189, v189, v194
	v_mul_f32_e32 v194, v219, v191
	v_fma_f32 v194, v218, v190, -v194
	v_add_f32_e32 v188, v188, v194
	v_cndmask_b32_e64 v193, v195, v193, s[0:1]
	v_cndmask_b32_e64 v188, v190, v188, s[0:1]
	v_mul_f32_e32 v190, v226, v192
	v_fmac_f32_e32 v190, v232, v193
	s_waitcnt vmcnt(45)
	v_add_f32_e32 v187, v187, v190
	v_mul_f32_e32 v190, v226, v193
	v_fma_f32 v190, v232, v192, -v190
	v_cndmask_b32_e64 v189, v191, v189, s[0:1]
	v_add_f32_e32 v186, v186, v190
	v_mul_f32_e32 v190, v219, v188
	v_fmac_f32_e32 v190, v218, v189
	s_waitcnt vmcnt(44)
	v_add_f32_e32 v183, v183, v190
	v_mul_f32_e32 v190, v219, v189
	v_cmp_lt_u32_e64 s[0:1], 8, v233
	v_fma_f32 v190, v218, v188, -v190
	v_add_f32_e32 v182, v182, v190
	v_cndmask_b32_e64 v186, v192, v186, s[0:1]
	v_cndmask_b32_e64 v187, v193, v187, s[0:1]
	v_cndmask_b32_e64 v182, v188, v182, s[0:1]
	v_mul_f32_e32 v188, v226, v186
	v_fmac_f32_e32 v188, v232, v187
	s_waitcnt vmcnt(43)
	v_add_f32_e32 v185, v185, v188
	v_mul_f32_e32 v188, v226, v187
	v_fma_f32 v188, v232, v186, -v188
	v_cndmask_b32_e64 v183, v189, v183, s[0:1]
	v_add_f32_e32 v184, v184, v188
	v_cmp_lt_u32_e64 s[0:1], 9, v233
	s_nop 1
	v_cndmask_b32_e64 v184, v186, v184, s[0:1]
	v_mul_f32_e32 v186, v219, v182
	v_fmac_f32_e32 v186, v218, v183
	s_waitcnt vmcnt(42)
	v_add_f32_e32 v181, v181, v186
	v_mul_f32_e32 v186, v219, v183
	v_fma_f32 v186, v218, v182, -v186
	v_add_f32_e32 v180, v180, v186
	v_cndmask_b32_e64 v185, v187, v185, s[0:1]
	v_cndmask_b32_e64 v180, v182, v180, s[0:1]
	v_mul_f32_e32 v182, v226, v184
	v_fmac_f32_e32 v182, v232, v185
	s_waitcnt vmcnt(41)
	v_add_f32_e32 v179, v179, v182
	v_mul_f32_e32 v182, v226, v185
	v_fma_f32 v182, v232, v184, -v182
	v_cndmask_b32_e64 v181, v183, v181, s[0:1]
	v_add_f32_e32 v178, v178, v182
	v_mul_f32_e32 v182, v219, v180
	v_fmac_f32_e32 v182, v218, v181
	s_waitcnt vmcnt(40)
	v_add_f32_e32 v97, v97, v182
	v_mul_f32_e32 v182, v219, v181
	v_cmp_lt_u32_e64 s[0:1], 10, v233
	v_fma_f32 v182, v218, v180, -v182
	v_add_f32_e32 v96, v96, v182
	v_cndmask_b32_e64 v178, v184, v178, s[0:1]
	v_cndmask_b32_e64 v179, v185, v179, s[0:1]
	v_cndmask_b32_e64 v96, v180, v96, s[0:1]
	v_mul_f32_e32 v180, v226, v178
	v_fmac_f32_e32 v180, v232, v179
	s_waitcnt vmcnt(39)
	v_add_f32_e32 v177, v177, v180
	v_mul_f32_e32 v180, v226, v179
	v_fma_f32 v180, v232, v178, -v180
	v_cndmask_b32_e64 v97, v181, v97, s[0:1]
	v_add_f32_e32 v176, v176, v180
	v_cmp_lt_u32_e64 s[0:1], 11, v233
	s_nop 1
	v_cndmask_b32_e64 v176, v178, v176, s[0:1]
	v_mul_f32_e32 v178, v219, v96
	v_fmac_f32_e32 v178, v218, v97
	s_waitcnt vmcnt(38)
	v_add_f32_e32 v95, v95, v178
	v_mul_f32_e32 v178, v219, v97
	v_fma_f32 v178, v218, v96, -v178
	v_add_f32_e32 v94, v94, v178
	v_cndmask_b32_e64 v177, v179, v177, s[0:1]
	v_cndmask_b32_e64 v94, v96, v94, s[0:1]
	v_mul_f32_e32 v96, v226, v176
	v_fmac_f32_e32 v96, v232, v177
	s_waitcnt vmcnt(37)
	v_add_f32_e32 v93, v93, v96
	v_mul_f32_e32 v96, v226, v177
	v_fma_f32 v96, v232, v176, -v96
	v_cndmask_b32_e64 v95, v97, v95, s[0:1]
	v_add_f32_e32 v92, v92, v96
	v_mul_f32_e32 v96, v219, v94
	v_fmac_f32_e32 v96, v218, v95
	s_waitcnt vmcnt(36)
	v_add_f32_e32 v81, v81, v96
	v_mul_f32_e32 v96, v219, v95
	v_cmp_lt_u32_e64 s[0:1], 12, v233
	v_fma_f32 v96, v218, v94, -v96
	v_add_f32_e32 v80, v80, v96
	v_cndmask_b32_e64 v92, v176, v92, s[0:1]
	v_cndmask_b32_e64 v93, v177, v93, s[0:1]
	v_cndmask_b32_e64 v80, v94, v80, s[0:1]
	v_mul_f32_e32 v94, v226, v92
	v_fmac_f32_e32 v94, v232, v93
	s_waitcnt vmcnt(35)
	v_add_f32_e32 v83, v83, v94
	v_mul_f32_e32 v94, v226, v93
	v_fma_f32 v94, v232, v92, -v94
	v_cndmask_b32_e64 v81, v95, v81, s[0:1]
	v_add_f32_e32 v82, v82, v94
	v_cmp_lt_u32_e64 s[0:1], 13, v233
	v_lshl_add_u64 v[176:177], s[2:3], 1, v[166:167]
	s_lshl_b32 s2, s34, 7
	v_cndmask_b32_e64 v82, v92, v82, s[0:1]
	v_mul_f32_e32 v92, v219, v80
	v_fmac_f32_e32 v92, v218, v81
	s_waitcnt vmcnt(34)
	v_add_f32_e32 v79, v79, v92
	v_mul_f32_e32 v92, v219, v81
	v_fma_f32 v92, v218, v80, -v92
	v_add_f32_e32 v78, v78, v92
	v_cndmask_b32_e64 v83, v93, v83, s[0:1]
	v_cndmask_b32_e64 v78, v80, v78, s[0:1]
	v_mul_f32_e32 v80, v226, v82
	v_fmac_f32_e32 v80, v232, v83
	s_waitcnt vmcnt(33)
	v_add_f32_e32 v77, v77, v80
	v_mul_f32_e32 v80, v226, v83
	v_fma_f32 v80, v232, v82, -v80
	v_cndmask_b32_e64 v79, v81, v79, s[0:1]
	v_add_f32_e32 v76, v76, v80
	v_mul_f32_e32 v80, v219, v78
	v_fmac_f32_e32 v80, v218, v79
	s_waitcnt vmcnt(32)
	v_add_f32_e32 v73, v73, v80
	v_mul_f32_e32 v80, v219, v79
	v_cmp_lt_u32_e64 s[0:1], 14, v233
	v_fma_f32 v80, v218, v78, -v80
	v_add_f32_e32 v72, v72, v80
	v_cndmask_b32_e64 v76, v82, v76, s[0:1]
	v_cndmask_b32_e64 v77, v83, v77, s[0:1]
	v_cndmask_b32_e64 v72, v78, v72, s[0:1]
	v_mul_f32_e32 v78, v226, v76
	v_fmac_f32_e32 v78, v232, v77
	s_waitcnt vmcnt(31)
	v_add_f32_e32 v75, v75, v78
	v_mul_f32_e32 v78, v226, v77
	v_fma_f32 v78, v232, v76, -v78
	v_add_f32_e32 v74, v74, v78
	v_cndmask_b32_e64 v73, v79, v73, s[0:1]
	v_cndmask_b32_e64 v74, v74, v76, s[4:5]
	v_mul_f32_e32 v76, v219, v72
	v_fmac_f32_e32 v76, v218, v73
	s_waitcnt vmcnt(30)
	v_add_f32_e32 v67, v67, v76
	v_mul_f32_e32 v76, v219, v73
	v_fma_f32 v76, v218, v72, -v76
	v_add_f32_e32 v66, v66, v76
	v_cndmask_b32_e64 v75, v75, v77, s[4:5]
	v_cndmask_b32_e64 v66, v66, v72, s[4:5]
	v_mul_f32_e32 v72, v226, v74
	v_fmac_f32_e32 v72, v232, v75
	s_waitcnt vmcnt(29)
	v_add_f32_e32 v65, v65, v72
	v_mul_f32_e32 v72, v226, v75
	v_fma_f32 v72, v232, v74, -v72
	v_cndmask_b32_e64 v67, v67, v73, s[4:5]
	v_add_f32_e32 v64, v64, v72
	v_mul_f32_e32 v72, v219, v66
	v_fmac_f32_e32 v72, v218, v67
	s_waitcnt vmcnt(28)
	v_add_f32_e32 v61, v61, v72
	v_mul_f32_e32 v72, v219, v67
	v_cmp_lt_u32_e64 s[0:1], 16, v233
	v_fma_f32 v72, v218, v66, -v72
	v_add_f32_e32 v60, v60, v72
	v_cndmask_b32_e64 v64, v74, v64, s[0:1]
	v_cndmask_b32_e64 v65, v75, v65, s[0:1]
	v_cndmask_b32_e64 v60, v66, v60, s[0:1]
	v_mul_f32_e32 v66, v226, v64
	v_fmac_f32_e32 v66, v232, v65
	s_waitcnt vmcnt(27)
	v_add_f32_e32 v63, v63, v66
	v_mul_f32_e32 v66, v226, v65
	v_fma_f32 v66, v232, v64, -v66
	v_cndmask_b32_e64 v61, v67, v61, s[0:1]
	v_add_f32_e32 v62, v62, v66
	v_cmp_lt_u32_e64 s[0:1], 17, v233
	v_mov_b32_e32 v179, s23
	s_or_b32 s3, s2, 0x800
	v_cndmask_b32_e64 v62, v64, v62, s[0:1]
	v_mul_f32_e32 v64, v219, v60
	v_fmac_f32_e32 v64, v218, v61
	s_waitcnt vmcnt(26)
	v_add_f32_e32 v59, v59, v64
	v_mul_f32_e32 v64, v219, v61
	v_fma_f32 v64, v218, v60, -v64
	v_add_f32_e32 v58, v58, v64
	v_cndmask_b32_e64 v63, v65, v63, s[0:1]
	v_cndmask_b32_e64 v58, v60, v58, s[0:1]
	v_mul_f32_e32 v60, v226, v62
	v_fmac_f32_e32 v60, v232, v63
	s_waitcnt vmcnt(25)
	v_add_f32_e32 v57, v57, v60
	v_mul_f32_e32 v60, v226, v63
	v_fma_f32 v60, v232, v62, -v60
	v_cndmask_b32_e64 v59, v61, v59, s[0:1]
	v_add_f32_e32 v56, v56, v60
	v_mul_f32_e32 v60, v219, v58
	v_fmac_f32_e32 v60, v218, v59
	s_waitcnt vmcnt(24)
	v_add_f32_e32 v53, v53, v60
	v_mul_f32_e32 v60, v219, v59
	v_cmp_lt_u32_e64 s[0:1], 18, v233
	v_fma_f32 v60, v218, v58, -v60
	v_add_f32_e32 v52, v52, v60
	v_cndmask_b32_e64 v56, v62, v56, s[0:1]
	v_cndmask_b32_e64 v57, v63, v57, s[0:1]
	v_cndmask_b32_e64 v52, v58, v52, s[0:1]
	v_mul_f32_e32 v58, v226, v56
	v_fmac_f32_e32 v58, v232, v57
	s_waitcnt vmcnt(23)
	v_add_f32_e32 v55, v55, v58
	v_mul_f32_e32 v58, v226, v57
	v_fma_f32 v58, v232, v56, -v58
	v_cndmask_b32_e64 v53, v59, v53, s[0:1]
	v_add_f32_e32 v54, v54, v58
	v_cmp_lt_u32_e64 s[0:1], 19, v233
	s_nop 1
	v_cndmask_b32_e64 v54, v56, v54, s[0:1]
	v_mul_f32_e32 v56, v219, v52
	v_fmac_f32_e32 v56, v218, v53
	s_waitcnt vmcnt(22)
	v_add_f32_e32 v51, v51, v56
	v_mul_f32_e32 v56, v219, v53
	v_fma_f32 v56, v218, v52, -v56
	v_add_f32_e32 v50, v50, v56
	v_cndmask_b32_e64 v55, v57, v55, s[0:1]
	v_cndmask_b32_e64 v50, v52, v50, s[0:1]
	v_mul_f32_e32 v52, v226, v54
	v_fmac_f32_e32 v52, v232, v55
	s_waitcnt vmcnt(21)
	v_add_f32_e32 v49, v49, v52
	v_mul_f32_e32 v52, v226, v55
	v_fma_f32 v52, v232, v54, -v52
	v_cndmask_b32_e64 v51, v53, v51, s[0:1]
	v_add_f32_e32 v48, v48, v52
	v_mul_f32_e32 v52, v219, v50
	v_fmac_f32_e32 v52, v218, v51
	s_waitcnt vmcnt(20)
	v_add_f32_e32 v45, v45, v52
	v_mul_f32_e32 v52, v219, v51
	v_cmp_lt_u32_e64 s[0:1], 20, v233
	v_fma_f32 v52, v218, v50, -v52
	v_add_f32_e32 v44, v44, v52
	v_cndmask_b32_e64 v48, v54, v48, s[0:1]
	v_cndmask_b32_e64 v49, v55, v49, s[0:1]
	v_cndmask_b32_e64 v44, v50, v44, s[0:1]
	v_mul_f32_e32 v50, v226, v48
	v_fmac_f32_e32 v50, v232, v49
	s_waitcnt vmcnt(19)
	v_add_f32_e32 v47, v47, v50
	v_mul_f32_e32 v50, v226, v49
	v_fma_f32 v50, v232, v48, -v50
	v_cndmask_b32_e64 v45, v51, v45, s[0:1]
	v_add_f32_e32 v46, v46, v50
	v_cmp_lt_u32_e64 s[0:1], 21, v233
	s_nop 1
	v_cndmask_b32_e64 v46, v48, v46, s[0:1]
	v_mul_f32_e32 v48, v219, v44
	v_fmac_f32_e32 v48, v218, v45
	s_waitcnt vmcnt(18)
	v_add_f32_e32 v43, v43, v48
	v_mul_f32_e32 v48, v219, v45
	v_fma_f32 v48, v218, v44, -v48
	v_add_f32_e32 v42, v42, v48
	v_cndmask_b32_e64 v47, v49, v47, s[0:1]
	v_cndmask_b32_e64 v42, v44, v42, s[0:1]
	v_mul_f32_e32 v44, v226, v46
	v_fmac_f32_e32 v44, v232, v47
	s_waitcnt vmcnt(17)
	v_add_f32_e32 v41, v41, v44
	v_mul_f32_e32 v44, v226, v47
	v_fma_f32 v44, v232, v46, -v44
	v_cndmask_b32_e64 v43, v45, v43, s[0:1]
	v_add_f32_e32 v40, v40, v44
	v_mul_f32_e32 v44, v219, v42
	v_fmac_f32_e32 v44, v218, v43
	s_waitcnt vmcnt(16)
	v_add_f32_e32 v37, v37, v44
	v_mul_f32_e32 v44, v219, v43
	v_cmp_lt_u32_e64 s[0:1], 22, v233
	v_fma_f32 v44, v218, v42, -v44
	v_add_f32_e32 v36, v36, v44
	v_cndmask_b32_e64 v40, v46, v40, s[0:1]
	v_cndmask_b32_e64 v41, v47, v41, s[0:1]
	v_cndmask_b32_e64 v36, v42, v36, s[0:1]
	v_mul_f32_e32 v42, v226, v40
	v_fmac_f32_e32 v42, v232, v41
	s_waitcnt vmcnt(15)
	v_add_f32_e32 v39, v39, v42
	v_mul_f32_e32 v42, v226, v41
	v_fma_f32 v42, v232, v40, -v42
	v_cndmask_b32_e64 v37, v43, v37, s[0:1]
	v_add_f32_e32 v38, v38, v42
	v_cmp_lt_u32_e64 s[0:1], 23, v233
	s_nop 1
	v_cndmask_b32_e64 v38, v40, v38, s[0:1]
	v_mul_f32_e32 v40, v219, v36
	v_fmac_f32_e32 v40, v218, v37
	s_waitcnt vmcnt(14)
	v_add_f32_e32 v35, v35, v40
	v_mul_f32_e32 v40, v219, v37
	v_fma_f32 v40, v218, v36, -v40
	v_add_f32_e32 v34, v34, v40
	v_cndmask_b32_e64 v39, v41, v39, s[0:1]
	v_cndmask_b32_e64 v34, v36, v34, s[0:1]
	v_mul_f32_e32 v36, v226, v38
	v_fmac_f32_e32 v36, v232, v39
	s_waitcnt vmcnt(13)
	v_add_f32_e32 v33, v33, v36
	v_mul_f32_e32 v36, v226, v39
	v_fma_f32 v36, v232, v38, -v36
	v_cndmask_b32_e64 v35, v37, v35, s[0:1]
	v_add_f32_e32 v32, v32, v36
	v_mul_f32_e32 v36, v219, v34
	v_fmac_f32_e32 v36, v218, v35
	s_waitcnt vmcnt(12)
	v_add_f32_e32 v29, v29, v36
	v_mul_f32_e32 v36, v219, v35
	v_cmp_lt_u32_e64 s[0:1], 24, v233
	v_fma_f32 v36, v218, v34, -v36
	v_add_f32_e32 v28, v28, v36
	v_cndmask_b32_e64 v32, v38, v32, s[0:1]
	v_cndmask_b32_e64 v33, v39, v33, s[0:1]
	v_cndmask_b32_e64 v28, v34, v28, s[0:1]
	v_mul_f32_e32 v34, v226, v32
	v_fmac_f32_e32 v34, v232, v33
	s_waitcnt vmcnt(11)
	v_add_f32_e32 v31, v31, v34
	v_mul_f32_e32 v34, v226, v33
	v_fma_f32 v34, v232, v32, -v34
	v_cndmask_b32_e64 v29, v35, v29, s[0:1]
	v_add_f32_e32 v30, v30, v34
	v_cmp_lt_u32_e64 s[0:1], 25, v233
	s_nop 1
	v_cndmask_b32_e64 v30, v32, v30, s[0:1]
	v_mul_f32_e32 v32, v219, v28
	v_fmac_f32_e32 v32, v218, v29
	s_waitcnt vmcnt(10)
	v_add_f32_e32 v27, v27, v32
	v_mul_f32_e32 v32, v219, v29
	v_fma_f32 v32, v218, v28, -v32
	v_add_f32_e32 v26, v26, v32
	v_cndmask_b32_e64 v31, v33, v31, s[0:1]
	v_cndmask_b32_e64 v26, v28, v26, s[0:1]
	v_mul_f32_e32 v28, v226, v30
	v_fmac_f32_e32 v28, v232, v31
	s_waitcnt vmcnt(9)
	v_add_f32_e32 v25, v25, v28
	v_mul_f32_e32 v28, v226, v31
	v_fma_f32 v28, v232, v30, -v28
	v_cndmask_b32_e64 v27, v29, v27, s[0:1]
	v_add_f32_e32 v24, v24, v28
	v_mul_f32_e32 v28, v219, v26
	v_fmac_f32_e32 v28, v218, v27
	s_waitcnt vmcnt(8)
	v_add_f32_e32 v21, v21, v28
	v_mul_f32_e32 v28, v219, v27
	v_cmp_lt_u32_e64 s[0:1], 26, v233
	v_fma_f32 v28, v218, v26, -v28
	v_add_f32_e32 v20, v20, v28
	v_cndmask_b32_e64 v24, v30, v24, s[0:1]
	v_cndmask_b32_e64 v25, v31, v25, s[0:1]
	v_cndmask_b32_e64 v20, v26, v20, s[0:1]
	v_mul_f32_e32 v26, v226, v24
	v_fmac_f32_e32 v26, v232, v25
	s_waitcnt vmcnt(7)
	v_add_f32_e32 v23, v23, v26
	v_mul_f32_e32 v26, v226, v25
	v_fma_f32 v26, v232, v24, -v26
	v_cndmask_b32_e64 v21, v27, v21, s[0:1]
	v_add_f32_e32 v22, v22, v26
	v_cmp_lt_u32_e64 s[0:1], 27, v233
	s_nop 1
	v_cndmask_b32_e64 v22, v24, v22, s[0:1]
	v_mul_f32_e32 v24, v219, v20
	v_fmac_f32_e32 v24, v218, v21
	s_waitcnt vmcnt(6)
	v_add_f32_e32 v19, v19, v24
	v_mul_f32_e32 v24, v219, v21
	v_fma_f32 v24, v218, v20, -v24
	v_add_f32_e32 v18, v18, v24
	v_cndmask_b32_e64 v23, v25, v23, s[0:1]
	v_cndmask_b32_e64 v18, v20, v18, s[0:1]
	v_mul_f32_e32 v20, v226, v22
	v_fmac_f32_e32 v20, v232, v23
	s_waitcnt vmcnt(5)
	v_add_f32_e32 v17, v17, v20
	v_mul_f32_e32 v20, v226, v23
	v_fma_f32 v20, v232, v22, -v20
	v_cndmask_b32_e64 v19, v21, v19, s[0:1]
	v_add_f32_e32 v16, v16, v20
	v_mul_f32_e32 v20, v219, v18
	v_fmac_f32_e32 v20, v218, v19
	s_waitcnt vmcnt(4)
	v_add_f32_e32 v13, v13, v20
	v_mul_f32_e32 v20, v219, v19
	v_cmp_lt_u32_e64 s[0:1], 28, v233
	v_fma_f32 v20, v218, v18, -v20
	v_add_f32_e32 v12, v12, v20
	v_cndmask_b32_e64 v16, v22, v16, s[0:1]
	v_cndmask_b32_e64 v17, v23, v17, s[0:1]
	v_cndmask_b32_e64 v18, v18, v12, s[0:1]
	v_mul_f32_e32 v12, v226, v16
	v_fmac_f32_e32 v12, v232, v17
	v_cndmask_b32_e64 v13, v19, v13, s[0:1]
	s_waitcnt vmcnt(3)
	v_add_f32_e32 v12, v15, v12
	v_mul_f32_e32 v15, v226, v17
	v_cmp_lt_u32_e64 s[0:1], 29, v233
	v_fma_f32 v15, v232, v16, -v15
	v_add_f32_e32 v14, v14, v15
	v_cndmask_b32_e64 v17, v17, v12, s[0:1]
	ds_read_b32 v12, v239
	v_cndmask_b32_e64 v16, v16, v14, s[0:1]
	v_mul_f32_e32 v14, v219, v18
	v_fmac_f32_e32 v14, v218, v13
	s_waitcnt vmcnt(2)
	v_add_f32_e32 v11, v11, v14
	v_lshlrev_b32_e32 v14, 16, v2
	v_and_b32_e32 v15, 0xffff0000, v2
	v_lshlrev_b32_e32 v2, 16, v3
	v_and_b32_e32 v3, 0xffff0000, v3
	s_waitcnt lgkmcnt(0)
	v_pk_mul_f32 v[14:15], v[12:13], v[14:15] op_sel_hi:[0,1]
	v_pk_mul_f32 v[2:3], v[12:13], v[2:3] op_sel_hi:[0,1]
	v_pk_mul_f32 v[72:73], v[138:139], v[14:15]
	v_lshlrev_b32_e32 v14, 16, v4
	v_and_b32_e32 v15, 0xffff0000, v4
	v_pk_mul_f32 v[74:75], v[140:141], v[2:3]
	v_lshlrev_b32_e32 v2, 16, v5
	v_and_b32_e32 v3, 0xffff0000, v5
	v_pk_mul_f32 v[14:15], v[12:13], v[14:15] op_sel_hi:[0,1]
	v_pk_mul_f32 v[2:3], v[12:13], v[2:3] op_sel_hi:[0,1]
	v_pk_mul_f32 v[76:77], v[126:127], v[14:15]
	v_pk_mul_f32 v[78:79], v[128:129], v[2:3]
	v_cvt_pk_bf16_f32 v2, v72, v73
	v_cvt_pk_bf16_f32 v3, v74, v75
	v_cvt_pk_bf16_f32 v4, v76, v77
	v_mul_f32_e32 v19, v219, v13
	v_cvt_pk_bf16_f32 v5, v78, v79
	v_fma_f32 v12, v218, v18, -v19
	v_mfma_f32_32x32x16_bf16 v[52:67], v[2:5], v[118:121], 0
	v_add_f32_e32 v10, v10, v12
	v_mul_f32_e32 v12, v226, v16
	v_fmac_f32_e32 v12, v232, v17
	s_waitcnt vmcnt(1)
	v_add_f32_e32 v9, v9, v12
	v_mul_f32_e32 v12, v226, v17
	v_cndmask_b32_e64 v11, v13, v11, s[0:1]
	v_cndmask_b32_e64 v10, v18, v10, s[0:1]
	v_mfma_f32_32x32x16_bf16 v[20:35], v[2:5], v[122:125], 0
	v_fma_f32 v12, v232, v16, -v12
	v_cmp_eq_u32_e64 s[0:1], 31, v233
	v_add_f32_e32 v8, v8, v12
	ds_write_b128 v249, v[72:75] offset:8704
	ds_write_b128 v249, v[76:79] offset:8720
	v_cndmask_b32_e64 v18, v17, v9, s[0:1]
	v_cndmask_b32_e64 v19, v16, v8, s[0:1]
	v_fma_f32 v52, -v175, v18, v52
	v_fmac_f32_e32 v52, v174, v19
	s_nop 2
	v_fma_f32 v19, v175, v19, v20
	v_fmac_f32_e32 v19, v174, v18
	v_mul_f32_e32 v8, v219, v10
	v_fma_f32 v18, -v175, v19, v53
	v_fma_f32 v20, v175, v52, v21
	v_fmac_f32_e32 v8, v218, v11
	v_fmac_f32_e32 v18, v174, v52
	v_fmac_f32_e32 v20, v174, v19
	s_waitcnt vmcnt(0)
	v_add_f32_e32 v7, v7, v8
	v_mul_f32_e32 v8, v219, v11
	v_fma_f32 v21, -v175, v20, v54
	v_fma_f32 v22, v175, v18, v22
	v_fma_f32 v8, v218, v10, -v8
	v_fmac_f32_e32 v21, v174, v18
	v_fmac_f32_e32 v22, v174, v20
	v_add_f32_e32 v6, v6, v8
	v_fma_f32 v53, -v175, v22, v55
	v_fma_f32 v23, v175, v21, v23
	v_mfma_f32_32x32x16_bf16 v[36:51], v[2:5], v[130:133], 0
	v_cndmask_b32_e64 v80, v11, v7, s[0:1]
	v_cndmask_b32_e64 v81, v10, v6, s[0:1]
	v_fmac_f32_e32 v53, v174, v21
	v_fmac_f32_e32 v23, v174, v22
	v_fma_f32 v54, -v175, v23, v56
	v_fma_f32 v24, v175, v53, v24
	v_fmac_f32_e32 v54, v174, v53
	v_mfma_f32_32x32x16_bf16 v[2:17], v[2:5], v[134:137], 0
	v_fmac_f32_e32 v24, v174, v23
	v_fma_f32 v55, -v175, v24, v57
	v_fma_f32 v25, v175, v54, v25
	v_fmac_f32_e32 v55, v174, v54
	v_fmac_f32_e32 v25, v174, v24
	v_fma_f32 v56, -v175, v25, v58
	v_fma_f32 v26, v175, v55, v26
	v_fmac_f32_e32 v56, v174, v55
	v_fmac_f32_e32 v26, v174, v25
	v_fma_f32 v57, -v175, v26, v59
	v_fma_f32 v27, v175, v56, v27
	v_fmac_f32_e32 v57, v174, v56
	v_fmac_f32_e32 v27, v174, v26
	v_fma_f32 v36, -v173, v80, v36
	v_fma_f32 v2, v173, v81, v2
	v_fma_f32 v58, -v175, v27, v60
	v_fma_f32 v28, v175, v57, v28
	v_fmac_f32_e32 v36, v172, v81
	v_fmac_f32_e32 v2, v172, v80
	v_fmac_f32_e32 v58, v174, v57
	v_fmac_f32_e32 v28, v174, v27
	v_fma_f32 v37, -v173, v2, v37
	v_fma_f32 v3, v173, v36, v3
	v_cvt_pk_bf16_f32 v19, v52, v19
	ds_write_b32 v241, v19
	v_cvt_pk_bf16_f32 v18, v18, v20
	v_fma_f32 v59, -v175, v28, v61
	v_fma_f32 v29, v175, v58, v29
	v_fmac_f32_e32 v37, v172, v36
	v_fmac_f32_e32 v3, v172, v2
	ds_write_b32 v241, v18 offset:272
	v_cvt_pk_bf16_f32 v18, v21, v22
	v_fmac_f32_e32 v59, v174, v58
	v_fmac_f32_e32 v29, v174, v28
	v_fma_f32 v38, -v173, v3, v38
	v_fma_f32 v4, v173, v37, v4
	ds_write_b32 v241, v18 offset:544
	v_cvt_pk_bf16_f32 v18, v53, v23
	v_fma_f32 v60, -v175, v29, v62
	v_fma_f32 v30, v175, v59, v30
	v_fmac_f32_e32 v38, v172, v37
	v_fmac_f32_e32 v4, v172, v3
	ds_write_b32 v241, v18 offset:816
	v_cvt_pk_bf16_f32 v18, v54, v24
	v_fmac_f32_e32 v60, v174, v59
	v_fmac_f32_e32 v30, v174, v29
	v_fma_f32 v39, -v173, v4, v39
	v_fma_f32 v5, v173, v38, v5
	ds_write_b32 v241, v18 offset:1088
	v_cvt_pk_bf16_f32 v18, v55, v25
	v_fma_f32 v61, -v175, v30, v63
	v_fma_f32 v31, v175, v60, v31
	v_fmac_f32_e32 v39, v172, v38
	v_fmac_f32_e32 v5, v172, v4
	ds_write_b32 v241, v18 offset:1360
	v_cvt_pk_bf16_f32 v18, v56, v26
	v_fmac_f32_e32 v61, v174, v60
	v_fmac_f32_e32 v31, v174, v30
	v_fma_f32 v40, -v173, v5, v40
	v_fma_f32 v6, v173, v39, v6
	ds_write_b32 v241, v18 offset:1632
	v_cvt_pk_bf16_f32 v18, v57, v27
	v_fma_f32 v62, -v175, v31, v64
	v_fma_f32 v32, v175, v61, v32
	v_fmac_f32_e32 v40, v172, v39
	v_fmac_f32_e32 v6, v172, v5
	ds_write_b32 v241, v18 offset:1904
	v_cvt_pk_bf16_f32 v18, v58, v28
	v_fmac_f32_e32 v62, v174, v61
	v_fmac_f32_e32 v32, v174, v31
	v_fma_f32 v41, -v173, v6, v41
	v_fma_f32 v7, v173, v40, v7
	ds_write_b32 v241, v18 offset:2176
	v_cvt_pk_bf16_f32 v18, v59, v29
	v_fma_f32 v63, -v175, v32, v65
	v_fma_f32 v33, v175, v62, v33
	v_fmac_f32_e32 v41, v172, v40
	v_fmac_f32_e32 v7, v172, v6
	ds_write_b32 v241, v18 offset:2448
	v_cvt_pk_bf16_f32 v18, v60, v30
	v_fmac_f32_e32 v63, v174, v62
	v_fmac_f32_e32 v33, v174, v32
	v_fma_f32 v42, -v173, v7, v42
	v_fma_f32 v8, v173, v41, v8
	ds_write_b32 v241, v18 offset:2720
	v_cvt_pk_bf16_f32 v18, v61, v31
	v_fma_f32 v64, -v175, v33, v66
	v_fma_f32 v34, v175, v63, v34
	v_fmac_f32_e32 v42, v172, v41
	v_fmac_f32_e32 v8, v172, v7
	ds_write_b32 v241, v18 offset:2992
	v_cvt_pk_bf16_f32 v18, v62, v32
	v_fmac_f32_e32 v64, v174, v63
	v_fmac_f32_e32 v34, v174, v33
	v_fma_f32 v43, -v173, v8, v43
	v_fma_f32 v9, v173, v42, v9
	ds_write_b32 v241, v18 offset:3264
	v_cvt_pk_bf16_f32 v18, v63, v33
	v_fma_f32 v92, -v175, v34, v67
	v_fmac_f32_e32 v35, v175, v64
	v_fmac_f32_e32 v43, v172, v42
	v_fmac_f32_e32 v9, v172, v8
	ds_write_b32 v241, v18 offset:3536
	v_cvt_pk_bf16_f32 v18, v64, v34
	v_fmac_f32_e32 v92, v174, v64
	v_fmac_f32_e32 v35, v174, v34
	v_fma_f32 v44, -v173, v9, v44
	v_fma_f32 v10, v173, v43, v10
	ds_write_b32 v241, v18 offset:3808
	v_cvt_pk_bf16_f32 v18, v92, v35
	ds_write_b32 v241, v18 offset:4080
	v_cvt_pk_bf16_f32 v2, v36, v2
	v_fmac_f32_e32 v44, v172, v43
	v_fmac_f32_e32 v10, v172, v9
	ds_write_b32 v241, v2 offset:128
	v_cvt_pk_bf16_f32 v2, v37, v3
	v_fma_f32 v45, -v173, v10, v45
	v_fma_f32 v11, v173, v44, v11
	ds_write_b32 v241, v2 offset:400
	v_cvt_pk_bf16_f32 v2, v38, v4
	v_fmac_f32_e32 v45, v172, v44
	v_fmac_f32_e32 v11, v172, v10
	ds_write_b32 v241, v2 offset:672
	v_cvt_pk_bf16_f32 v2, v39, v5
	v_fma_f32 v46, -v173, v11, v46
	v_fma_f32 v12, v173, v45, v12
	ds_write_b32 v241, v2 offset:944
	v_cvt_pk_bf16_f32 v2, v40, v6
	v_fmac_f32_e32 v46, v172, v45
	v_fmac_f32_e32 v12, v172, v11
	ds_write_b32 v241, v2 offset:1216
	v_cvt_pk_bf16_f32 v2, v41, v7
	v_fma_f32 v47, -v173, v12, v47
	v_fma_f32 v13, v173, v46, v13
	ds_write_b32 v241, v2 offset:1488
	v_cvt_pk_bf16_f32 v2, v42, v8
	v_fmac_f32_e32 v47, v172, v46
	v_fmac_f32_e32 v13, v172, v12
	ds_write_b32 v241, v2 offset:1760
	v_cvt_pk_bf16_f32 v2, v43, v9
	v_fma_f32 v48, -v173, v13, v48
	v_fma_f32 v14, v173, v47, v14
	ds_write_b32 v241, v2 offset:2032
	v_cvt_pk_bf16_f32 v2, v44, v10
	v_fmac_f32_e32 v48, v172, v47
	v_fmac_f32_e32 v14, v172, v13
	ds_write_b32 v241, v2 offset:2304
	v_cvt_pk_bf16_f32 v2, v45, v11
	v_fma_f32 v49, -v173, v14, v49
	v_fma_f32 v15, v173, v48, v15
	ds_write_b32 v241, v2 offset:2576
	v_cvt_pk_bf16_f32 v2, v46, v12
	v_fmac_f32_e32 v49, v172, v48
	v_fmac_f32_e32 v15, v172, v14
	ds_write_b32 v241, v2 offset:2848
	v_cvt_pk_bf16_f32 v2, v47, v13
	v_fma_f32 v50, -v173, v15, v50
	v_fma_f32 v16, v173, v49, v16
	ds_write_b32 v241, v2 offset:3120
	v_cvt_pk_bf16_f32 v2, v48, v14
	v_fmac_f32_e32 v50, v172, v49
	v_fmac_f32_e32 v16, v172, v15
	ds_write_b32 v241, v2 offset:3392
	v_cvt_pk_bf16_f32 v2, v49, v15
	v_fma_f32 v93, -v173, v16, v51
	v_fmac_f32_e32 v17, v173, v50
	ds_write_b32 v241, v2 offset:3664
	v_cvt_pk_bf16_f32 v2, v50, v16
	v_fmac_f32_e32 v93, v172, v50
	v_fmac_f32_e32 v17, v172, v16
	ds_write_b32 v241, v2 offset:3936
	v_cvt_pk_bf16_f32 v2, v93, v17
	ds_write_b32 v241, v2 offset:4208
	ds_read_b32 v182, v251 offset:8704
	ds_read_b32 v183, v251 offset:8768
	ds_read_b32 v184, v251 offset:8832
	ds_read_b32 v185, v252 offset:8704
	ds_read_b32 v186, v253 offset:8704
	ds_read_b32 v187, v251 offset:9792
	ds_read_b32 v188, v251 offset:9856
	ds_read_b32 v189, v254 offset:8704
	ds_read_b128 v[2:5], v250
	ds_read_b128 v[6:9], v250 offset:64
	s_waitcnt lgkmcnt(1)
	v_mfma_f32_16x16x32_bf16 v[2:5], v[2:5], v[110:113], 0
	ds_read_b128 v[10:13], v250 offset:128
	s_waitcnt lgkmcnt(1)
	v_mfma_f32_16x16x32_bf16 v[2:5], v[6:9], v[106:109], v[2:5]
	ds_read_b128 v[6:9], v250 offset:192
	s_waitcnt lgkmcnt(1)
	v_mfma_f32_16x16x32_bf16 v[2:5], v[10:13], v[102:105], v[2:5]
	s_waitcnt lgkmcnt(0)
	v_mfma_f32_16x16x32_bf16 v[2:5], v[6:9], v[98:101], v[2:5]
	s_nop 0
	s_nop 6
	v_fma_f32 v2, v228, v182, v2
	v_mul_f32_e32 v6, 0x3d372713, v2
	v_mul_f32_e32 v6, v2, v6
	v_fma_f32 v6, v2, v6, v2
	v_mul_f32_e32 v6, 0xbfcc422a, v6
	v_mul_f32_e32 v6, 0x3fb8aa3b, v6
	v_exp_f32_e32 v6, v6
	s_nop 0
	v_add_f32_e32 v6, 1.0, v6
	v_rcp_f32_e32 v6, v6
	s_nop 0
	v_mul_f32_e32 v2, v2, v6
	v_cvt_pk_bf16_f32 v6, v2, v155
	s_nop 0
	v_fma_f32 v7, v228, v183, v3
	v_mul_f32_e32 v2, 0x3d372713, v7
	v_mul_f32_e32 v2, v7, v2
	v_fma_f32 v2, v7, v2, v7
	v_mul_f32_e32 v2, 0xbfcc422a, v2
	v_mul_f32_e32 v2, 0x3fb8aa3b, v2
	v_exp_f32_e32 v2, v2
	v_or_b32_e32 v3, s2, v240
	v_or_b32_e32 v178, s22, v3
	v_add_f32_e32 v2, 1.0, v2
	v_rcp_f32_e32 v8, v2
	v_lshlrev_b64 v[2:3], 11, v[178:179]
	v_lshl_add_u64 v[2:3], v[176:177], 0, v[2:3]
	global_store_short v[2:3], v6, off
	v_mul_f32_e32 v2, v7, v8
	v_cvt_pk_bf16_f32 v6, v2, v155
	v_mov_b32_e32 v3, s23
	s_nop 0
	v_fma_f32 v4, v228, v184, v4
	v_mul_f32_e32 v2, 0x3d372713, v4
	v_mul_f32_e32 v2, v4, v2
	v_fma_f32 v2, v4, v2, v4
	v_mul_f32_e32 v2, 0xbfcc422a, v2
	v_mul_f32_e32 v2, 0x3fb8aa3b, v2
	v_exp_f32_e32 v7, v2
	v_or_b32_e32 v2, 1, v178
	v_lshlrev_b64 v[2:3], 11, v[2:3]
	v_lshl_add_u64 v[2:3], v[176:177], 0, v[2:3]
	v_add_f32_e32 v7, 1.0, v7
	v_rcp_f32_e32 v7, v7
	global_store_short v[2:3], v6, off
	v_mov_b32_e32 v3, s23
	v_mul_f32_e32 v2, v4, v7
	v_cvt_pk_bf16_f32 v4, v2, v155
	s_nop 0
	v_fmac_f32_e32 v5, v228, v185
	v_mul_f32_e32 v2, 0x3d372713, v5
	v_mul_f32_e32 v2, v5, v2
	v_fma_f32 v2, v5, v2, v5
	v_mul_f32_e32 v2, 0xbfcc422a, v2
	v_mul_f32_e32 v2, 0x3fb8aa3b, v2
	v_exp_f32_e32 v6, v2
	v_or_b32_e32 v2, 2, v178
	v_lshlrev_b64 v[2:3], 11, v[2:3]
	v_lshl_add_u64 v[2:3], v[176:177], 0, v[2:3]
	v_add_f32_e32 v6, 1.0, v6
	v_rcp_f32_e32 v6, v6
	global_store_short v[2:3], v4, off
	v_or_b32_e32 v178, 3, v178
	v_mul_f32_e32 v2, v5, v6
	v_cvt_pk_bf16_f32 v14, v2, v155
	ds_read_b128 v[2:5], v250 offset:4352
	ds_read_b128 v[6:9], v250 offset:4416
	s_waitcnt lgkmcnt(1)
	v_mfma_f32_16x16x32_bf16 v[2:5], v[2:5], v[110:113], 0
	ds_read_b128 v[10:13], v250 offset:4480
	s_waitcnt lgkmcnt(1)
	v_mfma_f32_16x16x32_bf16 v[2:5], v[6:9], v[106:109], v[2:5]
	ds_read_b128 v[6:9], v250 offset:4544
	s_waitcnt lgkmcnt(1)
	v_mfma_f32_16x16x32_bf16 v[2:5], v[10:13], v[102:105], v[2:5]
	v_and_b32_e32 v11, 0xffff0000, v71
	s_waitcnt lgkmcnt(0)
	v_mfma_f32_16x16x32_bf16 v[2:5], v[6:9], v[98:101], v[2:5]
	s_nop 0
	s_nop 6
	v_fma_f32 v2, v228, v186, v2
	v_mul_f32_e32 v6, 0x3d372713, v2
	v_mul_f32_e32 v6, v2, v6
	v_fma_f32 v6, v2, v6, v2
	v_mul_f32_e32 v6, 0xbfcc422a, v6
	v_mul_f32_e32 v6, 0x3fb8aa3b, v6
	v_exp_f32_e32 v6, v6
	v_lshlrev_b32_e32 v10, 16, v71
	v_add_f32_e32 v6, 1.0, v6
	v_rcp_f32_e32 v8, v6
	v_lshlrev_b64 v[6:7], 11, v[178:179]
	v_lshl_add_u64 v[6:7], v[176:177], 0, v[6:7]
	global_store_short v[6:7], v14, off
	v_mul_f32_e32 v2, v2, v8
	v_cvt_pk_bf16_f32 v6, v2, v155
	s_nop 0
	v_fma_f32 v7, v228, v187, v3
	v_mul_f32_e32 v2, 0x3d372713, v7
	v_mul_f32_e32 v2, v7, v2
	v_fma_f32 v2, v7, v2, v7
	v_mul_f32_e32 v2, 0xbfcc422a, v2
	v_mul_f32_e32 v2, 0x3fb8aa3b, v2
	v_exp_f32_e32 v2, v2
	v_or_b32_e32 v3, s3, v240
	v_or_b32_e32 v178, s22, v3
	v_add_f32_e32 v2, 1.0, v2
	v_rcp_f32_e32 v8, v2
	v_lshlrev_b64 v[2:3], 11, v[178:179]
	v_lshl_add_u64 v[2:3], v[176:177], 0, v[2:3]
	global_store_short v[2:3], v6, off
	v_mul_f32_e32 v2, v7, v8
	v_cvt_pk_bf16_f32 v6, v2, v155
	v_mov_b32_e32 v3, s23
	s_nop 0
	v_fma_f32 v4, v228, v188, v4
	v_mul_f32_e32 v2, 0x3d372713, v4
	v_mul_f32_e32 v2, v4, v2
	v_fma_f32 v2, v4, v2, v4
	v_mul_f32_e32 v2, 0xbfcc422a, v2
	v_mul_f32_e32 v2, 0x3fb8aa3b, v2
	v_exp_f32_e32 v7, v2
	v_or_b32_e32 v2, 1, v178
	v_lshlrev_b64 v[2:3], 11, v[2:3]
	v_lshl_add_u64 v[2:3], v[176:177], 0, v[2:3]
	v_add_f32_e32 v7, 1.0, v7
	v_rcp_f32_e32 v7, v7
	global_store_short v[2:3], v6, off
	v_mov_b32_e32 v3, s23
	v_mul_f32_e32 v2, v4, v7
	v_cvt_pk_bf16_f32 v4, v2, v155
	s_nop 0
	v_fmac_f32_e32 v5, v228, v189
	v_mul_f32_e32 v2, 0x3d372713, v5
	v_mul_f32_e32 v2, v5, v2
	v_fma_f32 v2, v5, v2, v5
	v_mul_f32_e32 v2, 0xbfcc422a, v2
	v_mul_f32_e32 v2, 0x3fb8aa3b, v2
	v_exp_f32_e32 v6, v2
	v_or_b32_e32 v2, 2, v178
	v_lshlrev_b64 v[2:3], 11, v[2:3]
	v_lshl_add_u64 v[2:3], v[176:177], 0, v[2:3]
	v_add_f32_e32 v6, 1.0, v6
	v_rcp_f32_e32 v6, v6
	global_store_short v[2:3], v4, off
	v_or_b32_e32 v178, 3, v178
	v_mul_f32_e32 v2, v5, v6
	v_cvt_pk_bf16_f32 v4, v2, v155
	v_lshlrev_b64 v[2:3], 11, v[178:179]
	v_lshl_add_u64 v[2:3], v[176:177], 0, v[2:3]
	global_store_short v[2:3], v4, off
	ds_read_b32 v8, v239 offset:64
	v_lshlrev_b32_e32 v4, 16, v70
	v_and_b32_e32 v5, 0xffff0000, v70
	v_lshlrev_b32_e32 v2, 16, v68
	v_and_b32_e32 v3, 0xffff0000, v68
	s_waitcnt lgkmcnt(0)
	v_pk_mul_f32 v[4:5], v[8:9], v[4:5] op_sel_hi:[0,1]
	v_pk_mul_f32 v[6:7], v[126:127], v[4:5]
	v_lshlrev_b32_e32 v4, 16, v69
	v_and_b32_e32 v5, 0xffff0000, v69
	v_pk_mul_f32 v[2:3], v[8:9], v[2:3] op_sel_hi:[0,1]
	v_pk_mul_f32 v[4:5], v[8:9], v[4:5] op_sel_hi:[0,1]
	v_pk_mul_f32 v[8:9], v[8:9], v[10:11] op_sel_hi:[0,1]
	v_pk_mul_f32 v[2:3], v[138:139], v[2:3]
	v_pk_mul_f32 v[4:5], v[140:141], v[4:5]
	v_pk_mul_f32 v[8:9], v[128:129], v[8:9]
	v_cvt_pk_bf16_f32 v10, v2, v3
	v_cvt_pk_bf16_f32 v11, v4, v5
	v_cvt_pk_bf16_f32 v12, v6, v7
	s_nop 0
	v_cvt_pk_bf16_f32 v13, v8, v9
	ds_write_b128 v249, v[2:5] offset:8704
	ds_write_b128 v249, v[6:9] offset:8720
	v_mfma_f32_32x32x16_bf16 v[68:83], v[10:13], v[118:121], 0
	v_mfma_f32_32x32x16_bf16 v[36:51], v[10:13], v[122:125], 0
	v_mfma_f32_32x32x16_bf16 v[52:67], v[10:13], v[130:133], 0
	v_mfma_f32_32x32x16_bf16 v[18:33], v[10:13], v[134:137], 0
	s_nop 8
	v_fma_f32 v10, -v175, v35, v68
	v_fma_f32 v11, v175, v92, v36
	v_fmac_f32_e32 v10, v174, v92
	v_fmac_f32_e32 v11, v174, v35
	v_fma_f32 v12, -v175, v11, v69
	v_fma_f32 v13, v175, v10, v37
	v_fmac_f32_e32 v12, v174, v10
	v_fmac_f32_e32 v13, v174, v11
	v_fma_f32 v14, -v175, v13, v70
	v_fma_f32 v15, v175, v12, v38
	v_fmac_f32_e32 v14, v174, v12
	v_fmac_f32_e32 v15, v174, v13
	v_fma_f32 v16, -v175, v15, v71
	v_fma_f32 v34, v175, v14, v39
	v_fmac_f32_e32 v16, v174, v14
	v_fmac_f32_e32 v34, v174, v15
	v_fma_f32 v35, -v175, v34, v72
	v_fma_f32 v36, v175, v16, v40
	v_fmac_f32_e32 v35, v174, v16
	v_fmac_f32_e32 v36, v174, v34
	v_fma_f32 v37, -v175, v36, v73
	v_fma_f32 v38, v175, v35, v41
	v_fmac_f32_e32 v37, v174, v35
	v_fmac_f32_e32 v38, v174, v36
	v_fma_f32 v39, -v175, v38, v74
	v_fma_f32 v40, v175, v37, v42
	v_fmac_f32_e32 v39, v174, v37
	v_fmac_f32_e32 v40, v174, v38
	v_fma_f32 v41, -v175, v40, v75
	v_fma_f32 v42, v175, v39, v43
	v_fmac_f32_e32 v41, v174, v39
	v_fmac_f32_e32 v42, v174, v40
	v_fma_f32 v43, -v175, v42, v76
	v_fma_f32 v44, v175, v41, v44
	v_fma_f32 v52, -v173, v17, v52
	v_fma_f32 v18, v173, v93, v18
	v_cvt_pk_bf16_f32 v2, v10, v11
	v_fmac_f32_e32 v43, v174, v41
	v_fmac_f32_e32 v44, v174, v42
	v_fmac_f32_e32 v52, v172, v93
	v_fmac_f32_e32 v18, v172, v17
	ds_write_b32 v241, v2
	v_cvt_pk_bf16_f32 v2, v12, v13
	v_fma_f32 v68, -v175, v44, v77
	v_fma_f32 v45, v175, v43, v45
	v_fma_f32 v17, -v173, v18, v53
	v_fma_f32 v19, v173, v52, v19
	ds_write_b32 v241, v2 offset:272
	v_cvt_pk_bf16_f32 v2, v14, v15
	v_fmac_f32_e32 v68, v174, v43
	v_fmac_f32_e32 v45, v174, v44
	v_fmac_f32_e32 v17, v172, v52
	v_fmac_f32_e32 v19, v172, v18
	ds_write_b32 v241, v2 offset:544
	v_cvt_pk_bf16_f32 v2, v16, v34
	v_fma_f32 v69, -v175, v45, v78
	v_fma_f32 v46, v175, v68, v46
	v_fma_f32 v53, -v173, v19, v54
	v_fma_f32 v20, v173, v17, v20
	ds_write_b32 v241, v2 offset:816
	v_cvt_pk_bf16_f32 v2, v35, v36
	v_fmac_f32_e32 v69, v174, v68
	v_fmac_f32_e32 v46, v174, v45
	v_fmac_f32_e32 v53, v172, v17
	v_fmac_f32_e32 v20, v172, v19
	ds_write_b32 v241, v2 offset:1088
	v_cvt_pk_bf16_f32 v2, v37, v38
	v_fma_f32 v70, -v175, v46, v79
	v_fma_f32 v47, v175, v69, v47
	v_fma_f32 v54, -v173, v20, v55
	v_fma_f32 v21, v173, v53, v21
	ds_write_b32 v241, v2 offset:1360
	v_cvt_pk_bf16_f32 v2, v39, v40
	v_fmac_f32_e32 v70, v174, v69
	v_fmac_f32_e32 v47, v174, v46
	v_fmac_f32_e32 v54, v172, v53
	v_fmac_f32_e32 v21, v172, v20
	ds_write_b32 v241, v2 offset:1632
	v_cvt_pk_bf16_f32 v2, v41, v42
	v_fma_f32 v71, -v175, v47, v80
	v_fma_f32 v48, v175, v70, v48
	v_fma_f32 v55, -v173, v21, v56
	v_fma_f32 v22, v173, v54, v22
	ds_write_b32 v241, v2 offset:1904
	v_cvt_pk_bf16_f32 v2, v43, v44
	v_fmac_f32_e32 v71, v174, v70
	v_fmac_f32_e32 v48, v174, v47
	v_fmac_f32_e32 v55, v172, v54
	v_fmac_f32_e32 v22, v172, v21
	ds_write_b32 v241, v2 offset:2176
	v_cvt_pk_bf16_f32 v2, v68, v45
	v_fma_f32 v72, -v175, v48, v81
	v_fma_f32 v49, v175, v71, v49
	v_fma_f32 v56, -v173, v22, v57
	v_fma_f32 v23, v173, v55, v23
	ds_write_b32 v241, v2 offset:2448
	v_cvt_pk_bf16_f32 v2, v69, v46
	v_fmac_f32_e32 v72, v174, v71
	v_fmac_f32_e32 v49, v174, v48
	v_fmac_f32_e32 v56, v172, v55
	v_fmac_f32_e32 v23, v172, v22
	ds_write_b32 v241, v2 offset:2720
	v_cvt_pk_bf16_f32 v2, v70, v47
	v_fma_f32 v73, -v175, v49, v82
	v_fma_f32 v50, v175, v72, v50
	v_fma_f32 v57, -v173, v23, v58
	v_fma_f32 v24, v173, v56, v24
	ds_write_b32 v241, v2 offset:2992
	v_cvt_pk_bf16_f32 v2, v71, v48
	v_fmac_f32_e32 v73, v174, v72
	v_fmac_f32_e32 v50, v174, v49
	v_fmac_f32_e32 v57, v172, v56
	v_fmac_f32_e32 v24, v172, v23
	ds_write_b32 v241, v2 offset:3264
	v_cvt_pk_bf16_f32 v2, v72, v49
	v_fma_f32 v92, -v175, v50, v83
	v_fmac_f32_e32 v51, v175, v73
	v_fma_f32 v58, -v173, v24, v59
	v_fma_f32 v25, v173, v57, v25
	ds_write_b32 v241, v2 offset:3536
	v_cvt_pk_bf16_f32 v2, v73, v50
	v_fmac_f32_e32 v92, v174, v73
	v_fmac_f32_e32 v51, v174, v50
	v_fmac_f32_e32 v58, v172, v57
	v_fmac_f32_e32 v25, v172, v24
	ds_write_b32 v241, v2 offset:3808
	v_cvt_pk_bf16_f32 v2, v92, v51
	v_fma_f32 v59, -v173, v25, v60
	v_fma_f32 v26, v173, v58, v26
	ds_write_b32 v241, v2 offset:4080
	v_cvt_pk_bf16_f32 v2, v52, v18
	v_fmac_f32_e32 v59, v172, v58
	v_fmac_f32_e32 v26, v172, v25
	ds_write_b32 v241, v2 offset:128
	v_cvt_pk_bf16_f32 v2, v17, v19
	v_fma_f32 v60, -v173, v26, v61
	v_fma_f32 v27, v173, v59, v27
	ds_write_b32 v241, v2 offset:400
	v_cvt_pk_bf16_f32 v2, v53, v20
	v_fmac_f32_e32 v60, v172, v59
	v_fmac_f32_e32 v27, v172, v26
	ds_write_b32 v241, v2 offset:672
	v_cvt_pk_bf16_f32 v2, v54, v21
	v_fma_f32 v61, -v173, v27, v62
	v_fma_f32 v28, v173, v60, v28
	ds_write_b32 v241, v2 offset:944
	v_cvt_pk_bf16_f32 v2, v55, v22
	v_fmac_f32_e32 v61, v172, v60
	v_fmac_f32_e32 v28, v172, v27
	ds_write_b32 v241, v2 offset:1216
	v_cvt_pk_bf16_f32 v2, v56, v23
	v_fma_f32 v62, -v173, v28, v63
	v_fma_f32 v29, v173, v61, v29
	ds_write_b32 v241, v2 offset:1488
	v_cvt_pk_bf16_f32 v2, v57, v24
	v_fmac_f32_e32 v62, v172, v61
	v_fmac_f32_e32 v29, v172, v28
	ds_write_b32 v241, v2 offset:1760
	v_cvt_pk_bf16_f32 v2, v58, v25
	v_fma_f32 v63, -v173, v29, v64
	v_fma_f32 v30, v173, v62, v30
	ds_write_b32 v241, v2 offset:2032
	v_cvt_pk_bf16_f32 v2, v59, v26
	v_fmac_f32_e32 v63, v172, v62
	v_fmac_f32_e32 v30, v172, v29
	ds_write_b32 v241, v2 offset:2304
	v_cvt_pk_bf16_f32 v2, v60, v27
	v_fma_f32 v64, -v173, v30, v65
	v_fma_f32 v31, v173, v63, v31
	ds_write_b32 v241, v2 offset:2576
	v_cvt_pk_bf16_f32 v2, v61, v28
	v_fmac_f32_e32 v64, v172, v63
	v_fmac_f32_e32 v31, v172, v30
	ds_write_b32 v241, v2 offset:2848
	v_cvt_pk_bf16_f32 v2, v62, v29
	v_fma_f32 v65, -v173, v31, v66
	v_fma_f32 v32, v173, v64, v32
	ds_write_b32 v241, v2 offset:3120
	v_cvt_pk_bf16_f32 v2, v63, v30
	v_fmac_f32_e32 v65, v172, v64
	v_fmac_f32_e32 v32, v172, v31
	ds_write_b32 v241, v2 offset:3392
	v_cvt_pk_bf16_f32 v2, v64, v31
	v_fma_f32 v93, -v173, v32, v67
	v_fmac_f32_e32 v33, v173, v65
	ds_write_b32 v241, v2 offset:3664
	v_cvt_pk_bf16_f32 v2, v65, v32
	v_fmac_f32_e32 v93, v172, v65
	v_fmac_f32_e32 v33, v172, v32
	ds_write_b32 v241, v2 offset:3936
	v_cvt_pk_bf16_f32 v2, v93, v33
	ds_write_b32 v241, v2 offset:4208
	ds_read_b32 v182, v251 offset:8704
	ds_read_b32 v183, v251 offset:8768
	ds_read_b32 v184, v251 offset:8832
	ds_read_b32 v185, v252 offset:8704
	ds_read_b32 v186, v253 offset:8704
	ds_read_b32 v187, v251 offset:9792
	ds_read_b32 v188, v251 offset:9856
	ds_read_b32 v189, v254 offset:8704
	ds_read_b128 v[2:5], v250
	ds_read_b128 v[6:9], v250 offset:64
	s_waitcnt lgkmcnt(1)
	v_mfma_f32_16x16x32_bf16 v[2:5], v[2:5], v[110:113], 0
	ds_read_b128 v[10:13], v250 offset:128
	s_waitcnt lgkmcnt(1)
	v_mfma_f32_16x16x32_bf16 v[2:5], v[6:9], v[106:109], v[2:5]
	ds_read_b128 v[6:9], v250 offset:192
	s_waitcnt lgkmcnt(1)
	v_mfma_f32_16x16x32_bf16 v[2:5], v[10:13], v[102:105], v[2:5]
	s_waitcnt lgkmcnt(0)
	v_mfma_f32_16x16x32_bf16 v[2:5], v[6:9], v[98:101], v[2:5]
	s_nop 0
	s_nop 6
	v_fma_f32 v2, v228, v182, v2
	v_mul_f32_e32 v6, 0x3d372713, v2
	v_mul_f32_e32 v6, v2, v6
	v_fma_f32 v6, v2, v6, v2
	v_mul_f32_e32 v6, 0xbfcc422a, v6
	v_mul_f32_e32 v6, 0x3fb8aa3b, v6
	v_exp_f32_e32 v6, v6
	s_nop 0
	v_add_f32_e32 v6, 1.0, v6
	v_rcp_f32_e32 v6, v6
	s_nop 0
	v_mul_f32_e32 v2, v2, v6
	v_cvt_pk_bf16_f32 v6, v2, v155
	s_nop 0
	v_fma_f32 v7, v228, v183, v3
	v_mul_f32_e32 v2, 0x3d372713, v7
	v_mul_f32_e32 v2, v7, v2
	v_fma_f32 v2, v7, v2, v7
	v_mul_f32_e32 v2, 0xbfcc422a, v2
	v_mul_f32_e32 v2, 0x3fb8aa3b, v2
	v_exp_f32_e32 v2, v2
	v_or_b32_e32 v3, s2, v242
	v_or_b32_e32 v178, s22, v3
	v_add_f32_e32 v2, 1.0, v2
	v_rcp_f32_e32 v8, v2
	v_lshlrev_b64 v[2:3], 11, v[178:179]
	v_lshl_add_u64 v[2:3], v[176:177], 0, v[2:3]
	global_store_short v[2:3], v6, off
	v_mul_f32_e32 v2, v7, v8
	v_cvt_pk_bf16_f32 v6, v2, v155
	v_mov_b32_e32 v3, s23
	s_nop 0
	v_fma_f32 v4, v228, v184, v4
	v_mul_f32_e32 v2, 0x3d372713, v4
	v_mul_f32_e32 v2, v4, v2
	v_fma_f32 v2, v4, v2, v4
	v_mul_f32_e32 v2, 0xbfcc422a, v2
	v_mul_f32_e32 v2, 0x3fb8aa3b, v2
	v_exp_f32_e32 v7, v2
	v_or_b32_e32 v2, 1, v178
	v_lshlrev_b64 v[2:3], 11, v[2:3]
	v_lshl_add_u64 v[2:3], v[176:177], 0, v[2:3]
	v_add_f32_e32 v7, 1.0, v7
	v_rcp_f32_e32 v7, v7
	global_store_short v[2:3], v6, off
	v_mov_b32_e32 v3, s23
	v_mul_f32_e32 v2, v4, v7
	v_cvt_pk_bf16_f32 v4, v2, v155
	s_nop 0
	v_fmac_f32_e32 v5, v228, v185
	v_mul_f32_e32 v2, 0x3d372713, v5
	v_mul_f32_e32 v2, v5, v2
	v_fma_f32 v2, v5, v2, v5
	v_mul_f32_e32 v2, 0xbfcc422a, v2
	v_mul_f32_e32 v2, 0x3fb8aa3b, v2
	v_exp_f32_e32 v6, v2
	v_or_b32_e32 v2, 2, v178
	v_lshlrev_b64 v[2:3], 11, v[2:3]
	v_lshl_add_u64 v[2:3], v[176:177], 0, v[2:3]
	v_add_f32_e32 v6, 1.0, v6
	v_rcp_f32_e32 v6, v6
	global_store_short v[2:3], v4, off
	v_or_b32_e32 v178, 3, v178
	v_mul_f32_e32 v2, v5, v6
	v_cvt_pk_bf16_f32 v14, v2, v155
	ds_read_b128 v[2:5], v250 offset:4352
	ds_read_b128 v[6:9], v250 offset:4416
	s_waitcnt lgkmcnt(1)
	v_mfma_f32_16x16x32_bf16 v[2:5], v[2:5], v[110:113], 0
	ds_read_b128 v[10:13], v250 offset:4480
	s_waitcnt lgkmcnt(1)
	v_mfma_f32_16x16x32_bf16 v[2:5], v[6:9], v[106:109], v[2:5]
	ds_read_b128 v[6:9], v250 offset:4544
	s_waitcnt lgkmcnt(1)
	v_mfma_f32_16x16x32_bf16 v[2:5], v[10:13], v[102:105], v[2:5]
	s_waitcnt lgkmcnt(0)
	v_mfma_f32_16x16x32_bf16 v[2:5], v[6:9], v[98:101], v[2:5]
	s_nop 0
	s_nop 6
	v_fma_f32 v2, v228, v186, v2
	v_mul_f32_e32 v6, 0x3d372713, v2
	v_mul_f32_e32 v6, v2, v6
	v_fma_f32 v6, v2, v6, v2
	v_mul_f32_e32 v6, 0xbfcc422a, v6
	v_mul_f32_e32 v6, 0x3fb8aa3b, v6
	v_exp_f32_e32 v6, v6
	s_nop 0
	v_add_f32_e32 v6, 1.0, v6
	v_rcp_f32_e32 v8, v6
	v_lshlrev_b64 v[6:7], 11, v[178:179]
	v_lshl_add_u64 v[6:7], v[176:177], 0, v[6:7]
	global_store_short v[6:7], v14, off
	v_mul_f32_e32 v2, v2, v8
	v_cvt_pk_bf16_f32 v6, v2, v155
	s_nop 0
	v_fma_f32 v7, v228, v187, v3
	v_mul_f32_e32 v2, 0x3d372713, v7
	v_mul_f32_e32 v2, v7, v2
	v_fma_f32 v2, v7, v2, v7
	v_mul_f32_e32 v2, 0xbfcc422a, v2
	v_mul_f32_e32 v2, 0x3fb8aa3b, v2
	v_exp_f32_e32 v2, v2
	v_or_b32_e32 v3, s3, v242
	v_or_b32_e32 v178, s22, v3
	v_add_f32_e32 v2, 1.0, v2
	v_rcp_f32_e32 v8, v2
	v_lshlrev_b64 v[2:3], 11, v[178:179]
	v_lshl_add_u64 v[2:3], v[176:177], 0, v[2:3]
	global_store_short v[2:3], v6, off
	v_mul_f32_e32 v2, v7, v8
	v_cvt_pk_bf16_f32 v6, v2, v155
	v_mov_b32_e32 v3, s23
	s_nop 0
	v_fma_f32 v4, v228, v188, v4
	v_mul_f32_e32 v2, 0x3d372713, v4
	v_mul_f32_e32 v2, v4, v2
	v_fma_f32 v2, v4, v2, v4
	v_mul_f32_e32 v2, 0xbfcc422a, v2
	v_mul_f32_e32 v2, 0x3fb8aa3b, v2
	v_exp_f32_e32 v7, v2
	v_or_b32_e32 v2, 1, v178
	v_lshlrev_b64 v[2:3], 11, v[2:3]
	v_lshl_add_u64 v[2:3], v[176:177], 0, v[2:3]
	v_add_f32_e32 v7, 1.0, v7
	v_rcp_f32_e32 v7, v7
	global_store_short v[2:3], v6, off
	v_mov_b32_e32 v3, s23
	v_mul_f32_e32 v2, v4, v7
	v_cvt_pk_bf16_f32 v4, v2, v155
	s_nop 0
	v_fmac_f32_e32 v5, v228, v189
	v_mul_f32_e32 v2, 0x3d372713, v5
	v_mul_f32_e32 v2, v5, v2
	v_fma_f32 v2, v5, v2, v5
	v_mul_f32_e32 v2, 0xbfcc422a, v2
	v_mul_f32_e32 v2, 0x3fb8aa3b, v2
	v_exp_f32_e32 v6, v2
	v_or_b32_e32 v2, 2, v178
	v_lshlrev_b64 v[2:3], 11, v[2:3]
	v_lshl_add_u64 v[2:3], v[176:177], 0, v[2:3]
	v_add_f32_e32 v6, 1.0, v6
	v_rcp_f32_e32 v6, v6
	global_store_short v[2:3], v4, off
	v_or_b32_e32 v178, 3, v178
	v_mul_f32_e32 v2, v5, v6
	v_cvt_pk_bf16_f32 v4, v2, v155
	v_lshlrev_b64 v[2:3], 11, v[178:179]
	v_lshl_add_u64 v[2:3], v[176:177], 0, v[2:3]
	global_store_short v[2:3], v4, off
	ds_read_b32 v2, v239 offset:128
	v_lshlrev_b32_e32 v4, 16, v88
	v_and_b32_e32 v5, 0xffff0000, v88
	s_waitcnt lgkmcnt(0)
	v_pk_mul_f32 v[4:5], v[2:3], v[4:5] op_sel_hi:[0,1]
	v_pk_mul_f32 v[18:19], v[138:139], v[4:5]
	v_lshlrev_b32_e32 v4, 16, v90
	v_and_b32_e32 v5, 0xffff0000, v90
	v_pk_mul_f32 v[4:5], v[2:3], v[4:5] op_sel_hi:[0,1]
	v_pk_mul_f32 v[22:23], v[126:127], v[4:5]
	v_lshlrev_b32_e32 v4, 16, v89
	v_and_b32_e32 v5, 0xffff0000, v89
	v_pk_mul_f32 v[4:5], v[2:3], v[4:5] op_sel_hi:[0,1]
	v_pk_mul_f32 v[20:21], v[140:141], v[4:5]
	v_lshlrev_b32_e32 v4, 16, v91
	v_and_b32_e32 v5, 0xffff0000, v91
	v_pk_mul_f32 v[2:3], v[2:3], v[4:5] op_sel_hi:[0,1]
	v_pk_mul_f32 v[24:25], v[128:129], v[2:3]
	v_cvt_pk_bf16_f32 v2, v18, v19
	v_cvt_pk_bf16_f32 v3, v20, v21
	v_cvt_pk_bf16_f32 v4, v22, v23
	s_nop 0
	v_cvt_pk_bf16_f32 v5, v24, v25
	ds_write_b128 v249, v[18:21] offset:8704
	ds_write_b128 v249, v[22:25] offset:8720
	v_mfma_f32_32x32x16_bf16 v[68:83], v[2:5], v[118:121], 0
	v_mfma_f32_32x32x16_bf16 v[34:49], v[2:5], v[122:125], 0
	s_nop 10
	v_fma_f32 v26, -v175, v51, v68
	v_fmac_f32_e32 v26, v174, v92
	v_mfma_f32_32x32x16_bf16 v[52:67], v[2:5], v[130:133], 0
	v_fma_f32 v27, v175, v92, v34
	v_fmac_f32_e32 v27, v174, v51
	v_fma_f32 v28, -v175, v27, v69
	v_fma_f32 v29, v175, v26, v35
	v_fmac_f32_e32 v28, v174, v26
	v_fmac_f32_e32 v29, v174, v27
	v_fma_f32 v30, -v175, v29, v70
	v_fma_f32 v31, v175, v28, v36
	v_fmac_f32_e32 v30, v174, v28
	v_fmac_f32_e32 v31, v174, v29
	v_fma_f32 v32, -v175, v31, v71
	v_fma_f32 v34, v175, v30, v37
	v_mfma_f32_32x32x16_bf16 v[2:17], v[2:5], v[134:137], 0
	v_fmac_f32_e32 v32, v174, v30
	v_fmac_f32_e32 v34, v174, v31
	v_fma_f32 v35, -v175, v34, v72
	v_fma_f32 v36, v175, v32, v38
	v_fmac_f32_e32 v35, v174, v32
	v_fmac_f32_e32 v36, v174, v34
	v_fma_f32 v37, -v175, v36, v73
	v_fma_f32 v38, v175, v35, v39
	v_fmac_f32_e32 v37, v174, v35
	v_fmac_f32_e32 v38, v174, v36
	v_fma_f32 v39, -v175, v38, v74
	v_fma_f32 v40, v175, v37, v40
	v_fmac_f32_e32 v39, v174, v37
	v_fmac_f32_e32 v40, v174, v38
	v_fma_f32 v50, -v175, v40, v75
	v_fma_f32 v41, v175, v39, v41
	v_fmac_f32_e32 v50, v174, v39
	v_fmac_f32_e32 v41, v174, v40
	v_fma_f32 v52, -v173, v33, v52
	v_fma_f32 v2, v173, v93, v2
	v_fma_f32 v51, -v175, v41, v76
	v_fma_f32 v42, v175, v50, v42
	v_fmac_f32_e32 v52, v172, v93
	v_fmac_f32_e32 v2, v172, v33
	v_cvt_pk_bf16_f32 v18, v26, v27
	v_fmac_f32_e32 v51, v174, v50
	v_fmac_f32_e32 v42, v174, v41
	v_fma_f32 v33, -v173, v2, v53
	v_fma_f32 v3, v173, v52, v3
	ds_write_b32 v241, v18
	v_cvt_pk_bf16_f32 v18, v28, v29
	v_fma_f32 v68, -v175, v42, v77
	v_fma_f32 v43, v175, v51, v43
	v_fmac_f32_e32 v33, v172, v52
	v_fmac_f32_e32 v3, v172, v2
	ds_write_b32 v241, v18 offset:272
	v_cvt_pk_bf16_f32 v18, v30, v31
	v_fmac_f32_e32 v68, v174, v51
	v_fmac_f32_e32 v43, v174, v42
	v_fma_f32 v53, -v173, v3, v54
	v_fma_f32 v4, v173, v33, v4
	ds_write_b32 v241, v18 offset:544
	v_cvt_pk_bf16_f32 v18, v32, v34
	v_fma_f32 v69, -v175, v43, v78
	v_fma_f32 v44, v175, v68, v44
	v_fmac_f32_e32 v53, v172, v33
	v_fmac_f32_e32 v4, v172, v3
	ds_write_b32 v241, v18 offset:816
	v_cvt_pk_bf16_f32 v18, v35, v36
	v_fmac_f32_e32 v69, v174, v68
	v_fmac_f32_e32 v44, v174, v43
	v_fma_f32 v54, -v173, v4, v55
	v_fma_f32 v5, v173, v53, v5
	ds_write_b32 v241, v18 offset:1088
	v_cvt_pk_bf16_f32 v18, v37, v38
	v_fma_f32 v70, -v175, v44, v79
	v_fma_f32 v45, v175, v69, v45
	v_fmac_f32_e32 v54, v172, v53
	v_fmac_f32_e32 v5, v172, v4
	ds_write_b32 v241, v18 offset:1360
	v_cvt_pk_bf16_f32 v18, v39, v40
	v_fmac_f32_e32 v70, v174, v69
	v_fmac_f32_e32 v45, v174, v44
	v_fma_f32 v55, -v173, v5, v56
	v_fma_f32 v6, v173, v54, v6
	ds_write_b32 v241, v18 offset:1632
	v_cvt_pk_bf16_f32 v18, v50, v41
	v_fma_f32 v71, -v175, v45, v80
	v_fma_f32 v46, v175, v70, v46
	v_fmac_f32_e32 v55, v172, v54
	v_fmac_f32_e32 v6, v172, v5
	ds_write_b32 v241, v18 offset:1904
	v_cvt_pk_bf16_f32 v18, v51, v42
	v_fmac_f32_e32 v71, v174, v70
	v_fmac_f32_e32 v46, v174, v45
	v_fma_f32 v56, -v173, v6, v57
	v_fma_f32 v7, v173, v55, v7
	ds_write_b32 v241, v18 offset:2176
	v_cvt_pk_bf16_f32 v18, v68, v43
	v_fma_f32 v72, -v175, v46, v81
	v_fma_f32 v47, v175, v71, v47
	v_fmac_f32_e32 v56, v172, v55
	v_fmac_f32_e32 v7, v172, v6
	ds_write_b32 v241, v18 offset:2448
	v_cvt_pk_bf16_f32 v18, v69, v44
	v_fmac_f32_e32 v72, v174, v71
	v_fmac_f32_e32 v47, v174, v46
	v_fma_f32 v57, -v173, v7, v58
	v_fma_f32 v8, v173, v56, v8
	ds_write_b32 v241, v18 offset:2720
	v_cvt_pk_bf16_f32 v18, v70, v45
	v_fma_f32 v73, -v175, v47, v82
	v_fma_f32 v48, v175, v72, v48
	v_fmac_f32_e32 v57, v172, v56
	v_fmac_f32_e32 v8, v172, v7
	ds_write_b32 v241, v18 offset:2992
	v_cvt_pk_bf16_f32 v18, v71, v46
	v_fmac_f32_e32 v73, v174, v72
	v_fmac_f32_e32 v48, v174, v47
	v_fma_f32 v58, -v173, v8, v59
	v_fma_f32 v9, v173, v57, v9
	ds_write_b32 v241, v18 offset:3264
	v_cvt_pk_bf16_f32 v18, v72, v47
	v_fma_f32 v180, -v175, v48, v83
	v_fmac_f32_e32 v49, v175, v73
	v_fmac_f32_e32 v58, v172, v57
	v_fmac_f32_e32 v9, v172, v8
	ds_write_b32 v241, v18 offset:3536
	v_cvt_pk_bf16_f32 v18, v73, v48
	v_fmac_f32_e32 v180, v174, v73
	v_fmac_f32_e32 v49, v174, v48
	v_fma_f32 v59, -v173, v9, v60
	v_fma_f32 v10, v173, v58, v10
	ds_write_b32 v241, v18 offset:3808
	v_cvt_pk_bf16_f32 v18, v180, v49
	ds_write_b32 v241, v18 offset:4080
	v_cvt_pk_bf16_f32 v2, v52, v2
	v_fmac_f32_e32 v59, v172, v58
	v_fmac_f32_e32 v10, v172, v9
	ds_write_b32 v241, v2 offset:128
	v_cvt_pk_bf16_f32 v2, v33, v3
	v_fma_f32 v60, -v173, v10, v61
	v_fma_f32 v11, v173, v59, v11
	ds_write_b32 v241, v2 offset:400
	v_cvt_pk_bf16_f32 v2, v53, v4
	v_fmac_f32_e32 v60, v172, v59
	v_fmac_f32_e32 v11, v172, v10
	ds_write_b32 v241, v2 offset:672
	v_cvt_pk_bf16_f32 v2, v54, v5
	v_fma_f32 v61, -v173, v11, v62
	v_fma_f32 v12, v173, v60, v12
	ds_write_b32 v241, v2 offset:944
	v_cvt_pk_bf16_f32 v2, v55, v6
	v_fmac_f32_e32 v61, v172, v60
	v_fmac_f32_e32 v12, v172, v11
	ds_write_b32 v241, v2 offset:1216
	v_cvt_pk_bf16_f32 v2, v56, v7
	v_fma_f32 v62, -v173, v12, v63
	v_fma_f32 v13, v173, v61, v13
	ds_write_b32 v241, v2 offset:1488
	v_cvt_pk_bf16_f32 v2, v57, v8
	v_fmac_f32_e32 v62, v172, v61
	v_fmac_f32_e32 v13, v172, v12
	ds_write_b32 v241, v2 offset:1760
	v_cvt_pk_bf16_f32 v2, v58, v9
	v_fma_f32 v63, -v173, v13, v64
	v_fma_f32 v14, v173, v62, v14
	ds_write_b32 v241, v2 offset:2032
	v_cvt_pk_bf16_f32 v2, v59, v10
	v_fmac_f32_e32 v63, v172, v62
	v_fmac_f32_e32 v14, v172, v13
	ds_write_b32 v241, v2 offset:2304
	v_cvt_pk_bf16_f32 v2, v60, v11
	v_fma_f32 v64, -v173, v14, v65
	v_fma_f32 v15, v173, v63, v15
	ds_write_b32 v241, v2 offset:2576
	v_cvt_pk_bf16_f32 v2, v61, v12
	v_fmac_f32_e32 v64, v172, v63
	v_fmac_f32_e32 v15, v172, v14
	ds_write_b32 v241, v2 offset:2848
	v_cvt_pk_bf16_f32 v2, v62, v13
	v_fma_f32 v65, -v173, v15, v66
	v_fma_f32 v16, v173, v64, v16
	ds_write_b32 v241, v2 offset:3120
	v_cvt_pk_bf16_f32 v2, v63, v14
	v_fmac_f32_e32 v65, v172, v64
	v_fmac_f32_e32 v16, v172, v15
	ds_write_b32 v241, v2 offset:3392
	v_cvt_pk_bf16_f32 v2, v64, v15
	v_fma_f32 v181, -v173, v16, v67
	v_fmac_f32_e32 v17, v173, v65
	ds_write_b32 v241, v2 offset:3664
	v_cvt_pk_bf16_f32 v2, v65, v16
	v_fmac_f32_e32 v181, v172, v65
	v_fmac_f32_e32 v17, v172, v16
	ds_write_b32 v241, v2 offset:3936
	v_cvt_pk_bf16_f32 v2, v181, v17
	ds_write_b32 v241, v2 offset:4208
	ds_read_b32 v182, v251 offset:8704
	ds_read_b32 v183, v251 offset:8768
	ds_read_b32 v184, v251 offset:8832
	ds_read_b32 v185, v252 offset:8704
	ds_read_b32 v186, v253 offset:8704
	ds_read_b32 v187, v251 offset:9792
	ds_read_b32 v188, v251 offset:9856
	ds_read_b32 v189, v254 offset:8704
	ds_read_b128 v[2:5], v250
	ds_read_b128 v[6:9], v250 offset:64
	s_waitcnt lgkmcnt(1)
	v_mfma_f32_16x16x32_bf16 v[2:5], v[2:5], v[110:113], 0
	ds_read_b128 v[10:13], v250 offset:128
	s_waitcnt lgkmcnt(1)
	v_mfma_f32_16x16x32_bf16 v[2:5], v[6:9], v[106:109], v[2:5]
	ds_read_b128 v[6:9], v250 offset:192
	s_waitcnt lgkmcnt(1)
	v_mfma_f32_16x16x32_bf16 v[2:5], v[10:13], v[102:105], v[2:5]
	s_waitcnt lgkmcnt(0)
	v_mfma_f32_16x16x32_bf16 v[2:5], v[6:9], v[98:101], v[2:5]
	s_nop 0
	s_nop 6
	v_fma_f32 v2, v228, v182, v2
	v_mul_f32_e32 v6, 0x3d372713, v2
	v_mul_f32_e32 v6, v2, v6
	v_fma_f32 v6, v2, v6, v2
	v_mul_f32_e32 v6, 0xbfcc422a, v6
	v_mul_f32_e32 v6, 0x3fb8aa3b, v6
	v_exp_f32_e32 v6, v6
	s_nop 0
	v_add_f32_e32 v6, 1.0, v6
	v_rcp_f32_e32 v6, v6
	s_nop 0
	v_mul_f32_e32 v2, v2, v6
	v_cvt_pk_bf16_f32 v6, v2, v155
	s_nop 0
	v_fma_f32 v7, v228, v183, v3
	v_mul_f32_e32 v2, 0x3d372713, v7
	v_mul_f32_e32 v2, v7, v2
	v_fma_f32 v2, v7, v2, v7
	v_mul_f32_e32 v2, 0xbfcc422a, v2
	v_mul_f32_e32 v2, 0x3fb8aa3b, v2
	v_exp_f32_e32 v2, v2
	v_or_b32_e32 v3, s2, v243
	v_or_b32_e32 v178, s22, v3
	v_add_f32_e32 v2, 1.0, v2
	v_rcp_f32_e32 v8, v2
	v_lshlrev_b64 v[2:3], 11, v[178:179]
	v_lshl_add_u64 v[2:3], v[176:177], 0, v[2:3]
	global_store_short v[2:3], v6, off
	v_mul_f32_e32 v2, v7, v8
	v_cvt_pk_bf16_f32 v6, v2, v155
	v_mov_b32_e32 v3, s23
	s_nop 0
	v_fma_f32 v4, v228, v184, v4
	v_mul_f32_e32 v2, 0x3d372713, v4
	v_mul_f32_e32 v2, v4, v2
	v_fma_f32 v2, v4, v2, v4
	v_mul_f32_e32 v2, 0xbfcc422a, v2
	v_mul_f32_e32 v2, 0x3fb8aa3b, v2
	v_exp_f32_e32 v7, v2
	v_or_b32_e32 v2, 1, v178
	v_lshlrev_b64 v[2:3], 11, v[2:3]
	v_lshl_add_u64 v[2:3], v[176:177], 0, v[2:3]
	v_add_f32_e32 v7, 1.0, v7
	v_rcp_f32_e32 v7, v7
	global_store_short v[2:3], v6, off
	v_mov_b32_e32 v3, s23
	v_mul_f32_e32 v2, v4, v7
	v_cvt_pk_bf16_f32 v4, v2, v155
	s_nop 0
	v_fmac_f32_e32 v5, v228, v185
	v_mul_f32_e32 v2, 0x3d372713, v5
	v_mul_f32_e32 v2, v5, v2
	v_fma_f32 v2, v5, v2, v5
	v_mul_f32_e32 v2, 0xbfcc422a, v2
	v_mul_f32_e32 v2, 0x3fb8aa3b, v2
	v_exp_f32_e32 v6, v2
	v_or_b32_e32 v2, 2, v178
	v_lshlrev_b64 v[2:3], 11, v[2:3]
	v_lshl_add_u64 v[2:3], v[176:177], 0, v[2:3]
	v_add_f32_e32 v6, 1.0, v6
	v_rcp_f32_e32 v6, v6
	global_store_short v[2:3], v4, off
	v_or_b32_e32 v178, 3, v178
	v_mul_f32_e32 v2, v5, v6
	v_cvt_pk_bf16_f32 v14, v2, v155
	ds_read_b128 v[2:5], v250 offset:4352
	ds_read_b128 v[6:9], v250 offset:4416
	s_waitcnt lgkmcnt(1)
	v_mfma_f32_16x16x32_bf16 v[2:5], v[2:5], v[110:113], 0
	ds_read_b128 v[10:13], v250 offset:4480
	s_waitcnt lgkmcnt(1)
	v_mfma_f32_16x16x32_bf16 v[2:5], v[6:9], v[106:109], v[2:5]
	ds_read_b128 v[6:9], v250 offset:4544
	s_waitcnt lgkmcnt(1)
	v_mfma_f32_16x16x32_bf16 v[2:5], v[10:13], v[102:105], v[2:5]
	v_and_b32_e32 v11, 0xffff0000, v87
	s_waitcnt lgkmcnt(0)
	v_mfma_f32_16x16x32_bf16 v[2:5], v[6:9], v[98:101], v[2:5]
	s_nop 0
	s_nop 6
	v_fma_f32 v2, v228, v186, v2
	v_mul_f32_e32 v6, 0x3d372713, v2
	v_mul_f32_e32 v6, v2, v6
	v_fma_f32 v6, v2, v6, v2
	v_mul_f32_e32 v6, 0xbfcc422a, v6
	v_mul_f32_e32 v6, 0x3fb8aa3b, v6
	v_exp_f32_e32 v6, v6
	v_lshlrev_b32_e32 v10, 16, v87
	v_add_f32_e32 v6, 1.0, v6
	v_rcp_f32_e32 v8, v6
	v_lshlrev_b64 v[6:7], 11, v[178:179]
	v_lshl_add_u64 v[6:7], v[176:177], 0, v[6:7]
	global_store_short v[6:7], v14, off
	v_mul_f32_e32 v2, v2, v8
	v_cvt_pk_bf16_f32 v6, v2, v155
	s_nop 0
	v_fma_f32 v7, v228, v187, v3
	v_mul_f32_e32 v2, 0x3d372713, v7
	v_mul_f32_e32 v2, v7, v2
	v_fma_f32 v2, v7, v2, v7
	v_mul_f32_e32 v2, 0xbfcc422a, v2
	v_mul_f32_e32 v2, 0x3fb8aa3b, v2
	v_exp_f32_e32 v2, v2
	v_or_b32_e32 v3, s3, v243
	v_or_b32_e32 v178, s22, v3
	v_add_f32_e32 v2, 1.0, v2
	v_rcp_f32_e32 v8, v2
	v_lshlrev_b64 v[2:3], 11, v[178:179]
	v_lshl_add_u64 v[2:3], v[176:177], 0, v[2:3]
	global_store_short v[2:3], v6, off
	v_mul_f32_e32 v2, v7, v8
	v_cvt_pk_bf16_f32 v6, v2, v155
	v_mov_b32_e32 v3, s23
	s_nop 0
	v_fma_f32 v4, v228, v188, v4
	v_mul_f32_e32 v2, 0x3d372713, v4
	v_mul_f32_e32 v2, v4, v2
	v_fma_f32 v2, v4, v2, v4
	v_mul_f32_e32 v2, 0xbfcc422a, v2
	v_mul_f32_e32 v2, 0x3fb8aa3b, v2
	v_exp_f32_e32 v7, v2
	v_or_b32_e32 v2, 1, v178
	v_lshlrev_b64 v[2:3], 11, v[2:3]
	v_lshl_add_u64 v[2:3], v[176:177], 0, v[2:3]
	v_add_f32_e32 v7, 1.0, v7
	v_rcp_f32_e32 v7, v7
	global_store_short v[2:3], v6, off
	v_mov_b32_e32 v3, s23
	v_mul_f32_e32 v2, v4, v7
	v_cvt_pk_bf16_f32 v4, v2, v155
	s_nop 0
	v_fmac_f32_e32 v5, v228, v189
	v_mul_f32_e32 v2, 0x3d372713, v5
	v_mul_f32_e32 v2, v5, v2
	v_fma_f32 v2, v5, v2, v5
	v_mul_f32_e32 v2, 0xbfcc422a, v2
	v_mul_f32_e32 v2, 0x3fb8aa3b, v2
	v_exp_f32_e32 v6, v2
	v_or_b32_e32 v2, 2, v178
	v_lshlrev_b64 v[2:3], 11, v[2:3]
	v_lshl_add_u64 v[2:3], v[176:177], 0, v[2:3]
	v_add_f32_e32 v6, 1.0, v6
	v_rcp_f32_e32 v6, v6
	global_store_short v[2:3], v4, off
	v_or_b32_e32 v178, 3, v178
	v_mul_f32_e32 v2, v5, v6
	v_cvt_pk_bf16_f32 v4, v2, v155
	v_lshlrev_b64 v[2:3], 11, v[178:179]
	v_lshl_add_u64 v[2:3], v[176:177], 0, v[2:3]
	global_store_short v[2:3], v4, off
	ds_read_b32 v8, v239 offset:192
	v_lshlrev_b32_e32 v4, 16, v86
	v_and_b32_e32 v5, 0xffff0000, v86
	v_lshlrev_b32_e32 v2, 16, v84
	v_and_b32_e32 v3, 0xffff0000, v84
	s_waitcnt lgkmcnt(0)
	v_pk_mul_f32 v[4:5], v[8:9], v[4:5] op_sel_hi:[0,1]
	v_pk_mul_f32 v[6:7], v[126:127], v[4:5]
	v_lshlrev_b32_e32 v4, 16, v85
	v_and_b32_e32 v5, 0xffff0000, v85
	v_pk_mul_f32 v[2:3], v[8:9], v[2:3] op_sel_hi:[0,1]
	v_pk_mul_f32 v[4:5], v[8:9], v[4:5] op_sel_hi:[0,1]
	v_pk_mul_f32 v[8:9], v[8:9], v[10:11] op_sel_hi:[0,1]
	v_pk_mul_f32 v[2:3], v[138:139], v[2:3]
	v_pk_mul_f32 v[4:5], v[140:141], v[4:5]
	v_pk_mul_f32 v[8:9], v[128:129], v[8:9]
	v_cvt_pk_bf16_f32 v10, v2, v3
	v_cvt_pk_bf16_f32 v11, v4, v5
	v_cvt_pk_bf16_f32 v12, v6, v7
	s_nop 0
	v_cvt_pk_bf16_f32 v13, v8, v9
	ds_write_b128 v249, v[2:5] offset:8704
	ds_write_b128 v249, v[6:9] offset:8720
	v_mfma_f32_32x32x16_bf16 v[82:97], v[10:13], v[118:121], 0
	v_mfma_f32_32x32x16_bf16 v[50:65], v[10:13], v[122:125], 0
	v_mfma_f32_32x32x16_bf16 v[66:81], v[10:13], v[130:133], 0
	v_mfma_f32_32x32x16_bf16 v[18:33], v[10:13], v[134:137], 0
	s_nop 8
	v_fma_f32 v10, -v175, v49, v82
	v_fma_f32 v11, v175, v180, v50
	v_fmac_f32_e32 v10, v174, v180
	v_fmac_f32_e32 v11, v174, v49
	v_fma_f32 v12, -v175, v11, v83
	v_fma_f32 v13, v175, v10, v51
	v_fmac_f32_e32 v12, v174, v10
	v_fmac_f32_e32 v13, v174, v11
	v_fma_f32 v14, -v175, v13, v84
	v_fma_f32 v15, v175, v12, v52
	v_fmac_f32_e32 v14, v174, v12
	v_fmac_f32_e32 v15, v174, v13
	v_fma_f32 v16, -v175, v15, v85
	v_fma_f32 v34, v175, v14, v53
	v_fmac_f32_e32 v16, v174, v14
	v_fmac_f32_e32 v34, v174, v15
	v_fma_f32 v35, -v175, v34, v86
	v_fma_f32 v36, v175, v16, v54
	v_fmac_f32_e32 v35, v174, v16
	v_fmac_f32_e32 v36, v174, v34
	v_fma_f32 v37, -v175, v36, v87
	v_fma_f32 v38, v175, v35, v55
	v_fmac_f32_e32 v37, v174, v35
	v_fmac_f32_e32 v38, v174, v36
	v_fma_f32 v39, -v175, v38, v88
	v_fma_f32 v40, v175, v37, v56
	v_fmac_f32_e32 v39, v174, v37
	v_fmac_f32_e32 v40, v174, v38
	v_fma_f32 v41, -v175, v40, v89
	v_fma_f32 v42, v175, v39, v57
	v_fmac_f32_e32 v41, v174, v39
	v_fmac_f32_e32 v42, v174, v40
	v_fma_f32 v43, -v175, v42, v90
	v_fma_f32 v44, v175, v41, v58
	v_fma_f32 v58, -v173, v17, v66
	v_fma_f32 v18, v173, v181, v18
	v_cvt_pk_bf16_f32 v2, v10, v11
	v_fmac_f32_e32 v43, v174, v41
	v_fmac_f32_e32 v44, v174, v42
	v_fmac_f32_e32 v58, v172, v181
	v_fmac_f32_e32 v18, v172, v17
	ds_write_b32 v241, v2
	v_cvt_pk_bf16_f32 v2, v12, v13
	v_fma_f32 v45, -v175, v44, v91
	v_fma_f32 v46, v175, v43, v59
	v_fma_f32 v17, -v173, v18, v67
	v_fma_f32 v19, v173, v58, v19
	ds_write_b32 v241, v2 offset:272
	v_cvt_pk_bf16_f32 v2, v14, v15
	v_fmac_f32_e32 v45, v174, v43
	v_fmac_f32_e32 v46, v174, v44
	v_fmac_f32_e32 v17, v172, v58
	v_fmac_f32_e32 v19, v172, v18
	ds_write_b32 v241, v2 offset:544
	v_cvt_pk_bf16_f32 v2, v16, v34
	v_fma_f32 v47, -v175, v46, v92
	v_fma_f32 v48, v175, v45, v60
	v_fma_f32 v59, -v173, v19, v68
	v_fma_f32 v20, v173, v17, v20
	ds_write_b32 v241, v2 offset:816
	v_cvt_pk_bf16_f32 v2, v35, v36
	v_fmac_f32_e32 v47, v174, v45
	v_fmac_f32_e32 v48, v174, v46
	v_fmac_f32_e32 v59, v172, v17
	v_fmac_f32_e32 v20, v172, v19
	ds_write_b32 v241, v2 offset:1088
	v_cvt_pk_bf16_f32 v2, v37, v38
	v_fma_f32 v49, -v175, v48, v93
	v_fma_f32 v50, v175, v47, v61
	v_fma_f32 v60, -v173, v20, v69
	v_fma_f32 v21, v173, v59, v21
	ds_write_b32 v241, v2 offset:1360
	v_cvt_pk_bf16_f32 v2, v39, v40
	v_fmac_f32_e32 v49, v174, v47
	v_fmac_f32_e32 v50, v174, v48
	v_fmac_f32_e32 v60, v172, v59
	v_fmac_f32_e32 v21, v172, v20
	ds_write_b32 v241, v2 offset:1632
	v_cvt_pk_bf16_f32 v2, v41, v42
	v_fma_f32 v51, -v175, v50, v94
	v_fma_f32 v52, v175, v49, v62
	v_fma_f32 v61, -v173, v21, v70
	v_fma_f32 v22, v173, v60, v22
	ds_write_b32 v241, v2 offset:1904
	v_cvt_pk_bf16_f32 v2, v43, v44
	v_fmac_f32_e32 v51, v174, v49
	v_fmac_f32_e32 v52, v174, v50
	v_fmac_f32_e32 v61, v172, v60
	v_fmac_f32_e32 v22, v172, v21
	ds_write_b32 v241, v2 offset:2176
	v_cvt_pk_bf16_f32 v2, v45, v46
	v_fma_f32 v53, -v175, v52, v95
	v_fma_f32 v54, v175, v51, v63
	v_fma_f32 v62, -v173, v22, v71
	v_fma_f32 v23, v173, v61, v23
	ds_write_b32 v241, v2 offset:2448
	v_cvt_pk_bf16_f32 v2, v47, v48
	v_fmac_f32_e32 v53, v174, v51
	v_fmac_f32_e32 v54, v174, v52
	v_fmac_f32_e32 v62, v172, v61
	v_fmac_f32_e32 v23, v172, v22
	ds_write_b32 v241, v2 offset:2720
	v_cvt_pk_bf16_f32 v2, v49, v50
	v_fma_f32 v55, -v175, v54, v96
	v_fma_f32 v56, v175, v53, v64
	v_fma_f32 v63, -v173, v23, v72
	v_fma_f32 v24, v173, v62, v24
	ds_write_b32 v241, v2 offset:2992
	v_cvt_pk_bf16_f32 v2, v51, v52
	v_fmac_f32_e32 v55, v174, v53
	v_fmac_f32_e32 v56, v174, v54
	v_fmac_f32_e32 v63, v172, v62
	v_fmac_f32_e32 v24, v172, v23
	ds_write_b32 v241, v2 offset:3264
	v_cvt_pk_bf16_f32 v2, v53, v54
	v_fma_f32 v57, -v175, v56, v97
	v_fmac_f32_e32 v65, v175, v55
	v_fma_f32 v64, -v173, v24, v73
	v_fma_f32 v25, v173, v63, v25
	ds_write_b32 v241, v2 offset:3536
	v_cvt_pk_bf16_f32 v2, v55, v56
	v_fmac_f32_e32 v57, v174, v55
	v_fmac_f32_e32 v65, v174, v56
	v_fmac_f32_e32 v64, v172, v63
	v_fmac_f32_e32 v25, v172, v24
	ds_write_b32 v241, v2 offset:3808
	v_cvt_pk_bf16_f32 v2, v57, v65
	v_fma_f32 v66, -v173, v25, v74
	v_fma_f32 v26, v173, v64, v26
	ds_write_b32 v241, v2 offset:4080
	v_cvt_pk_bf16_f32 v2, v58, v18
	v_fmac_f32_e32 v66, v172, v64
	v_fmac_f32_e32 v26, v172, v25
	ds_write_b32 v241, v2 offset:128
	v_cvt_pk_bf16_f32 v2, v17, v19
	v_fma_f32 v67, -v173, v26, v75
	v_fma_f32 v27, v173, v66, v27
	ds_write_b32 v241, v2 offset:400
	v_cvt_pk_bf16_f32 v2, v59, v20
	v_fmac_f32_e32 v67, v172, v66
	v_fmac_f32_e32 v27, v172, v26
	ds_write_b32 v241, v2 offset:672
	v_cvt_pk_bf16_f32 v2, v60, v21
	v_fma_f32 v68, -v173, v27, v76
	v_fma_f32 v28, v173, v67, v28
	ds_write_b32 v241, v2 offset:944
	v_cvt_pk_bf16_f32 v2, v61, v22
	v_fmac_f32_e32 v68, v172, v67
	v_fmac_f32_e32 v28, v172, v27
	ds_write_b32 v241, v2 offset:1216
	v_cvt_pk_bf16_f32 v2, v62, v23
	v_fma_f32 v69, -v173, v28, v77
	v_fma_f32 v29, v173, v68, v29
	ds_write_b32 v241, v2 offset:1488
	v_cvt_pk_bf16_f32 v2, v63, v24
	v_fmac_f32_e32 v69, v172, v68
	v_fmac_f32_e32 v29, v172, v28
	ds_write_b32 v241, v2 offset:1760
	v_cvt_pk_bf16_f32 v2, v64, v25
	v_fma_f32 v70, -v173, v29, v78
	v_fma_f32 v30, v173, v69, v30
	ds_write_b32 v241, v2 offset:2032
	v_cvt_pk_bf16_f32 v2, v66, v26
	v_fmac_f32_e32 v70, v172, v69
	v_fmac_f32_e32 v30, v172, v29
	ds_write_b32 v241, v2 offset:2304
	v_cvt_pk_bf16_f32 v2, v67, v27
	v_fma_f32 v71, -v173, v30, v79
	v_fma_f32 v31, v173, v70, v31
	ds_write_b32 v241, v2 offset:2576
	v_cvt_pk_bf16_f32 v2, v68, v28
	v_fmac_f32_e32 v71, v172, v70
	v_fmac_f32_e32 v31, v172, v30
	ds_write_b32 v241, v2 offset:2848
	v_cvt_pk_bf16_f32 v2, v69, v29
	v_fma_f32 v72, -v173, v31, v80
	v_fma_f32 v32, v173, v71, v32
	ds_write_b32 v241, v2 offset:3120
	v_cvt_pk_bf16_f32 v2, v70, v30
	v_fmac_f32_e32 v72, v172, v71
	v_fmac_f32_e32 v32, v172, v31
	ds_write_b32 v241, v2 offset:3392
	v_cvt_pk_bf16_f32 v2, v71, v31
	v_fma_f32 v180, -v173, v32, v81
	v_fmac_f32_e32 v33, v173, v72
	ds_write_b32 v241, v2 offset:3664
	v_cvt_pk_bf16_f32 v2, v72, v32
	v_fmac_f32_e32 v180, v172, v72
	v_fmac_f32_e32 v33, v172, v32
	ds_write_b32 v241, v2 offset:3936
	v_cvt_pk_bf16_f32 v2, v180, v33
	ds_write_b32 v241, v2 offset:4208
	ds_read_b32 v182, v251 offset:8704
	ds_read_b32 v183, v251 offset:8768
	ds_read_b32 v184, v251 offset:8832
	ds_read_b32 v185, v252 offset:8704
	ds_read_b32 v186, v253 offset:8704
	ds_read_b32 v187, v251 offset:9792
	ds_read_b32 v188, v251 offset:9856
	ds_read_b32 v189, v254 offset:8704
	ds_read_b128 v[2:5], v250
	ds_read_b128 v[6:9], v250 offset:64
	s_waitcnt lgkmcnt(1)
	v_mfma_f32_16x16x32_bf16 v[2:5], v[2:5], v[110:113], 0
	ds_read_b128 v[10:13], v250 offset:128
	s_waitcnt lgkmcnt(1)
	v_mfma_f32_16x16x32_bf16 v[2:5], v[6:9], v[106:109], v[2:5]
	ds_read_b128 v[6:9], v250 offset:192
	s_waitcnt lgkmcnt(1)
	v_mfma_f32_16x16x32_bf16 v[2:5], v[10:13], v[102:105], v[2:5]
	s_waitcnt lgkmcnt(0)
	v_mfma_f32_16x16x32_bf16 v[2:5], v[6:9], v[98:101], v[2:5]
	s_nop 0
	s_nop 6
	v_fma_f32 v2, v228, v182, v2
	v_mul_f32_e32 v6, 0x3d372713, v2
	v_mul_f32_e32 v6, v2, v6
	v_fma_f32 v6, v2, v6, v2
	v_mul_f32_e32 v6, 0xbfcc422a, v6
	v_mul_f32_e32 v6, 0x3fb8aa3b, v6
	v_exp_f32_e32 v6, v6
	s_nop 0
	v_add_f32_e32 v6, 1.0, v6
	v_rcp_f32_e32 v6, v6
	s_nop 0
	v_mul_f32_e32 v2, v2, v6
	v_cvt_pk_bf16_f32 v6, v2, v155
	s_nop 0
	v_fma_f32 v7, v228, v183, v3
	v_mul_f32_e32 v2, 0x3d372713, v7
	v_mul_f32_e32 v2, v7, v2
	v_fma_f32 v2, v7, v2, v7
	v_mul_f32_e32 v2, 0xbfcc422a, v2
	v_mul_f32_e32 v2, 0x3fb8aa3b, v2
	v_exp_f32_e32 v2, v2
	v_or_b32_e32 v3, s2, v244
	v_or_b32_e32 v178, s22, v3
	v_add_f32_e32 v2, 1.0, v2
	v_rcp_f32_e32 v8, v2
	v_lshlrev_b64 v[2:3], 11, v[178:179]
	v_lshl_add_u64 v[2:3], v[176:177], 0, v[2:3]
	global_store_short v[2:3], v6, off
	v_mul_f32_e32 v2, v7, v8
	v_cvt_pk_bf16_f32 v6, v2, v155
	v_mov_b32_e32 v3, s23
	s_nop 0
	v_fma_f32 v4, v228, v184, v4
	v_mul_f32_e32 v2, 0x3d372713, v4
	v_mul_f32_e32 v2, v4, v2
	v_fma_f32 v2, v4, v2, v4
	v_mul_f32_e32 v2, 0xbfcc422a, v2
	v_mul_f32_e32 v2, 0x3fb8aa3b, v2
	v_exp_f32_e32 v7, v2
	v_or_b32_e32 v2, 1, v178
	v_lshlrev_b64 v[2:3], 11, v[2:3]
	v_lshl_add_u64 v[2:3], v[176:177], 0, v[2:3]
	v_add_f32_e32 v7, 1.0, v7
	v_rcp_f32_e32 v7, v7
	global_store_short v[2:3], v6, off
	v_mov_b32_e32 v3, s23
	v_mul_f32_e32 v2, v4, v7
	v_cvt_pk_bf16_f32 v4, v2, v155
	s_nop 0
	v_fmac_f32_e32 v5, v228, v185
	v_mul_f32_e32 v2, 0x3d372713, v5
	v_mul_f32_e32 v2, v5, v2
	v_fma_f32 v2, v5, v2, v5
	v_mul_f32_e32 v2, 0xbfcc422a, v2
	v_mul_f32_e32 v2, 0x3fb8aa3b, v2
	v_exp_f32_e32 v6, v2
	v_or_b32_e32 v2, 2, v178
	v_lshlrev_b64 v[2:3], 11, v[2:3]
	v_lshl_add_u64 v[2:3], v[176:177], 0, v[2:3]
	v_add_f32_e32 v6, 1.0, v6
	v_rcp_f32_e32 v6, v6
	global_store_short v[2:3], v4, off
	v_or_b32_e32 v178, 3, v178
	v_mul_f32_e32 v2, v5, v6
	v_cvt_pk_bf16_f32 v14, v2, v155
	ds_read_b128 v[2:5], v250 offset:4352
	ds_read_b128 v[6:9], v250 offset:4416
	s_waitcnt lgkmcnt(1)
	v_mfma_f32_16x16x32_bf16 v[2:5], v[2:5], v[110:113], 0
	ds_read_b128 v[10:13], v250 offset:4480
	s_waitcnt lgkmcnt(1)
	v_mfma_f32_16x16x32_bf16 v[2:5], v[6:9], v[106:109], v[2:5]
	ds_read_b128 v[6:9], v250 offset:4544
	s_waitcnt lgkmcnt(1)
	v_mfma_f32_16x16x32_bf16 v[2:5], v[10:13], v[102:105], v[2:5]
	s_waitcnt lgkmcnt(0)
	v_mfma_f32_16x16x32_bf16 v[2:5], v[6:9], v[98:101], v[2:5]
	s_nop 0
	s_nop 6
	v_fma_f32 v2, v228, v186, v2
	v_mul_f32_e32 v6, 0x3d372713, v2
	v_mul_f32_e32 v6, v2, v6
	v_fma_f32 v6, v2, v6, v2
	v_mul_f32_e32 v6, 0xbfcc422a, v6
	v_mul_f32_e32 v6, 0x3fb8aa3b, v6
	v_exp_f32_e32 v6, v6
	s_nop 0
	v_add_f32_e32 v6, 1.0, v6
	v_rcp_f32_e32 v8, v6
	v_lshlrev_b64 v[6:7], 11, v[178:179]
	v_lshl_add_u64 v[6:7], v[176:177], 0, v[6:7]
	global_store_short v[6:7], v14, off
	v_mul_f32_e32 v2, v2, v8
	v_cvt_pk_bf16_f32 v6, v2, v155
	s_nop 0
	v_fma_f32 v7, v228, v187, v3
	v_mul_f32_e32 v2, 0x3d372713, v7
	v_mul_f32_e32 v2, v7, v2
	v_fma_f32 v2, v7, v2, v7
	v_mul_f32_e32 v2, 0xbfcc422a, v2
	v_mul_f32_e32 v2, 0x3fb8aa3b, v2
	v_exp_f32_e32 v2, v2
	v_or_b32_e32 v3, s3, v244
	v_or_b32_e32 v178, s22, v3
	v_add_f32_e32 v2, 1.0, v2
	v_rcp_f32_e32 v8, v2
	v_lshlrev_b64 v[2:3], 11, v[178:179]
	v_lshl_add_u64 v[2:3], v[176:177], 0, v[2:3]
	global_store_short v[2:3], v6, off
	v_mul_f32_e32 v2, v7, v8
	v_cvt_pk_bf16_f32 v6, v2, v155
	v_mov_b32_e32 v3, s23
	s_nop 0
	v_fma_f32 v4, v228, v188, v4
	v_mul_f32_e32 v2, 0x3d372713, v4
	v_mul_f32_e32 v2, v4, v2
	v_fma_f32 v2, v4, v2, v4
	v_mul_f32_e32 v2, 0xbfcc422a, v2
	v_mul_f32_e32 v2, 0x3fb8aa3b, v2
	v_exp_f32_e32 v7, v2
	v_or_b32_e32 v2, 1, v178
	v_lshlrev_b64 v[2:3], 11, v[2:3]
	v_lshl_add_u64 v[2:3], v[176:177], 0, v[2:3]
	v_add_f32_e32 v7, 1.0, v7
	v_rcp_f32_e32 v7, v7
	global_store_short v[2:3], v6, off
	v_mov_b32_e32 v3, s23
	v_mul_f32_e32 v2, v4, v7
	v_cvt_pk_bf16_f32 v4, v2, v155
	s_nop 0
	v_fmac_f32_e32 v5, v228, v189
	v_mul_f32_e32 v2, 0x3d372713, v5
	v_mul_f32_e32 v2, v5, v2
	v_fma_f32 v2, v5, v2, v5
	v_mul_f32_e32 v2, 0xbfcc422a, v2
	v_mul_f32_e32 v2, 0x3fb8aa3b, v2
	v_exp_f32_e32 v6, v2
	v_or_b32_e32 v2, 2, v178
	v_lshlrev_b64 v[2:3], 11, v[2:3]
	v_lshl_add_u64 v[2:3], v[176:177], 0, v[2:3]
	v_add_f32_e32 v6, 1.0, v6
	v_rcp_f32_e32 v6, v6
	global_store_short v[2:3], v4, off
	v_or_b32_e32 v178, 3, v178
	v_mul_f32_e32 v2, v5, v6
	v_cvt_pk_bf16_f32 v4, v2, v155
	v_lshlrev_b64 v[2:3], 11, v[178:179]
	v_lshl_add_u64 v[2:3], v[176:177], 0, v[2:3]
	global_store_short v[2:3], v4, off
	ds_read_b32 v2, v239 offset:256
	v_lshlrev_b32_e32 v4, 16, v150
	v_and_b32_e32 v5, 0xffff0000, v150
	s_waitcnt lgkmcnt(0)
	v_pk_mul_f32 v[4:5], v[2:3], v[4:5] op_sel_hi:[0,1]
	v_pk_mul_f32 v[18:19], v[138:139], v[4:5]
	v_lshlrev_b32_e32 v4, 16, v152
	v_and_b32_e32 v5, 0xffff0000, v152
	v_pk_mul_f32 v[4:5], v[2:3], v[4:5] op_sel_hi:[0,1]
	v_pk_mul_f32 v[22:23], v[126:127], v[4:5]
	v_lshlrev_b32_e32 v4, 16, v151
	v_and_b32_e32 v5, 0xffff0000, v151
	v_pk_mul_f32 v[4:5], v[2:3], v[4:5] op_sel_hi:[0,1]
	v_pk_mul_f32 v[20:21], v[140:141], v[4:5]
	v_lshlrev_b32_e32 v4, 16, v153
	v_and_b32_e32 v5, 0xffff0000, v153
	v_pk_mul_f32 v[2:3], v[2:3], v[4:5] op_sel_hi:[0,1]
	v_pk_mul_f32 v[24:25], v[128:129], v[2:3]
	v_cvt_pk_bf16_f32 v2, v18, v19
	v_cvt_pk_bf16_f32 v3, v20, v21
	v_cvt_pk_bf16_f32 v4, v22, v23
	s_nop 0
	v_cvt_pk_bf16_f32 v5, v24, v25
	ds_write_b128 v249, v[18:21] offset:8704
	ds_write_b128 v249, v[22:25] offset:8720
	v_mfma_f32_32x32x16_bf16 v[82:97], v[2:5], v[118:121], 0
	v_mfma_f32_32x32x16_bf16 v[34:49], v[2:5], v[122:125], 0
	s_nop 10
	v_fma_f32 v26, -v175, v65, v82
	v_fmac_f32_e32 v26, v174, v57
	v_mfma_f32_32x32x16_bf16 v[66:81], v[2:5], v[130:133], 0
	v_fma_f32 v27, v175, v57, v34
	v_fmac_f32_e32 v27, v174, v65
	v_fma_f32 v28, -v175, v27, v83
	v_fma_f32 v29, v175, v26, v35
	v_fmac_f32_e32 v28, v174, v26
	v_fmac_f32_e32 v29, v174, v27
	v_fma_f32 v30, -v175, v29, v84
	v_fma_f32 v31, v175, v28, v36
	v_fmac_f32_e32 v30, v174, v28
	v_fmac_f32_e32 v31, v174, v29
	v_fma_f32 v32, -v175, v31, v85
	v_fma_f32 v34, v175, v30, v37
	v_mfma_f32_32x32x16_bf16 v[2:17], v[2:5], v[134:137], 0
	v_fmac_f32_e32 v32, v174, v30
	v_fmac_f32_e32 v34, v174, v31
	v_fma_f32 v35, -v175, v34, v86
	v_fma_f32 v36, v175, v32, v38
	v_fmac_f32_e32 v35, v174, v32
	v_fmac_f32_e32 v36, v174, v34
	v_fma_f32 v37, -v175, v36, v87
	v_fma_f32 v38, v175, v35, v39
	v_fmac_f32_e32 v37, v174, v35
	v_fmac_f32_e32 v38, v174, v36
	v_fma_f32 v39, -v175, v38, v88
	v_fma_f32 v40, v175, v37, v40
	v_fmac_f32_e32 v39, v174, v37
	v_fmac_f32_e32 v40, v174, v38
	v_fma_f32 v50, -v175, v40, v89
	v_fma_f32 v41, v175, v39, v41
	v_fmac_f32_e32 v50, v174, v39
	v_fmac_f32_e32 v41, v174, v40
	v_fma_f32 v58, -v173, v33, v66
	v_fma_f32 v2, v173, v180, v2
	v_fma_f32 v51, -v175, v41, v90
	v_fma_f32 v42, v175, v50, v42
	v_fmac_f32_e32 v58, v172, v180
	v_fmac_f32_e32 v2, v172, v33
	v_cvt_pk_bf16_f32 v18, v26, v27
	v_fmac_f32_e32 v51, v174, v50
	v_fmac_f32_e32 v42, v174, v41
	v_fma_f32 v33, -v173, v2, v67
	v_fma_f32 v3, v173, v58, v3
	ds_write_b32 v241, v18
	v_cvt_pk_bf16_f32 v18, v28, v29
	v_fma_f32 v52, -v175, v42, v91
	v_fma_f32 v43, v175, v51, v43
	v_fmac_f32_e32 v33, v172, v58
	v_fmac_f32_e32 v3, v172, v2
	ds_write_b32 v241, v18 offset:272
	v_cvt_pk_bf16_f32 v18, v30, v31
	v_fmac_f32_e32 v52, v174, v51
	v_fmac_f32_e32 v43, v174, v42
	v_fma_f32 v59, -v173, v3, v68
	v_fma_f32 v4, v173, v33, v4
	ds_write_b32 v241, v18 offset:544
	v_cvt_pk_bf16_f32 v18, v32, v34
	v_fma_f32 v53, -v175, v43, v92
	v_fma_f32 v44, v175, v52, v44
	v_fmac_f32_e32 v59, v172, v33
	v_fmac_f32_e32 v4, v172, v3
	ds_write_b32 v241, v18 offset:816
	v_cvt_pk_bf16_f32 v18, v35, v36
	v_fmac_f32_e32 v53, v174, v52
	v_fmac_f32_e32 v44, v174, v43
	v_fma_f32 v60, -v173, v4, v69
	v_fma_f32 v5, v173, v59, v5
	ds_write_b32 v241, v18 offset:1088
	v_cvt_pk_bf16_f32 v18, v37, v38
	v_fma_f32 v54, -v175, v44, v93
	v_fma_f32 v45, v175, v53, v45
	v_fmac_f32_e32 v60, v172, v59
	v_fmac_f32_e32 v5, v172, v4
	ds_write_b32 v241, v18 offset:1360
	v_cvt_pk_bf16_f32 v18, v39, v40
	v_fmac_f32_e32 v54, v174, v53
	v_fmac_f32_e32 v45, v174, v44
	v_fma_f32 v61, -v173, v5, v70
	v_fma_f32 v6, v173, v60, v6
	ds_write_b32 v241, v18 offset:1632
	v_cvt_pk_bf16_f32 v18, v50, v41
	v_fma_f32 v55, -v175, v45, v94
	v_fma_f32 v46, v175, v54, v46
	v_fmac_f32_e32 v61, v172, v60
	v_fmac_f32_e32 v6, v172, v5
	ds_write_b32 v241, v18 offset:1904
	v_cvt_pk_bf16_f32 v18, v51, v42
	v_fmac_f32_e32 v55, v174, v54
	v_fmac_f32_e32 v46, v174, v45
	v_fma_f32 v62, -v173, v6, v71
	v_fma_f32 v7, v173, v61, v7
	ds_write_b32 v241, v18 offset:2176
	v_cvt_pk_bf16_f32 v18, v52, v43
	v_fma_f32 v56, -v175, v46, v95
	v_fma_f32 v47, v175, v55, v47
	v_fmac_f32_e32 v62, v172, v61
	v_fmac_f32_e32 v7, v172, v6
	ds_write_b32 v241, v18 offset:2448
	v_cvt_pk_bf16_f32 v18, v53, v44
	v_fmac_f32_e32 v56, v174, v55
	v_fmac_f32_e32 v47, v174, v46
	v_fma_f32 v63, -v173, v7, v72
	v_fma_f32 v8, v173, v62, v8
	ds_write_b32 v241, v18 offset:2720
	v_cvt_pk_bf16_f32 v18, v54, v45
	v_fma_f32 v57, -v175, v47, v96
	v_fma_f32 v48, v175, v56, v48
	v_fmac_f32_e32 v63, v172, v62
	v_fmac_f32_e32 v8, v172, v7
	ds_write_b32 v241, v18 offset:2992
	v_cvt_pk_bf16_f32 v18, v55, v46
	v_fmac_f32_e32 v57, v174, v56
	v_fmac_f32_e32 v48, v174, v47
	v_fma_f32 v64, -v173, v8, v73
	v_fma_f32 v9, v173, v63, v9
	ds_write_b32 v241, v18 offset:3264
	v_cvt_pk_bf16_f32 v18, v56, v47
	v_fma_f32 v150, -v175, v48, v97
	v_fmac_f32_e32 v49, v175, v57
	v_fmac_f32_e32 v64, v172, v63
	v_fmac_f32_e32 v9, v172, v8
	ds_write_b32 v241, v18 offset:3536
	v_cvt_pk_bf16_f32 v18, v57, v48
	v_fmac_f32_e32 v150, v174, v57
	v_fmac_f32_e32 v49, v174, v48
	v_fma_f32 v65, -v173, v9, v74
	v_fma_f32 v10, v173, v64, v10
	ds_write_b32 v241, v18 offset:3808
	v_cvt_pk_bf16_f32 v18, v150, v49
	ds_write_b32 v241, v18 offset:4080
	v_cvt_pk_bf16_f32 v2, v58, v2
	v_fmac_f32_e32 v65, v172, v64
	v_fmac_f32_e32 v10, v172, v9
	ds_write_b32 v241, v2 offset:128
	v_cvt_pk_bf16_f32 v2, v33, v3
	v_fma_f32 v66, -v173, v10, v75
	v_fma_f32 v11, v173, v65, v11
	ds_write_b32 v241, v2 offset:400
	v_cvt_pk_bf16_f32 v2, v59, v4
	v_fmac_f32_e32 v66, v172, v65
	v_fmac_f32_e32 v11, v172, v10
	ds_write_b32 v241, v2 offset:672
	v_cvt_pk_bf16_f32 v2, v60, v5
	v_fma_f32 v67, -v173, v11, v76
	v_fma_f32 v12, v173, v66, v12
	ds_write_b32 v241, v2 offset:944
	v_cvt_pk_bf16_f32 v2, v61, v6
	v_fmac_f32_e32 v67, v172, v66
	v_fmac_f32_e32 v12, v172, v11
	ds_write_b32 v241, v2 offset:1216
	v_cvt_pk_bf16_f32 v2, v62, v7
	v_fma_f32 v68, -v173, v12, v77
	v_fma_f32 v13, v173, v67, v13
	ds_write_b32 v241, v2 offset:1488
	v_cvt_pk_bf16_f32 v2, v63, v8
	v_fmac_f32_e32 v68, v172, v67
	v_fmac_f32_e32 v13, v172, v12
	ds_write_b32 v241, v2 offset:1760
	v_cvt_pk_bf16_f32 v2, v64, v9
	v_fma_f32 v69, -v173, v13, v78
	v_fma_f32 v14, v173, v68, v14
	ds_write_b32 v241, v2 offset:2032
	v_cvt_pk_bf16_f32 v2, v65, v10
	v_fmac_f32_e32 v69, v172, v68
	v_fmac_f32_e32 v14, v172, v13
	ds_write_b32 v241, v2 offset:2304
	v_cvt_pk_bf16_f32 v2, v66, v11
	v_fma_f32 v70, -v173, v14, v79
	v_fma_f32 v15, v173, v69, v15
	ds_write_b32 v241, v2 offset:2576
	v_cvt_pk_bf16_f32 v2, v67, v12
	v_fmac_f32_e32 v70, v172, v69
	v_fmac_f32_e32 v15, v172, v14
	ds_write_b32 v241, v2 offset:2848
	v_cvt_pk_bf16_f32 v2, v68, v13
	v_fma_f32 v71, -v173, v15, v80
	v_fma_f32 v16, v173, v70, v16
	ds_write_b32 v241, v2 offset:3120
	v_cvt_pk_bf16_f32 v2, v69, v14
	v_fmac_f32_e32 v71, v172, v70
	v_fmac_f32_e32 v16, v172, v15
	ds_write_b32 v241, v2 offset:3392
	v_cvt_pk_bf16_f32 v2, v70, v15
	v_fma_f32 v151, -v173, v16, v81
	v_fmac_f32_e32 v17, v173, v71
	ds_write_b32 v241, v2 offset:3664
	v_cvt_pk_bf16_f32 v2, v71, v16
	v_fmac_f32_e32 v151, v172, v71
	v_fmac_f32_e32 v17, v172, v16
	ds_write_b32 v241, v2 offset:3936
	v_cvt_pk_bf16_f32 v2, v151, v17
	ds_write_b32 v241, v2 offset:4208
	ds_read_b32 v182, v251 offset:8704
	ds_read_b32 v183, v251 offset:8768
	ds_read_b32 v184, v251 offset:8832
	ds_read_b32 v185, v252 offset:8704
	ds_read_b32 v186, v253 offset:8704
	ds_read_b32 v187, v251 offset:9792
	ds_read_b32 v188, v251 offset:9856
	ds_read_b32 v189, v254 offset:8704
	ds_read_b128 v[2:5], v250
	ds_read_b128 v[6:9], v250 offset:64
	s_waitcnt lgkmcnt(1)
	v_mfma_f32_16x16x32_bf16 v[2:5], v[2:5], v[110:113], 0
	ds_read_b128 v[10:13], v250 offset:128
	s_waitcnt lgkmcnt(1)
	v_mfma_f32_16x16x32_bf16 v[2:5], v[6:9], v[106:109], v[2:5]
	ds_read_b128 v[6:9], v250 offset:192
	s_waitcnt lgkmcnt(1)
	v_mfma_f32_16x16x32_bf16 v[2:5], v[10:13], v[102:105], v[2:5]
	s_waitcnt lgkmcnt(0)
	v_mfma_f32_16x16x32_bf16 v[2:5], v[6:9], v[98:101], v[2:5]
	s_nop 0
	s_nop 6
	v_fma_f32 v2, v228, v182, v2
	v_mul_f32_e32 v6, 0x3d372713, v2
	v_mul_f32_e32 v6, v2, v6
	v_fma_f32 v6, v2, v6, v2
	v_mul_f32_e32 v6, 0xbfcc422a, v6
	v_mul_f32_e32 v6, 0x3fb8aa3b, v6
	v_exp_f32_e32 v6, v6
	s_nop 0
	v_add_f32_e32 v6, 1.0, v6
	v_rcp_f32_e32 v6, v6
	s_nop 0
	v_mul_f32_e32 v2, v2, v6
	v_cvt_pk_bf16_f32 v6, v2, v155
	s_nop 0
	v_fma_f32 v7, v228, v183, v3
	v_mul_f32_e32 v2, 0x3d372713, v7
	v_mul_f32_e32 v2, v7, v2
	v_fma_f32 v2, v7, v2, v7
	v_mul_f32_e32 v2, 0xbfcc422a, v2
	v_mul_f32_e32 v2, 0x3fb8aa3b, v2
	v_exp_f32_e32 v2, v2
	v_or_b32_e32 v3, s2, v245
	v_or_b32_e32 v178, s22, v3
	v_add_f32_e32 v2, 1.0, v2
	v_rcp_f32_e32 v8, v2
	v_lshlrev_b64 v[2:3], 11, v[178:179]
	v_lshl_add_u64 v[2:3], v[176:177], 0, v[2:3]
	global_store_short v[2:3], v6, off
	v_mul_f32_e32 v2, v7, v8
	v_cvt_pk_bf16_f32 v6, v2, v155
	v_mov_b32_e32 v3, s23
	s_nop 0
	v_fma_f32 v4, v228, v184, v4
	v_mul_f32_e32 v2, 0x3d372713, v4
	v_mul_f32_e32 v2, v4, v2
	v_fma_f32 v2, v4, v2, v4
	v_mul_f32_e32 v2, 0xbfcc422a, v2
	v_mul_f32_e32 v2, 0x3fb8aa3b, v2
	v_exp_f32_e32 v7, v2
	v_or_b32_e32 v2, 1, v178
	v_lshlrev_b64 v[2:3], 11, v[2:3]
	v_lshl_add_u64 v[2:3], v[176:177], 0, v[2:3]
	v_add_f32_e32 v7, 1.0, v7
	v_rcp_f32_e32 v7, v7
	global_store_short v[2:3], v6, off
	v_mov_b32_e32 v3, s23
	v_mul_f32_e32 v2, v4, v7
	v_cvt_pk_bf16_f32 v4, v2, v155
	s_nop 0
	v_fmac_f32_e32 v5, v228, v185
	v_mul_f32_e32 v2, 0x3d372713, v5
	v_mul_f32_e32 v2, v5, v2
	v_fma_f32 v2, v5, v2, v5
	v_mul_f32_e32 v2, 0xbfcc422a, v2
	v_mul_f32_e32 v2, 0x3fb8aa3b, v2
	v_exp_f32_e32 v6, v2
	v_or_b32_e32 v2, 2, v178
	v_lshlrev_b64 v[2:3], 11, v[2:3]
	v_lshl_add_u64 v[2:3], v[176:177], 0, v[2:3]
	v_add_f32_e32 v6, 1.0, v6
	v_rcp_f32_e32 v6, v6
	global_store_short v[2:3], v4, off
	v_or_b32_e32 v178, 3, v178
	v_mul_f32_e32 v2, v5, v6
	v_cvt_pk_bf16_f32 v14, v2, v155
	ds_read_b128 v[2:5], v250 offset:4352
	ds_read_b128 v[6:9], v250 offset:4416
	s_waitcnt lgkmcnt(1)
	v_mfma_f32_16x16x32_bf16 v[2:5], v[2:5], v[110:113], 0
	ds_read_b128 v[10:13], v250 offset:4480
	s_waitcnt lgkmcnt(1)
	v_mfma_f32_16x16x32_bf16 v[2:5], v[6:9], v[106:109], v[2:5]
	ds_read_b128 v[6:9], v250 offset:4544
	s_waitcnt lgkmcnt(1)
	v_mfma_f32_16x16x32_bf16 v[2:5], v[10:13], v[102:105], v[2:5]
	v_and_b32_e32 v11, 0xffff0000, v149
	s_waitcnt lgkmcnt(0)
	v_mfma_f32_16x16x32_bf16 v[2:5], v[6:9], v[98:101], v[2:5]
	s_nop 0
	s_nop 6
	v_fma_f32 v2, v228, v186, v2
	v_mul_f32_e32 v6, 0x3d372713, v2
	v_mul_f32_e32 v6, v2, v6
	v_fma_f32 v6, v2, v6, v2
	v_mul_f32_e32 v6, 0xbfcc422a, v6
	v_mul_f32_e32 v6, 0x3fb8aa3b, v6
	v_exp_f32_e32 v6, v6
	v_lshlrev_b32_e32 v10, 16, v149
	v_add_f32_e32 v6, 1.0, v6
	v_rcp_f32_e32 v8, v6
	v_lshlrev_b64 v[6:7], 11, v[178:179]
	v_lshl_add_u64 v[6:7], v[176:177], 0, v[6:7]
	global_store_short v[6:7], v14, off
	v_mul_f32_e32 v2, v2, v8
	v_cvt_pk_bf16_f32 v6, v2, v155
	s_nop 0
	v_fma_f32 v7, v228, v187, v3
	v_mul_f32_e32 v2, 0x3d372713, v7
	v_mul_f32_e32 v2, v7, v2
	v_fma_f32 v2, v7, v2, v7
	v_mul_f32_e32 v2, 0xbfcc422a, v2
	v_mul_f32_e32 v2, 0x3fb8aa3b, v2
	v_exp_f32_e32 v2, v2
	v_or_b32_e32 v3, s3, v245
	v_or_b32_e32 v178, s22, v3
	v_add_f32_e32 v2, 1.0, v2
	v_rcp_f32_e32 v8, v2
	v_lshlrev_b64 v[2:3], 11, v[178:179]
	v_lshl_add_u64 v[2:3], v[176:177], 0, v[2:3]
	global_store_short v[2:3], v6, off
	v_mul_f32_e32 v2, v7, v8
	v_cvt_pk_bf16_f32 v6, v2, v155
	v_mov_b32_e32 v3, s23
	s_nop 0
	v_fma_f32 v4, v228, v188, v4
	v_mul_f32_e32 v2, 0x3d372713, v4
	v_mul_f32_e32 v2, v4, v2
	v_fma_f32 v2, v4, v2, v4
	v_mul_f32_e32 v2, 0xbfcc422a, v2
	v_mul_f32_e32 v2, 0x3fb8aa3b, v2
	v_exp_f32_e32 v7, v2
	v_or_b32_e32 v2, 1, v178
	v_lshlrev_b64 v[2:3], 11, v[2:3]
	v_lshl_add_u64 v[2:3], v[176:177], 0, v[2:3]
	v_add_f32_e32 v7, 1.0, v7
	v_rcp_f32_e32 v7, v7
	global_store_short v[2:3], v6, off
	v_mov_b32_e32 v3, s23
	v_mul_f32_e32 v2, v4, v7
	v_cvt_pk_bf16_f32 v4, v2, v155
	s_nop 0
	v_fmac_f32_e32 v5, v228, v189
	v_mul_f32_e32 v2, 0x3d372713, v5
	v_mul_f32_e32 v2, v5, v2
	v_fma_f32 v2, v5, v2, v5
	v_mul_f32_e32 v2, 0xbfcc422a, v2
	v_mul_f32_e32 v2, 0x3fb8aa3b, v2
	v_exp_f32_e32 v6, v2
	v_or_b32_e32 v2, 2, v178
	v_lshlrev_b64 v[2:3], 11, v[2:3]
	v_lshl_add_u64 v[2:3], v[176:177], 0, v[2:3]
	v_add_f32_e32 v6, 1.0, v6
	v_rcp_f32_e32 v6, v6
	global_store_short v[2:3], v4, off
	v_or_b32_e32 v178, 3, v178
	v_mul_f32_e32 v2, v5, v6
	v_cvt_pk_bf16_f32 v4, v2, v155
	v_lshlrev_b64 v[2:3], 11, v[178:179]
	v_lshl_add_u64 v[2:3], v[176:177], 0, v[2:3]
	global_store_short v[2:3], v4, off
	ds_read_b32 v8, v239 offset:320
	v_lshlrev_b32_e32 v4, 16, v148
	v_and_b32_e32 v5, 0xffff0000, v148
	v_lshlrev_b32_e32 v2, 16, v146
	v_and_b32_e32 v3, 0xffff0000, v146
	s_waitcnt lgkmcnt(0)
	v_pk_mul_f32 v[4:5], v[8:9], v[4:5] op_sel_hi:[0,1]
	v_pk_mul_f32 v[6:7], v[126:127], v[4:5]
	v_lshlrev_b32_e32 v4, 16, v147
	v_and_b32_e32 v5, 0xffff0000, v147
	v_pk_mul_f32 v[2:3], v[8:9], v[2:3] op_sel_hi:[0,1]
	v_pk_mul_f32 v[4:5], v[8:9], v[4:5] op_sel_hi:[0,1]
	v_pk_mul_f32 v[8:9], v[8:9], v[10:11] op_sel_hi:[0,1]
	v_pk_mul_f32 v[2:3], v[138:139], v[2:3]
	v_pk_mul_f32 v[4:5], v[140:141], v[4:5]
	v_pk_mul_f32 v[8:9], v[128:129], v[8:9]
	v_cvt_pk_bf16_f32 v10, v2, v3
	v_cvt_pk_bf16_f32 v11, v4, v5
	v_cvt_pk_bf16_f32 v12, v6, v7
	s_nop 0
	v_cvt_pk_bf16_f32 v13, v8, v9
	ds_write_b128 v249, v[2:5] offset:8704
	ds_write_b128 v249, v[6:9] offset:8720
	v_mfma_f32_32x32x16_bf16 v[82:97], v[10:13], v[118:121], 0
	v_mfma_f32_32x32x16_bf16 v[50:65], v[10:13], v[122:125], 0
	v_mfma_f32_32x32x16_bf16 v[66:81], v[10:13], v[130:133], 0
	v_mfma_f32_32x32x16_bf16 v[18:33], v[10:13], v[134:137], 0
	s_nop 8
	v_fma_f32 v10, -v175, v49, v82
	v_fma_f32 v11, v175, v150, v50
	v_fmac_f32_e32 v10, v174, v150
	v_fmac_f32_e32 v11, v174, v49
	v_fma_f32 v12, -v175, v11, v83
	v_fma_f32 v13, v175, v10, v51
	v_fmac_f32_e32 v12, v174, v10
	v_fmac_f32_e32 v13, v174, v11
	v_fma_f32 v14, -v175, v13, v84
	v_fma_f32 v15, v175, v12, v52
	v_fmac_f32_e32 v14, v174, v12
	v_fmac_f32_e32 v15, v174, v13
	v_fma_f32 v16, -v175, v15, v85
	v_fma_f32 v34, v175, v14, v53
	v_fmac_f32_e32 v16, v174, v14
	v_fmac_f32_e32 v34, v174, v15
	v_fma_f32 v35, -v175, v34, v86
	v_fma_f32 v36, v175, v16, v54
	v_fmac_f32_e32 v35, v174, v16
	v_fmac_f32_e32 v36, v174, v34
	v_fma_f32 v37, -v175, v36, v87
	v_fma_f32 v38, v175, v35, v55
	v_fmac_f32_e32 v37, v174, v35
	v_fmac_f32_e32 v38, v174, v36
	v_fma_f32 v39, -v175, v38, v88
	v_fma_f32 v40, v175, v37, v56
	v_fmac_f32_e32 v39, v174, v37
	v_fmac_f32_e32 v40, v174, v38
	v_fma_f32 v41, -v175, v40, v89
	v_fma_f32 v42, v175, v39, v57
	v_fmac_f32_e32 v41, v174, v39
	v_fmac_f32_e32 v42, v174, v40
	v_fma_f32 v43, -v175, v42, v90
	v_fma_f32 v44, v175, v41, v58
	v_fma_f32 v58, -v173, v17, v66
	v_fma_f32 v18, v173, v151, v18
	v_cvt_pk_bf16_f32 v2, v10, v11
	v_fmac_f32_e32 v43, v174, v41
	v_fmac_f32_e32 v44, v174, v42
	v_fmac_f32_e32 v58, v172, v151
	v_fmac_f32_e32 v18, v172, v17
	ds_write_b32 v241, v2
	v_cvt_pk_bf16_f32 v2, v12, v13
	v_fma_f32 v45, -v175, v44, v91
	v_fma_f32 v46, v175, v43, v59
	v_fma_f32 v17, -v173, v18, v67
	v_fma_f32 v19, v173, v58, v19
	ds_write_b32 v241, v2 offset:272
	v_cvt_pk_bf16_f32 v2, v14, v15
	v_fmac_f32_e32 v45, v174, v43
	v_fmac_f32_e32 v46, v174, v44
	v_fmac_f32_e32 v17, v172, v58
	v_fmac_f32_e32 v19, v172, v18
	ds_write_b32 v241, v2 offset:544
	v_cvt_pk_bf16_f32 v2, v16, v34
	v_fma_f32 v47, -v175, v46, v92
	v_fma_f32 v48, v175, v45, v60
	v_fma_f32 v59, -v173, v19, v68
	v_fma_f32 v20, v173, v17, v20
	ds_write_b32 v241, v2 offset:816
	v_cvt_pk_bf16_f32 v2, v35, v36
	v_fmac_f32_e32 v47, v174, v45
	v_fmac_f32_e32 v48, v174, v46
	v_fmac_f32_e32 v59, v172, v17
	v_fmac_f32_e32 v20, v172, v19
	ds_write_b32 v241, v2 offset:1088
	v_cvt_pk_bf16_f32 v2, v37, v38
	v_fma_f32 v49, -v175, v48, v93
	v_fma_f32 v50, v175, v47, v61
	v_fma_f32 v60, -v173, v20, v69
	v_fma_f32 v21, v173, v59, v21
	ds_write_b32 v241, v2 offset:1360
	v_cvt_pk_bf16_f32 v2, v39, v40
	v_fmac_f32_e32 v49, v174, v47
	v_fmac_f32_e32 v50, v174, v48
	v_fmac_f32_e32 v60, v172, v59
	v_fmac_f32_e32 v21, v172, v20
	ds_write_b32 v241, v2 offset:1632
	v_cvt_pk_bf16_f32 v2, v41, v42
	v_fma_f32 v51, -v175, v50, v94
	v_fma_f32 v52, v175, v49, v62
	v_fma_f32 v61, -v173, v21, v70
	v_fma_f32 v22, v173, v60, v22
	ds_write_b32 v241, v2 offset:1904
	v_cvt_pk_bf16_f32 v2, v43, v44
	v_fmac_f32_e32 v51, v174, v49
	v_fmac_f32_e32 v52, v174, v50
	v_fmac_f32_e32 v61, v172, v60
	v_fmac_f32_e32 v22, v172, v21
	ds_write_b32 v241, v2 offset:2176
	v_cvt_pk_bf16_f32 v2, v45, v46
	v_fma_f32 v53, -v175, v52, v95
	v_fma_f32 v54, v175, v51, v63
	v_fma_f32 v62, -v173, v22, v71
	v_fma_f32 v23, v173, v61, v23
	ds_write_b32 v241, v2 offset:2448
	v_cvt_pk_bf16_f32 v2, v47, v48
	v_fmac_f32_e32 v53, v174, v51
	v_fmac_f32_e32 v54, v174, v52
	v_fmac_f32_e32 v62, v172, v61
	v_fmac_f32_e32 v23, v172, v22
	ds_write_b32 v241, v2 offset:2720
	v_cvt_pk_bf16_f32 v2, v49, v50
	v_fma_f32 v55, -v175, v54, v96
	v_fma_f32 v56, v175, v53, v64
	v_fma_f32 v63, -v173, v23, v72
	v_fma_f32 v24, v173, v62, v24
	ds_write_b32 v241, v2 offset:2992
	v_cvt_pk_bf16_f32 v2, v51, v52
	v_fmac_f32_e32 v55, v174, v53
	v_fmac_f32_e32 v56, v174, v54
	v_fmac_f32_e32 v63, v172, v62
	v_fmac_f32_e32 v24, v172, v23
	ds_write_b32 v241, v2 offset:3264
	v_cvt_pk_bf16_f32 v2, v53, v54
	v_fma_f32 v57, -v175, v56, v97
	v_fmac_f32_e32 v65, v175, v55
	v_fma_f32 v64, -v173, v24, v73
	v_fma_f32 v25, v173, v63, v25
	ds_write_b32 v241, v2 offset:3536
	v_cvt_pk_bf16_f32 v2, v55, v56
	v_fmac_f32_e32 v57, v174, v55
	v_fmac_f32_e32 v65, v174, v56
	v_fmac_f32_e32 v64, v172, v63
	v_fmac_f32_e32 v25, v172, v24
	ds_write_b32 v241, v2 offset:3808
	v_cvt_pk_bf16_f32 v2, v57, v65
	v_fma_f32 v66, -v173, v25, v74
	v_fma_f32 v26, v173, v64, v26
	ds_write_b32 v241, v2 offset:4080
	v_cvt_pk_bf16_f32 v2, v58, v18
	v_fmac_f32_e32 v66, v172, v64
	v_fmac_f32_e32 v26, v172, v25
	ds_write_b32 v241, v2 offset:128
	v_cvt_pk_bf16_f32 v2, v17, v19
	v_fma_f32 v67, -v173, v26, v75
	v_fma_f32 v27, v173, v66, v27
	ds_write_b32 v241, v2 offset:400
	v_cvt_pk_bf16_f32 v2, v59, v20
	v_fmac_f32_e32 v67, v172, v66
	v_fmac_f32_e32 v27, v172, v26
	ds_write_b32 v241, v2 offset:672
	v_cvt_pk_bf16_f32 v2, v60, v21
	v_fma_f32 v68, -v173, v27, v76
	v_fma_f32 v28, v173, v67, v28
	ds_write_b32 v241, v2 offset:944
	v_cvt_pk_bf16_f32 v2, v61, v22
	v_fmac_f32_e32 v68, v172, v67
	v_fmac_f32_e32 v28, v172, v27
	ds_write_b32 v241, v2 offset:1216
	v_cvt_pk_bf16_f32 v2, v62, v23
	v_fma_f32 v69, -v173, v28, v77
	v_fma_f32 v29, v173, v68, v29
	ds_write_b32 v241, v2 offset:1488
	v_cvt_pk_bf16_f32 v2, v63, v24
	v_fmac_f32_e32 v69, v172, v68
	v_fmac_f32_e32 v29, v172, v28
	ds_write_b32 v241, v2 offset:1760
	v_cvt_pk_bf16_f32 v2, v64, v25
	v_fma_f32 v70, -v173, v29, v78
	v_fma_f32 v30, v173, v69, v30
	ds_write_b32 v241, v2 offset:2032
	v_cvt_pk_bf16_f32 v2, v66, v26
	v_fmac_f32_e32 v70, v172, v69
	v_fmac_f32_e32 v30, v172, v29
	ds_write_b32 v241, v2 offset:2304
	v_cvt_pk_bf16_f32 v2, v67, v27
	v_fma_f32 v71, -v173, v30, v79
	v_fma_f32 v31, v173, v70, v31
	ds_write_b32 v241, v2 offset:2576
	v_cvt_pk_bf16_f32 v2, v68, v28
	v_fmac_f32_e32 v71, v172, v70
	v_fmac_f32_e32 v31, v172, v30
	ds_write_b32 v241, v2 offset:2848
	v_cvt_pk_bf16_f32 v2, v69, v29
	v_fma_f32 v72, -v173, v31, v80
	v_fma_f32 v32, v173, v71, v32
	ds_write_b32 v241, v2 offset:3120
	v_cvt_pk_bf16_f32 v2, v70, v30
	v_fmac_f32_e32 v72, v172, v71
	v_fmac_f32_e32 v32, v172, v31
	ds_write_b32 v241, v2 offset:3392
	v_cvt_pk_bf16_f32 v2, v71, v31
	v_fma_f32 v146, -v173, v32, v81
	v_fmac_f32_e32 v33, v173, v72
	ds_write_b32 v241, v2 offset:3664
	v_cvt_pk_bf16_f32 v2, v72, v32
	v_fmac_f32_e32 v146, v172, v72
	v_fmac_f32_e32 v33, v172, v32
	ds_write_b32 v241, v2 offset:3936
	v_cvt_pk_bf16_f32 v2, v146, v33
	ds_write_b32 v241, v2 offset:4208
	ds_read_b32 v182, v251 offset:8704
	ds_read_b32 v183, v251 offset:8768
	ds_read_b32 v184, v251 offset:8832
	ds_read_b32 v185, v252 offset:8704
	ds_read_b32 v186, v253 offset:8704
	ds_read_b32 v187, v251 offset:9792
	ds_read_b32 v188, v251 offset:9856
	ds_read_b32 v189, v254 offset:8704
	ds_read_b128 v[2:5], v250
	ds_read_b128 v[6:9], v250 offset:64
	s_waitcnt lgkmcnt(1)
	v_mfma_f32_16x16x32_bf16 v[2:5], v[2:5], v[110:113], 0
	ds_read_b128 v[10:13], v250 offset:128
	s_waitcnt lgkmcnt(1)
	v_mfma_f32_16x16x32_bf16 v[2:5], v[6:9], v[106:109], v[2:5]
	ds_read_b128 v[6:9], v250 offset:192
	s_waitcnt lgkmcnt(1)
	v_mfma_f32_16x16x32_bf16 v[2:5], v[10:13], v[102:105], v[2:5]
	s_waitcnt lgkmcnt(0)
	v_mfma_f32_16x16x32_bf16 v[2:5], v[6:9], v[98:101], v[2:5]
	s_nop 0
	s_nop 6
	v_fma_f32 v2, v228, v182, v2
	v_mul_f32_e32 v6, 0x3d372713, v2
	v_mul_f32_e32 v6, v2, v6
	v_fma_f32 v6, v2, v6, v2
	v_mul_f32_e32 v6, 0xbfcc422a, v6
	v_mul_f32_e32 v6, 0x3fb8aa3b, v6
	v_exp_f32_e32 v6, v6
	s_nop 0
	v_add_f32_e32 v6, 1.0, v6
	v_rcp_f32_e32 v6, v6
	s_nop 0
	v_mul_f32_e32 v2, v2, v6
	v_cvt_pk_bf16_f32 v6, v2, v155
	s_nop 0
	v_fma_f32 v7, v228, v183, v3
	v_mul_f32_e32 v2, 0x3d372713, v7
	v_mul_f32_e32 v2, v7, v2
	v_fma_f32 v2, v7, v2, v7
	v_mul_f32_e32 v2, 0xbfcc422a, v2
	v_mul_f32_e32 v2, 0x3fb8aa3b, v2
	v_exp_f32_e32 v2, v2
	v_or_b32_e32 v3, s2, v246
	v_or_b32_e32 v178, s22, v3
	v_add_f32_e32 v2, 1.0, v2
	v_rcp_f32_e32 v8, v2
	v_lshlrev_b64 v[2:3], 11, v[178:179]
	v_lshl_add_u64 v[2:3], v[176:177], 0, v[2:3]
	global_store_short v[2:3], v6, off
	v_mul_f32_e32 v2, v7, v8
	v_cvt_pk_bf16_f32 v6, v2, v155
	v_mov_b32_e32 v3, s23
	s_nop 0
	v_fma_f32 v4, v228, v184, v4
	v_mul_f32_e32 v2, 0x3d372713, v4
	v_mul_f32_e32 v2, v4, v2
	v_fma_f32 v2, v4, v2, v4
	v_mul_f32_e32 v2, 0xbfcc422a, v2
	v_mul_f32_e32 v2, 0x3fb8aa3b, v2
	v_exp_f32_e32 v7, v2
	v_or_b32_e32 v2, 1, v178
	v_lshlrev_b64 v[2:3], 11, v[2:3]
	v_lshl_add_u64 v[2:3], v[176:177], 0, v[2:3]
	v_add_f32_e32 v7, 1.0, v7
	v_rcp_f32_e32 v7, v7
	global_store_short v[2:3], v6, off
	v_mov_b32_e32 v3, s23
	v_mul_f32_e32 v2, v4, v7
	v_cvt_pk_bf16_f32 v4, v2, v155
	s_nop 0
	v_fmac_f32_e32 v5, v228, v185
	v_mul_f32_e32 v2, 0x3d372713, v5
	v_mul_f32_e32 v2, v5, v2
	v_fma_f32 v2, v5, v2, v5
	v_mul_f32_e32 v2, 0xbfcc422a, v2
	v_mul_f32_e32 v2, 0x3fb8aa3b, v2
	v_exp_f32_e32 v6, v2
	v_or_b32_e32 v2, 2, v178
	v_lshlrev_b64 v[2:3], 11, v[2:3]
	v_lshl_add_u64 v[2:3], v[176:177], 0, v[2:3]
	v_add_f32_e32 v6, 1.0, v6
	v_rcp_f32_e32 v6, v6
	global_store_short v[2:3], v4, off
	v_or_b32_e32 v178, 3, v178
	v_mul_f32_e32 v2, v5, v6
	v_cvt_pk_bf16_f32 v14, v2, v155
	ds_read_b128 v[2:5], v250 offset:4352
	ds_read_b128 v[6:9], v250 offset:4416
	s_waitcnt lgkmcnt(1)
	v_mfma_f32_16x16x32_bf16 v[2:5], v[2:5], v[110:113], 0
	ds_read_b128 v[10:13], v250 offset:4480
	s_waitcnt lgkmcnt(1)
	v_mfma_f32_16x16x32_bf16 v[2:5], v[6:9], v[106:109], v[2:5]
	ds_read_b128 v[6:9], v250 offset:4544
	s_waitcnt lgkmcnt(1)
	v_mfma_f32_16x16x32_bf16 v[2:5], v[10:13], v[102:105], v[2:5]
	s_waitcnt lgkmcnt(0)
	v_mfma_f32_16x16x32_bf16 v[2:5], v[6:9], v[98:101], v[2:5]
	s_nop 0
	s_nop 6
	v_fma_f32 v2, v228, v186, v2
	v_mul_f32_e32 v6, 0x3d372713, v2
	v_mul_f32_e32 v6, v2, v6
	v_fma_f32 v6, v2, v6, v2
	v_mul_f32_e32 v6, 0xbfcc422a, v6
	v_mul_f32_e32 v6, 0x3fb8aa3b, v6
	v_exp_f32_e32 v6, v6
	s_nop 0
	v_add_f32_e32 v6, 1.0, v6
	v_rcp_f32_e32 v8, v6
	v_lshlrev_b64 v[6:7], 11, v[178:179]
	v_lshl_add_u64 v[6:7], v[176:177], 0, v[6:7]
	global_store_short v[6:7], v14, off
	v_mul_f32_e32 v2, v2, v8
	v_cvt_pk_bf16_f32 v6, v2, v155
	s_nop 0
	v_fma_f32 v7, v228, v187, v3
	v_mul_f32_e32 v2, 0x3d372713, v7
	v_mul_f32_e32 v2, v7, v2
	v_fma_f32 v2, v7, v2, v7
	v_mul_f32_e32 v2, 0xbfcc422a, v2
	v_mul_f32_e32 v2, 0x3fb8aa3b, v2
	v_exp_f32_e32 v2, v2
	v_or_b32_e32 v3, s3, v246
	v_or_b32_e32 v178, s22, v3
	v_add_f32_e32 v2, 1.0, v2
	v_rcp_f32_e32 v8, v2
	v_lshlrev_b64 v[2:3], 11, v[178:179]
	v_lshl_add_u64 v[2:3], v[176:177], 0, v[2:3]
	global_store_short v[2:3], v6, off
	v_mul_f32_e32 v2, v7, v8
	v_cvt_pk_bf16_f32 v6, v2, v155
	v_mov_b32_e32 v3, s23
	s_nop 0
	v_fma_f32 v4, v228, v188, v4
	v_mul_f32_e32 v2, 0x3d372713, v4
	v_mul_f32_e32 v2, v4, v2
	v_fma_f32 v2, v4, v2, v4
	v_mul_f32_e32 v2, 0xbfcc422a, v2
	v_mul_f32_e32 v2, 0x3fb8aa3b, v2
	v_exp_f32_e32 v7, v2
	v_or_b32_e32 v2, 1, v178
	v_lshlrev_b64 v[2:3], 11, v[2:3]
	v_lshl_add_u64 v[2:3], v[176:177], 0, v[2:3]
	v_add_f32_e32 v7, 1.0, v7
	v_rcp_f32_e32 v7, v7
	global_store_short v[2:3], v6, off
	v_mov_b32_e32 v3, s23
	v_mul_f32_e32 v2, v4, v7
	v_cvt_pk_bf16_f32 v4, v2, v155
	s_nop 0
	v_fmac_f32_e32 v5, v228, v189
	v_mul_f32_e32 v2, 0x3d372713, v5
	v_mul_f32_e32 v2, v5, v2
	v_fma_f32 v2, v5, v2, v5
	v_mul_f32_e32 v2, 0xbfcc422a, v2
	v_mul_f32_e32 v2, 0x3fb8aa3b, v2
	v_exp_f32_e32 v6, v2
	v_or_b32_e32 v2, 2, v178
	v_lshlrev_b64 v[2:3], 11, v[2:3]
	v_lshl_add_u64 v[2:3], v[176:177], 0, v[2:3]
	v_add_f32_e32 v6, 1.0, v6
	v_rcp_f32_e32 v6, v6
	global_store_short v[2:3], v4, off
	v_or_b32_e32 v178, 3, v178
	v_mul_f32_e32 v2, v5, v6
	v_cvt_pk_bf16_f32 v4, v2, v155
	v_lshlrev_b64 v[2:3], 11, v[178:179]
	v_lshl_add_u64 v[2:3], v[176:177], 0, v[2:3]
	global_store_short v[2:3], v4, off
	ds_read_b32 v2, v239 offset:384
	v_lshlrev_b32_e32 v4, 16, v142
	v_and_b32_e32 v5, 0xffff0000, v142
	s_waitcnt lgkmcnt(0)
	v_pk_mul_f32 v[4:5], v[2:3], v[4:5] op_sel_hi:[0,1]
	v_pk_mul_f32 v[18:19], v[138:139], v[4:5]
	v_lshlrev_b32_e32 v4, 16, v144
	v_and_b32_e32 v5, 0xffff0000, v144
	v_pk_mul_f32 v[4:5], v[2:3], v[4:5] op_sel_hi:[0,1]
	v_pk_mul_f32 v[22:23], v[126:127], v[4:5]
	v_lshlrev_b32_e32 v4, 16, v143
	v_and_b32_e32 v5, 0xffff0000, v143
	v_pk_mul_f32 v[4:5], v[2:3], v[4:5] op_sel_hi:[0,1]
	v_pk_mul_f32 v[20:21], v[140:141], v[4:5]
	v_lshlrev_b32_e32 v4, 16, v145
	v_and_b32_e32 v5, 0xffff0000, v145
	v_pk_mul_f32 v[2:3], v[2:3], v[4:5] op_sel_hi:[0,1]
	v_pk_mul_f32 v[24:25], v[128:129], v[2:3]
	v_cvt_pk_bf16_f32 v2, v18, v19
	v_cvt_pk_bf16_f32 v3, v20, v21
	v_cvt_pk_bf16_f32 v4, v22, v23
	s_nop 0
	v_cvt_pk_bf16_f32 v5, v24, v25
	ds_write_b128 v249, v[18:21] offset:8704
	ds_write_b128 v249, v[22:25] offset:8720
	v_mfma_f32_32x32x16_bf16 v[82:97], v[2:5], v[118:121], 0
	v_mfma_f32_32x32x16_bf16 v[34:49], v[2:5], v[122:125], 0
	s_nop 10
	v_fma_f32 v26, -v175, v65, v82
	v_fmac_f32_e32 v26, v174, v57
	v_mfma_f32_32x32x16_bf16 v[66:81], v[2:5], v[130:133], 0
	v_fma_f32 v27, v175, v57, v34
	v_fmac_f32_e32 v27, v174, v65
	v_fma_f32 v28, -v175, v27, v83
	v_fma_f32 v29, v175, v26, v35
	v_fmac_f32_e32 v28, v174, v26
	v_fmac_f32_e32 v29, v174, v27
	v_fma_f32 v30, -v175, v29, v84
	v_fma_f32 v31, v175, v28, v36
	v_fmac_f32_e32 v30, v174, v28
	v_fmac_f32_e32 v31, v174, v29
	v_fma_f32 v32, -v175, v31, v85
	v_fma_f32 v34, v175, v30, v37
	v_mfma_f32_32x32x16_bf16 v[2:17], v[2:5], v[134:137], 0
	v_fmac_f32_e32 v32, v174, v30
	v_fmac_f32_e32 v34, v174, v31
	v_fma_f32 v35, -v175, v34, v86
	v_fma_f32 v36, v175, v32, v38
	v_fmac_f32_e32 v35, v174, v32
	v_fmac_f32_e32 v36, v174, v34
	v_fma_f32 v37, -v175, v36, v87
	v_fma_f32 v38, v175, v35, v39
	v_fmac_f32_e32 v37, v174, v35
	v_fmac_f32_e32 v38, v174, v36
	v_fma_f32 v39, -v175, v38, v88
	v_fma_f32 v40, v175, v37, v40
	v_fmac_f32_e32 v39, v174, v37
	v_fmac_f32_e32 v40, v174, v38
	v_fma_f32 v50, -v175, v40, v89
	v_fma_f32 v41, v175, v39, v41
	v_fmac_f32_e32 v50, v174, v39
	v_fmac_f32_e32 v41, v174, v40
	v_fma_f32 v58, -v173, v33, v66
	v_fma_f32 v2, v173, v146, v2
	v_fma_f32 v51, -v175, v41, v90
	v_fma_f32 v42, v175, v50, v42
	v_fmac_f32_e32 v58, v172, v146
	v_fmac_f32_e32 v2, v172, v33
	v_cvt_pk_bf16_f32 v18, v26, v27
	v_fmac_f32_e32 v51, v174, v50
	v_fmac_f32_e32 v42, v174, v41
	v_fma_f32 v33, -v173, v2, v67
	v_fma_f32 v3, v173, v58, v3
	ds_write_b32 v241, v18
	v_cvt_pk_bf16_f32 v18, v28, v29
	v_fma_f32 v52, -v175, v42, v91
	v_fma_f32 v43, v175, v51, v43
	v_fmac_f32_e32 v33, v172, v58
	v_fmac_f32_e32 v3, v172, v2
	ds_write_b32 v241, v18 offset:272
	v_cvt_pk_bf16_f32 v18, v30, v31
	v_fmac_f32_e32 v52, v174, v51
	v_fmac_f32_e32 v43, v174, v42
	v_fma_f32 v59, -v173, v3, v68
	v_fma_f32 v4, v173, v33, v4
	ds_write_b32 v241, v18 offset:544
	v_cvt_pk_bf16_f32 v18, v32, v34
	v_fma_f32 v53, -v175, v43, v92
	v_fma_f32 v44, v175, v52, v44
	v_fmac_f32_e32 v59, v172, v33
	v_fmac_f32_e32 v4, v172, v3
	ds_write_b32 v241, v18 offset:816
	v_cvt_pk_bf16_f32 v18, v35, v36
	v_fmac_f32_e32 v53, v174, v52
	v_fmac_f32_e32 v44, v174, v43
	v_fma_f32 v60, -v173, v4, v69
	v_fma_f32 v5, v173, v59, v5
	ds_write_b32 v241, v18 offset:1088
	v_cvt_pk_bf16_f32 v18, v37, v38
	v_fma_f32 v54, -v175, v44, v93
	v_fma_f32 v45, v175, v53, v45
	v_fmac_f32_e32 v60, v172, v59
	v_fmac_f32_e32 v5, v172, v4
	ds_write_b32 v241, v18 offset:1360
	v_cvt_pk_bf16_f32 v18, v39, v40
	v_fmac_f32_e32 v54, v174, v53
	v_fmac_f32_e32 v45, v174, v44
	v_fma_f32 v61, -v173, v5, v70
	v_fma_f32 v6, v173, v60, v6
	ds_write_b32 v241, v18 offset:1632
	v_cvt_pk_bf16_f32 v18, v50, v41
	v_fma_f32 v55, -v175, v45, v94
	v_fma_f32 v46, v175, v54, v46
	v_fmac_f32_e32 v61, v172, v60
	v_fmac_f32_e32 v6, v172, v5
	ds_write_b32 v241, v18 offset:1904
	v_cvt_pk_bf16_f32 v18, v51, v42
	v_fmac_f32_e32 v55, v174, v54
	v_fmac_f32_e32 v46, v174, v45
	v_fma_f32 v62, -v173, v6, v71
	v_fma_f32 v7, v173, v61, v7
	ds_write_b32 v241, v18 offset:2176
	v_cvt_pk_bf16_f32 v18, v52, v43
	v_fma_f32 v56, -v175, v46, v95
	v_fma_f32 v47, v175, v55, v47
	v_fmac_f32_e32 v62, v172, v61
	v_fmac_f32_e32 v7, v172, v6
	ds_write_b32 v241, v18 offset:2448
	v_cvt_pk_bf16_f32 v18, v53, v44
	v_fmac_f32_e32 v56, v174, v55
	v_fmac_f32_e32 v47, v174, v46
	v_fma_f32 v63, -v173, v7, v72
	v_fma_f32 v8, v173, v62, v8
	ds_write_b32 v241, v18 offset:2720
	v_cvt_pk_bf16_f32 v18, v54, v45
	v_fma_f32 v57, -v175, v47, v96
	v_fma_f32 v48, v175, v56, v48
	v_fmac_f32_e32 v63, v172, v62
	v_fmac_f32_e32 v8, v172, v7
	ds_write_b32 v241, v18 offset:2992
	v_cvt_pk_bf16_f32 v18, v55, v46
	v_fmac_f32_e32 v57, v174, v56
	v_fmac_f32_e32 v48, v174, v47
	v_fma_f32 v64, -v173, v8, v73
	v_fma_f32 v9, v173, v63, v9
	ds_write_b32 v241, v18 offset:3264
	v_cvt_pk_bf16_f32 v18, v56, v47
	v_fma_f32 v142, -v175, v48, v97
	v_fmac_f32_e32 v49, v175, v57
	v_fmac_f32_e32 v64, v172, v63
	v_fmac_f32_e32 v9, v172, v8
	ds_write_b32 v241, v18 offset:3536
	v_cvt_pk_bf16_f32 v18, v57, v48
	v_fmac_f32_e32 v142, v174, v57
	v_fmac_f32_e32 v49, v174, v48
	v_fma_f32 v65, -v173, v9, v74
	v_fma_f32 v10, v173, v64, v10
	ds_write_b32 v241, v18 offset:3808
	v_cvt_pk_bf16_f32 v18, v142, v49
	ds_write_b32 v241, v18 offset:4080
	v_cvt_pk_bf16_f32 v2, v58, v2
	v_fmac_f32_e32 v65, v172, v64
	v_fmac_f32_e32 v10, v172, v9
	ds_write_b32 v241, v2 offset:128
	v_cvt_pk_bf16_f32 v2, v33, v3
	v_fma_f32 v66, -v173, v10, v75
	v_fma_f32 v11, v173, v65, v11
	ds_write_b32 v241, v2 offset:400
	v_cvt_pk_bf16_f32 v2, v59, v4
	v_fmac_f32_e32 v66, v172, v65
	v_fmac_f32_e32 v11, v172, v10
	ds_write_b32 v241, v2 offset:672
	v_cvt_pk_bf16_f32 v2, v60, v5
	v_fma_f32 v67, -v173, v11, v76
	v_fma_f32 v12, v173, v66, v12
	ds_write_b32 v241, v2 offset:944
	v_cvt_pk_bf16_f32 v2, v61, v6
	v_fmac_f32_e32 v67, v172, v66
	v_fmac_f32_e32 v12, v172, v11
	ds_write_b32 v241, v2 offset:1216
	v_cvt_pk_bf16_f32 v2, v62, v7
	v_fma_f32 v68, -v173, v12, v77
	v_fma_f32 v13, v173, v67, v13
	ds_write_b32 v241, v2 offset:1488
	v_cvt_pk_bf16_f32 v2, v63, v8
	v_fmac_f32_e32 v68, v172, v67
	v_fmac_f32_e32 v13, v172, v12
	ds_write_b32 v241, v2 offset:1760
	v_cvt_pk_bf16_f32 v2, v64, v9
	v_fma_f32 v69, -v173, v13, v78
	v_fma_f32 v14, v173, v68, v14
	ds_write_b32 v241, v2 offset:2032
	v_cvt_pk_bf16_f32 v2, v65, v10
	v_fmac_f32_e32 v69, v172, v68
	v_fmac_f32_e32 v14, v172, v13
	ds_write_b32 v241, v2 offset:2304
	v_cvt_pk_bf16_f32 v2, v66, v11
	v_fma_f32 v70, -v173, v14, v79
	v_fma_f32 v15, v173, v69, v15
	ds_write_b32 v241, v2 offset:2576
	v_cvt_pk_bf16_f32 v2, v67, v12
	v_fmac_f32_e32 v70, v172, v69
	v_fmac_f32_e32 v15, v172, v14
	ds_write_b32 v241, v2 offset:2848
	v_cvt_pk_bf16_f32 v2, v68, v13
	v_fma_f32 v71, -v173, v15, v80
	v_fma_f32 v16, v173, v70, v16
	ds_write_b32 v241, v2 offset:3120
	v_cvt_pk_bf16_f32 v2, v69, v14
	v_fmac_f32_e32 v71, v172, v70
	v_fmac_f32_e32 v16, v172, v15
	ds_write_b32 v241, v2 offset:3392
	v_cvt_pk_bf16_f32 v2, v70, v15
	v_fma_f32 v143, -v173, v16, v81
	v_fmac_f32_e32 v17, v173, v71
	ds_write_b32 v241, v2 offset:3664
	v_cvt_pk_bf16_f32 v2, v71, v16
	v_fmac_f32_e32 v143, v172, v71
	v_fmac_f32_e32 v17, v172, v16
	ds_write_b32 v241, v2 offset:3936
	v_cvt_pk_bf16_f32 v2, v143, v17
	ds_write_b32 v241, v2 offset:4208
	ds_read_b32 v182, v251 offset:8704
	ds_read_b32 v183, v251 offset:8768
	ds_read_b32 v184, v251 offset:8832
	ds_read_b32 v185, v252 offset:8704
	ds_read_b32 v186, v253 offset:8704
	ds_read_b32 v187, v251 offset:9792
	ds_read_b32 v188, v251 offset:9856
	ds_read_b32 v189, v254 offset:8704
	ds_read_b128 v[2:5], v250
	ds_read_b128 v[6:9], v250 offset:64
	s_waitcnt lgkmcnt(1)
	v_mfma_f32_16x16x32_bf16 v[2:5], v[2:5], v[110:113], 0
	ds_read_b128 v[10:13], v250 offset:128
	s_waitcnt lgkmcnt(1)
	v_mfma_f32_16x16x32_bf16 v[2:5], v[6:9], v[106:109], v[2:5]
	ds_read_b128 v[6:9], v250 offset:192
	s_waitcnt lgkmcnt(1)
	v_mfma_f32_16x16x32_bf16 v[2:5], v[10:13], v[102:105], v[2:5]
	s_waitcnt lgkmcnt(0)
	v_mfma_f32_16x16x32_bf16 v[2:5], v[6:9], v[98:101], v[2:5]
	s_nop 0
	s_nop 6
	v_fma_f32 v2, v228, v182, v2
	v_mul_f32_e32 v6, 0x3d372713, v2
	v_mul_f32_e32 v6, v2, v6
	v_fma_f32 v6, v2, v6, v2
	v_mul_f32_e32 v6, 0xbfcc422a, v6
	v_mul_f32_e32 v6, 0x3fb8aa3b, v6
	v_exp_f32_e32 v6, v6
	s_nop 0
	v_add_f32_e32 v6, 1.0, v6
	v_rcp_f32_e32 v6, v6
	s_nop 0
	v_mul_f32_e32 v2, v2, v6
	v_cvt_pk_bf16_f32 v6, v2, v155
	s_nop 0
	v_fma_f32 v7, v228, v183, v3
	v_mul_f32_e32 v2, 0x3d372713, v7
	v_mul_f32_e32 v2, v7, v2
	v_fma_f32 v2, v7, v2, v7
	v_mul_f32_e32 v2, 0xbfcc422a, v2
	v_mul_f32_e32 v2, 0x3fb8aa3b, v2
	v_exp_f32_e32 v2, v2
	v_or_b32_e32 v3, s2, v247
	v_or_b32_e32 v178, s22, v3
	v_add_f32_e32 v2, 1.0, v2
	v_rcp_f32_e32 v8, v2
	v_lshlrev_b64 v[2:3], 11, v[178:179]
	v_lshl_add_u64 v[2:3], v[176:177], 0, v[2:3]
	global_store_short v[2:3], v6, off
	v_mul_f32_e32 v2, v7, v8
	v_cvt_pk_bf16_f32 v6, v2, v155
	v_mov_b32_e32 v3, s23
	s_nop 0
	v_fma_f32 v4, v228, v184, v4
	v_mul_f32_e32 v2, 0x3d372713, v4
	v_mul_f32_e32 v2, v4, v2
	v_fma_f32 v2, v4, v2, v4
	v_mul_f32_e32 v2, 0xbfcc422a, v2
	v_mul_f32_e32 v2, 0x3fb8aa3b, v2
	v_exp_f32_e32 v7, v2
	v_or_b32_e32 v2, 1, v178
	v_lshlrev_b64 v[2:3], 11, v[2:3]
	v_lshl_add_u64 v[2:3], v[176:177], 0, v[2:3]
	v_add_f32_e32 v7, 1.0, v7
	v_rcp_f32_e32 v7, v7
	global_store_short v[2:3], v6, off
	v_mov_b32_e32 v3, s23
	v_mul_f32_e32 v2, v4, v7
	v_cvt_pk_bf16_f32 v4, v2, v155
	s_nop 0
	v_fmac_f32_e32 v5, v228, v185
	v_mul_f32_e32 v2, 0x3d372713, v5
	v_mul_f32_e32 v2, v5, v2
	v_fma_f32 v2, v5, v2, v5
	v_mul_f32_e32 v2, 0xbfcc422a, v2
	v_mul_f32_e32 v2, 0x3fb8aa3b, v2
	v_exp_f32_e32 v6, v2
	v_or_b32_e32 v2, 2, v178
	v_lshlrev_b64 v[2:3], 11, v[2:3]
	v_lshl_add_u64 v[2:3], v[176:177], 0, v[2:3]
	v_add_f32_e32 v6, 1.0, v6
	v_rcp_f32_e32 v6, v6
	global_store_short v[2:3], v4, off
	v_or_b32_e32 v178, 3, v178
	v_mul_f32_e32 v2, v5, v6
	v_cvt_pk_bf16_f32 v14, v2, v155
	ds_read_b128 v[2:5], v250 offset:4352
	ds_read_b128 v[6:9], v250 offset:4416
	s_waitcnt lgkmcnt(1)
	v_mfma_f32_16x16x32_bf16 v[2:5], v[2:5], v[110:113], 0
	ds_read_b128 v[10:13], v250 offset:4480
	s_waitcnt lgkmcnt(1)
	v_mfma_f32_16x16x32_bf16 v[2:5], v[6:9], v[106:109], v[2:5]
	ds_read_b128 v[6:9], v250 offset:4544
	s_waitcnt lgkmcnt(1)
	v_mfma_f32_16x16x32_bf16 v[2:5], v[10:13], v[102:105], v[2:5]
	v_and_b32_e32 v11, 0xffff0000, v117
	s_waitcnt lgkmcnt(0)
	v_mfma_f32_16x16x32_bf16 v[2:5], v[6:9], v[98:101], v[2:5]
	s_nop 0
	s_nop 6
	v_fma_f32 v2, v228, v186, v2
	v_mul_f32_e32 v6, 0x3d372713, v2
	v_mul_f32_e32 v6, v2, v6
	v_fma_f32 v6, v2, v6, v2
	v_mul_f32_e32 v6, 0xbfcc422a, v6
	v_mul_f32_e32 v6, 0x3fb8aa3b, v6
	v_exp_f32_e32 v6, v6
	v_lshlrev_b32_e32 v10, 16, v117
	v_add_f32_e32 v6, 1.0, v6
	v_rcp_f32_e32 v8, v6
	v_lshlrev_b64 v[6:7], 11, v[178:179]
	v_lshl_add_u64 v[6:7], v[176:177], 0, v[6:7]
	global_store_short v[6:7], v14, off
	v_mul_f32_e32 v2, v2, v8
	v_cvt_pk_bf16_f32 v6, v2, v155
	s_nop 0
	v_fma_f32 v7, v228, v187, v3
	v_mul_f32_e32 v2, 0x3d372713, v7
	v_mul_f32_e32 v2, v7, v2
	v_fma_f32 v2, v7, v2, v7
	v_mul_f32_e32 v2, 0xbfcc422a, v2
	v_mul_f32_e32 v2, 0x3fb8aa3b, v2
	v_exp_f32_e32 v2, v2
	v_or_b32_e32 v3, s3, v247
	v_or_b32_e32 v178, s22, v3
	v_add_f32_e32 v2, 1.0, v2
	v_rcp_f32_e32 v8, v2
	v_lshlrev_b64 v[2:3], 11, v[178:179]
	v_lshl_add_u64 v[2:3], v[176:177], 0, v[2:3]
	global_store_short v[2:3], v6, off
	v_mul_f32_e32 v2, v7, v8
	v_cvt_pk_bf16_f32 v6, v2, v155
	v_mov_b32_e32 v3, s23
	s_nop 0
	v_fma_f32 v4, v228, v188, v4
	v_mul_f32_e32 v2, 0x3d372713, v4
	v_mul_f32_e32 v2, v4, v2
	v_fma_f32 v2, v4, v2, v4
	v_mul_f32_e32 v2, 0xbfcc422a, v2
	v_mul_f32_e32 v2, 0x3fb8aa3b, v2
	v_exp_f32_e32 v7, v2
	v_or_b32_e32 v2, 1, v178
	v_lshlrev_b64 v[2:3], 11, v[2:3]
	v_lshl_add_u64 v[2:3], v[176:177], 0, v[2:3]
	v_add_f32_e32 v7, 1.0, v7
	v_rcp_f32_e32 v7, v7
	global_store_short v[2:3], v6, off
	v_mov_b32_e32 v3, s23
	v_mul_f32_e32 v2, v4, v7
	v_cvt_pk_bf16_f32 v4, v2, v155
	v_and_b32_e32 v7, 0xffff0000, v116
	s_nop 0
	v_fmac_f32_e32 v5, v228, v189
	v_mul_f32_e32 v2, 0x3d372713, v5
	v_mul_f32_e32 v2, v5, v2
	v_fma_f32 v2, v5, v2, v5
	v_mul_f32_e32 v2, 0xbfcc422a, v2
	v_mul_f32_e32 v2, 0x3fb8aa3b, v2
	v_exp_f32_e32 v6, v2
	v_or_b32_e32 v2, 2, v178
	v_lshlrev_b64 v[2:3], 11, v[2:3]
	v_lshl_add_u64 v[2:3], v[176:177], 0, v[2:3]
	v_add_f32_e32 v6, 1.0, v6
	v_rcp_f32_e32 v6, v6
	global_store_short v[2:3], v4, off
	v_or_b32_e32 v178, 3, v178
	v_mul_f32_e32 v2, v5, v6
	v_cvt_pk_bf16_f32 v4, v2, v155
	v_lshlrev_b64 v[2:3], 11, v[178:179]
	v_lshl_add_u64 v[2:3], v[176:177], 0, v[2:3]
	global_store_short v[2:3], v4, off
	ds_read_b32 v2, v239 offset:448
	v_lshlrev_b32_e32 v6, 16, v116
	v_lshlrev_b32_e32 v4, 16, v114
	v_and_b32_e32 v5, 0xffff0000, v114
	s_waitcnt lgkmcnt(0)
	v_pk_mul_f32 v[6:7], v[2:3], v[6:7] op_sel_hi:[0,1]
	v_pk_mul_f32 v[8:9], v[126:127], v[6:7]
	v_lshlrev_b32_e32 v6, 16, v115
	v_and_b32_e32 v7, 0xffff0000, v115
	v_pk_mul_f32 v[4:5], v[2:3], v[4:5] op_sel_hi:[0,1]
	v_pk_mul_f32 v[6:7], v[2:3], v[6:7] op_sel_hi:[0,1]
	v_pk_mul_f32 v[2:3], v[2:3], v[10:11] op_sel_hi:[0,1]
	v_pk_mul_f32 v[4:5], v[138:139], v[4:5]
	v_pk_mul_f32 v[6:7], v[140:141], v[6:7]
	v_pk_mul_f32 v[10:11], v[128:129], v[2:3]
	v_cvt_pk_bf16_f32 v12, v4, v5
	v_cvt_pk_bf16_f32 v13, v6, v7
	v_cvt_pk_bf16_f32 v14, v8, v9
	s_nop 0
	v_cvt_pk_bf16_f32 v15, v10, v11
	ds_write_b128 v249, v[4:7] offset:8704
	ds_write_b128 v249, v[8:11] offset:8720
	v_mfma_f32_32x32x16_bf16 v[82:97], v[12:15], v[118:121], 0
	v_mfma_f32_32x32x16_bf16 v[50:65], v[12:15], v[122:125], 0
	v_mfma_f32_32x32x16_bf16 v[66:81], v[12:15], v[130:133], 0
	v_mfma_f32_32x32x16_bf16 v[18:33], v[12:15], v[134:137], 0
	s_nop 8
	v_fma_f32 v12, -v175, v49, v82
	v_fmac_f32_e32 v12, v174, v142
	v_fma_f32 v13, v175, v142, v50
	v_fmac_f32_e32 v13, v174, v49
	v_fma_f32 v15, v175, v12, v51
	v_fma_f32 v14, -v175, v13, v83
	v_fmac_f32_e32 v15, v174, v13
	v_fmac_f32_e32 v14, v174, v12
	v_fma_f32 v16, -v175, v15, v84
	v_fmac_f32_e32 v16, v174, v14
	v_fma_f32 v34, v175, v14, v52
	v_fmac_f32_e32 v34, v174, v15
	v_fma_f32 v36, v175, v16, v53
	v_fma_f32 v35, -v175, v34, v85
	v_fmac_f32_e32 v36, v174, v34
	v_fmac_f32_e32 v35, v174, v16
	v_fma_f32 v37, -v175, v36, v86
	v_fmac_f32_e32 v37, v174, v35
	v_fma_f32 v38, v175, v35, v54
	v_fmac_f32_e32 v38, v174, v36
	v_fma_f32 v40, v175, v37, v55
	v_fma_f32 v39, -v175, v38, v87
	v_fmac_f32_e32 v40, v174, v38
	v_fmac_f32_e32 v39, v174, v37
	v_fma_f32 v41, -v175, v40, v88
	v_fmac_f32_e32 v41, v174, v39
	v_fma_f32 v42, v175, v39, v56
	v_fmac_f32_e32 v42, v174, v40
	v_fma_f32 v44, v175, v41, v57
	v_fma_f32 v43, -v175, v42, v89
	v_fmac_f32_e32 v44, v174, v42
	v_fmac_f32_e32 v43, v174, v41
	v_fma_f32 v45, -v175, v44, v90
	v_fmac_f32_e32 v45, v174, v43
	v_fma_f32 v46, v175, v43, v58
	v_fma_f32 v48, v175, v45, v59
	v_fma_f32 v59, -v173, v17, v66
	v_fma_f32 v18, v173, v143, v18
	v_cvt_pk_bf16_f32 v4, v12, v13
	v_fmac_f32_e32 v46, v174, v44
	v_fmac_f32_e32 v59, v172, v143
	v_fmac_f32_e32 v18, v172, v17
	ds_write_b32 v241, v4
	v_cvt_pk_bf16_f32 v4, v14, v15
	v_fma_f32 v47, -v175, v46, v91
	v_fma_f32 v17, -v173, v18, v67
	v_fma_f32 v19, v173, v59, v19
	ds_write_b32 v241, v4 offset:272
	v_cvt_pk_bf16_f32 v4, v16, v34
	v_fmac_f32_e32 v47, v174, v45
	v_fmac_f32_e32 v48, v174, v46
	v_fmac_f32_e32 v17, v172, v59
	v_fmac_f32_e32 v19, v172, v18
	ds_write_b32 v241, v4 offset:544
	v_cvt_pk_bf16_f32 v4, v35, v36
	v_fma_f32 v49, -v175, v48, v92
	v_fma_f32 v50, v175, v47, v60
	v_fma_f32 v60, -v173, v19, v68
	v_fma_f32 v20, v173, v17, v20
	ds_write_b32 v241, v4 offset:816
	v_cvt_pk_bf16_f32 v4, v37, v38
	v_fmac_f32_e32 v49, v174, v47
	v_fmac_f32_e32 v50, v174, v48
	v_fmac_f32_e32 v60, v172, v17
	v_fmac_f32_e32 v20, v172, v19
	ds_write_b32 v241, v4 offset:1088
	v_cvt_pk_bf16_f32 v4, v39, v40
	v_fma_f32 v51, -v175, v50, v93
	v_fma_f32 v52, v175, v49, v61
	v_fma_f32 v61, -v173, v20, v69
	v_fma_f32 v21, v173, v60, v21
	ds_write_b32 v241, v4 offset:1360
	v_cvt_pk_bf16_f32 v4, v41, v42
	v_fmac_f32_e32 v51, v174, v49
	v_fmac_f32_e32 v52, v174, v50
	v_fmac_f32_e32 v61, v172, v60
	v_fmac_f32_e32 v21, v172, v20
	ds_write_b32 v241, v4 offset:1632
	v_cvt_pk_bf16_f32 v4, v43, v44
	v_fma_f32 v53, -v175, v52, v94
	v_fma_f32 v54, v175, v51, v62
	v_fma_f32 v62, -v173, v21, v70
	v_fma_f32 v22, v173, v61, v22
	ds_write_b32 v241, v4 offset:1904
	v_cvt_pk_bf16_f32 v4, v45, v46
	v_fmac_f32_e32 v53, v174, v51
	v_fmac_f32_e32 v54, v174, v52
	v_fmac_f32_e32 v62, v172, v61
	v_fmac_f32_e32 v22, v172, v21
	ds_write_b32 v241, v4 offset:2176
	v_cvt_pk_bf16_f32 v4, v47, v48
	v_fma_f32 v55, -v175, v54, v95
	v_fma_f32 v56, v175, v53, v63
	v_fma_f32 v63, -v173, v22, v71
	v_fma_f32 v23, v173, v62, v23
	ds_write_b32 v241, v4 offset:2448
	v_cvt_pk_bf16_f32 v4, v49, v50
	v_fmac_f32_e32 v55, v174, v53
	v_fmac_f32_e32 v56, v174, v54
	v_fmac_f32_e32 v63, v172, v62
	v_fmac_f32_e32 v23, v172, v22
	ds_write_b32 v241, v4 offset:2720
	v_cvt_pk_bf16_f32 v4, v51, v52
	v_fma_f32 v57, -v175, v56, v96
	v_fma_f32 v58, v175, v55, v64
	v_fma_f32 v64, -v173, v23, v72
	v_fma_f32 v24, v173, v63, v24
	ds_write_b32 v241, v4 offset:2992
	v_cvt_pk_bf16_f32 v4, v53, v54
	v_fmac_f32_e32 v57, v174, v55
	v_fmac_f32_e32 v58, v174, v56
	v_fmac_f32_e32 v64, v172, v63
	v_fmac_f32_e32 v24, v172, v23
	ds_write_b32 v241, v4 offset:3264
	v_cvt_pk_bf16_f32 v4, v55, v56
	v_fma_f32 v2, -v175, v58, v97
	v_fmac_f32_e32 v65, v175, v57
	v_fma_f32 v66, -v173, v24, v73
	v_fma_f32 v25, v173, v64, v25
	ds_write_b32 v241, v4 offset:3536
	v_cvt_pk_bf16_f32 v4, v57, v58
	v_fmac_f32_e32 v2, v174, v57
	v_fmac_f32_e32 v65, v174, v58
	v_fmac_f32_e32 v66, v172, v64
	v_fmac_f32_e32 v25, v172, v24
	ds_write_b32 v241, v4 offset:3808
	v_cvt_pk_bf16_f32 v4, v2, v65
	v_fma_f32 v67, -v173, v25, v74
	v_fma_f32 v26, v173, v66, v26
	ds_write_b32 v241, v4 offset:4080
	v_cvt_pk_bf16_f32 v4, v59, v18
	v_fmac_f32_e32 v67, v172, v66
	v_fmac_f32_e32 v26, v172, v25
	ds_write_b32 v241, v4 offset:128
	v_cvt_pk_bf16_f32 v4, v17, v19
	v_fma_f32 v68, -v173, v26, v75
	v_fma_f32 v27, v173, v67, v27
	ds_write_b32 v241, v4 offset:400
	v_cvt_pk_bf16_f32 v4, v60, v20
	v_fmac_f32_e32 v68, v172, v67
	v_fmac_f32_e32 v27, v172, v26
	ds_write_b32 v241, v4 offset:672
	v_cvt_pk_bf16_f32 v4, v61, v21
	v_fma_f32 v69, -v173, v27, v76
	v_fma_f32 v28, v173, v68, v28
	ds_write_b32 v241, v4 offset:944
	v_cvt_pk_bf16_f32 v4, v62, v22
	v_fmac_f32_e32 v69, v172, v68
	v_fmac_f32_e32 v28, v172, v27
	ds_write_b32 v241, v4 offset:1216
	v_cvt_pk_bf16_f32 v4, v63, v23
	v_fma_f32 v70, -v173, v28, v77
	v_fma_f32 v29, v173, v69, v29
	ds_write_b32 v241, v4 offset:1488
	v_cvt_pk_bf16_f32 v4, v64, v24
	v_fmac_f32_e32 v70, v172, v69
	v_fmac_f32_e32 v29, v172, v28
	ds_write_b32 v241, v4 offset:1760
	v_cvt_pk_bf16_f32 v4, v66, v25
	v_fma_f32 v71, -v173, v29, v78
	v_fma_f32 v30, v173, v70, v30
	ds_write_b32 v241, v4 offset:2032
	v_cvt_pk_bf16_f32 v4, v67, v26
	v_fmac_f32_e32 v71, v172, v70
	v_fmac_f32_e32 v30, v172, v29
	ds_write_b32 v241, v4 offset:2304
	v_cvt_pk_bf16_f32 v4, v68, v27
	v_fma_f32 v72, -v173, v30, v79
	v_fma_f32 v31, v173, v71, v31
	ds_write_b32 v241, v4 offset:2576
	v_cvt_pk_bf16_f32 v4, v69, v28
	v_fmac_f32_e32 v72, v172, v71
	v_fmac_f32_e32 v31, v172, v30
	ds_write_b32 v241, v4 offset:2848
	v_cvt_pk_bf16_f32 v4, v70, v29
	v_fma_f32 v73, -v173, v31, v80
	v_fma_f32 v32, v173, v72, v32
	ds_write_b32 v241, v4 offset:3120
	v_cvt_pk_bf16_f32 v4, v71, v30
	v_fmac_f32_e32 v73, v172, v72
	v_fmac_f32_e32 v32, v172, v31
	ds_write_b32 v241, v4 offset:3392
	v_cvt_pk_bf16_f32 v4, v72, v31
	v_fma_f32 v3, -v173, v32, v81
	v_fmac_f32_e32 v33, v173, v73
	ds_write_b32 v241, v4 offset:3664
	v_cvt_pk_bf16_f32 v4, v73, v32
	v_fmac_f32_e32 v3, v172, v73
	v_fmac_f32_e32 v33, v172, v32
	ds_write_b32 v241, v4 offset:3936
	v_cvt_pk_bf16_f32 v4, v3, v33
	ds_write_b32 v241, v4 offset:4208
	ds_read_b32 v182, v251 offset:8704
	ds_read_b32 v183, v251 offset:8768
	ds_read_b32 v184, v251 offset:8832
	ds_read_b32 v185, v252 offset:8704
	ds_read_b32 v186, v253 offset:8704
	ds_read_b32 v187, v251 offset:9792
	ds_read_b32 v188, v251 offset:9856
	ds_read_b32 v189, v254 offset:8704
	ds_read_b128 v[4:7], v250
	ds_read_b128 v[8:11], v250 offset:64
	s_waitcnt lgkmcnt(1)
	v_mfma_f32_16x16x32_bf16 v[4:7], v[4:7], v[110:113], 0
	ds_read_b128 v[12:15], v250 offset:128
	s_waitcnt lgkmcnt(1)
	v_mfma_f32_16x16x32_bf16 v[4:7], v[8:11], v[106:109], v[4:7]
	ds_read_b128 v[8:11], v250 offset:192
	s_waitcnt lgkmcnt(1)
	v_mfma_f32_16x16x32_bf16 v[4:7], v[12:15], v[102:105], v[4:7]
	s_waitcnt lgkmcnt(0)
	v_mfma_f32_16x16x32_bf16 v[4:7], v[8:11], v[98:101], v[4:7]
	s_nop 0
	s_nop 6
	v_fma_f32 v4, v228, v182, v4
	v_mul_f32_e32 v8, 0x3d372713, v4
	v_mul_f32_e32 v8, v4, v8
	v_fma_f32 v8, v4, v8, v4
	v_mul_f32_e32 v8, 0xbfcc422a, v8
	v_mul_f32_e32 v8, 0x3fb8aa3b, v8
	v_exp_f32_e32 v8, v8
	s_nop 0
	v_add_f32_e32 v8, 1.0, v8
	v_rcp_f32_e32 v8, v8
	s_nop 0
	v_mul_f32_e32 v4, v4, v8
	v_cvt_pk_bf16_f32 v8, v4, v155
	s_nop 0
	v_fma_f32 v9, v228, v183, v5
	v_mul_f32_e32 v4, 0x3d372713, v9
	v_mul_f32_e32 v4, v9, v4
	v_fma_f32 v4, v9, v4, v9
	v_mul_f32_e32 v4, 0xbfcc422a, v4
	v_mul_f32_e32 v4, 0x3fb8aa3b, v4
	v_exp_f32_e32 v4, v4
	v_or_b32_e32 v5, s2, v248
	v_or_b32_e32 v178, s22, v5
	v_add_f32_e32 v4, 1.0, v4
	v_rcp_f32_e32 v10, v4
	v_lshlrev_b64 v[4:5], 11, v[178:179]
	v_lshl_add_u64 v[4:5], v[176:177], 0, v[4:5]
	global_store_short v[4:5], v8, off
	v_mul_f32_e32 v4, v9, v10
	v_cvt_pk_bf16_f32 v8, v4, v155
	v_mov_b32_e32 v5, s23
	s_nop 0
	v_fma_f32 v6, v228, v184, v6
	v_mul_f32_e32 v4, 0x3d372713, v6
	v_mul_f32_e32 v4, v6, v4
	v_fma_f32 v4, v6, v4, v6
	v_mul_f32_e32 v4, 0xbfcc422a, v4
	v_mul_f32_e32 v4, 0x3fb8aa3b, v4
	v_exp_f32_e32 v9, v4
	v_or_b32_e32 v4, 1, v178
	v_lshlrev_b64 v[4:5], 11, v[4:5]
	v_lshl_add_u64 v[4:5], v[176:177], 0, v[4:5]
	v_add_f32_e32 v9, 1.0, v9
	v_rcp_f32_e32 v9, v9
	global_store_short v[4:5], v8, off
	v_mov_b32_e32 v5, s23
	v_mul_f32_e32 v4, v6, v9
	v_cvt_pk_bf16_f32 v6, v4, v155
	s_nop 0
	v_fmac_f32_e32 v7, v228, v185
	v_mul_f32_e32 v4, 0x3d372713, v7
	v_mul_f32_e32 v4, v7, v4
	v_fma_f32 v4, v7, v4, v7
	v_mul_f32_e32 v4, 0xbfcc422a, v4
	v_mul_f32_e32 v4, 0x3fb8aa3b, v4
	v_exp_f32_e32 v8, v4
	v_or_b32_e32 v4, 2, v178
	v_lshlrev_b64 v[4:5], 11, v[4:5]
	v_lshl_add_u64 v[4:5], v[176:177], 0, v[4:5]
	v_add_f32_e32 v8, 1.0, v8
	v_rcp_f32_e32 v8, v8
	global_store_short v[4:5], v6, off
	v_or_b32_e32 v178, 3, v178
	v_mul_f32_e32 v4, v7, v8
	v_cvt_pk_bf16_f32 v16, v4, v155
	ds_read_b128 v[4:7], v250 offset:4352
	ds_read_b128 v[8:11], v250 offset:4416
	s_waitcnt lgkmcnt(1)
	v_mfma_f32_16x16x32_bf16 v[4:7], v[4:7], v[110:113], 0
	ds_read_b128 v[12:15], v250 offset:4480
	s_waitcnt lgkmcnt(1)
	v_mfma_f32_16x16x32_bf16 v[4:7], v[8:11], v[106:109], v[4:7]
	ds_read_b128 v[8:11], v250 offset:4544
	s_waitcnt lgkmcnt(1)
	v_mfma_f32_16x16x32_bf16 v[4:7], v[12:15], v[102:105], v[4:7]
	s_waitcnt lgkmcnt(0)
	v_mfma_f32_16x16x32_bf16 v[4:7], v[8:11], v[98:101], v[4:7]
	s_nop 0
	s_nop 6
	v_fma_f32 v4, v228, v186, v4
	v_mul_f32_e32 v8, 0x3d372713, v4
	v_mul_f32_e32 v8, v4, v8
	v_fma_f32 v8, v4, v8, v4
	v_mul_f32_e32 v8, 0xbfcc422a, v8
	v_mul_f32_e32 v8, 0x3fb8aa3b, v8
	v_exp_f32_e32 v8, v8
	s_nop 0
	v_add_f32_e32 v8, 1.0, v8
	v_rcp_f32_e32 v10, v8
	v_lshlrev_b64 v[8:9], 11, v[178:179]
	v_lshl_add_u64 v[8:9], v[176:177], 0, v[8:9]
	global_store_short v[8:9], v16, off
	v_mul_f32_e32 v4, v4, v10
	v_cvt_pk_bf16_f32 v8, v4, v155
	s_nop 0
	v_fma_f32 v9, v228, v187, v5
	v_mul_f32_e32 v4, 0x3d372713, v9
	v_mul_f32_e32 v4, v9, v4
	v_fma_f32 v4, v9, v4, v9
	v_mul_f32_e32 v4, 0xbfcc422a, v4
	v_mul_f32_e32 v4, 0x3fb8aa3b, v4
	v_exp_f32_e32 v4, v4
	v_or_b32_e32 v5, s3, v248
	v_or_b32_e32 v178, s22, v5
	v_add_f32_e32 v4, 1.0, v4
	v_rcp_f32_e32 v10, v4
	v_lshlrev_b64 v[4:5], 11, v[178:179]
	v_lshl_add_u64 v[4:5], v[176:177], 0, v[4:5]
	global_store_short v[4:5], v8, off
	v_mul_f32_e32 v4, v9, v10
	v_cvt_pk_bf16_f32 v8, v4, v155
	v_mov_b32_e32 v5, s23
	s_nop 0
	v_fma_f32 v6, v228, v188, v6
	v_mul_f32_e32 v4, 0x3d372713, v6
	v_mul_f32_e32 v4, v6, v4
	v_fma_f32 v4, v6, v4, v6
	v_mul_f32_e32 v4, 0xbfcc422a, v4
	v_mul_f32_e32 v4, 0x3fb8aa3b, v4
	v_exp_f32_e32 v9, v4
	v_or_b32_e32 v4, 1, v178
	v_lshlrev_b64 v[4:5], 11, v[4:5]
	v_lshl_add_u64 v[4:5], v[176:177], 0, v[4:5]
	v_add_f32_e32 v9, 1.0, v9
	v_rcp_f32_e32 v9, v9
	global_store_short v[4:5], v8, off
	v_mov_b32_e32 v5, s23
	v_mul_f32_e32 v4, v6, v9
	v_cvt_pk_bf16_f32 v6, v4, v155
	s_nop 0
	v_fmac_f32_e32 v7, v228, v189
	v_mul_f32_e32 v4, 0x3d372713, v7
	v_mul_f32_e32 v4, v7, v4
	v_fma_f32 v4, v7, v4, v7
	v_mul_f32_e32 v4, 0xbfcc422a, v4
	v_mul_f32_e32 v4, 0x3fb8aa3b, v4
	v_exp_f32_e32 v8, v4
	v_or_b32_e32 v4, 2, v178
	v_lshlrev_b64 v[4:5], 11, v[4:5]
	v_lshl_add_u64 v[4:5], v[176:177], 0, v[4:5]
	v_add_f32_e32 v8, 1.0, v8
	v_rcp_f32_e32 v8, v8
	global_store_short v[4:5], v6, off
	v_or_b32_e32 v178, 3, v178
	v_mul_f32_e32 v4, v7, v8
	v_cvt_pk_bf16_f32 v6, v4, v155
	v_lshlrev_b64 v[4:5], 11, v[178:179]
	v_lshl_add_u64 v[4:5], v[176:177], 0, v[4:5]
	global_store_short v[4:5], v6, off
	s_and_saveexec_b64 s[2:3], s[0:1]
	s_cbranch_execz .LBB0_237
	s_lshl_b32 s0, s20, 6
	s_add_i32 s0, s0, s28
	s_add_i32 s0, s0, s31
	s_ashr_i32 s1, s0, 31
	s_lshl_b64 s[0:1], s[0:1], 8
	v_lshl_or_b32 v4, v156, 2, s0
	v_mov_b32_e32 v5, s1
	v_lshl_add_u64 v[6:7], s[14:15], 0, v[4:5]
	global_store_dword v[6:7], v2, off
	v_lshl_add_u64 v[6:7], s[16:17], 0, v[4:5]
	v_or_b32_e32 v4, 0x80, v4
	global_store_dword v[6:7], v65, off
	v_lshl_add_u64 v[6:7], s[14:15], 0, v[4:5]
	global_store_dword v[6:7], v3, off
	v_lshl_add_u64 v[2:3], s[16:17], 0, v[4:5]
	global_store_dword v[2:3], v33, off
	s_branch .LBB0_237
